# GEMM K-loops: one static s_setprio 1 for waves 4-7 (SIMD partners of waves 0-3) for the duration of each K-loop, reset at the loop tail
# speedup vs baseline: 1.0232x; 1.0046x over previous
.LBB0_143:
	s_lshl_b32 s4, s92, 8
	v_or_b32_e32 v2, s4, v1
	s_lshl_b32 s5, s91, 8
	v_ashrrev_i32_e32 v3, 31, v2
	v_or_b32_e32 v4, s5, v1
	v_lshlrev_b64 v[62:63], 11, v[2:3]
	v_ashrrev_i32_e32 v5, 31, v4
	v_lshl_add_u64 v[2:3], v[134:135], 0, v[62:63]
	v_lshlrev_b64 v[4:5], 11, v[4:5]
	v_lshl_add_u64 v[148:149], v[132:133], 0, v[4:5]
	v_add_co_u32_e32 v4, vcc, 0x20000, v2
	s_mov_b32 s6, 0
	s_nop 0
	v_addc_co_u32_e32 v5, vcc, 0, v3, vcc
	global_load_dwordx4 v[30:33], v[2:3], off
	global_load_dwordx4 v[34:37], v[4:5], off
	v_add_co_u32_e32 v4, vcc, 0x40000, v2
	s_mov_b64 s[0:1], 0
	s_nop 0
	v_addc_co_u32_e32 v5, vcc, 0, v3, vcc
	v_add_co_u32_e32 v2, vcc, 0x60000, v2
	v_lshl_add_u64 v[150:151], v[146:147], 0, v[62:63]
	s_nop 0
	v_addc_co_u32_e32 v3, vcc, 0, v3, vcc
	global_load_dwordx4 v[38:41], v[4:5], off
	global_load_dwordx4 v[42:45], v[2:3], off
	v_add_co_u32_e32 v2, vcc, s43, v148
	s_nop 1
	v_addc_co_u32_e32 v3, vcc, 0, v149, vcc
	s_barrier
	global_load_dwordx4 v[46:49], v[148:149], off
	global_load_dwordx4 v[50:53], v[2:3], off
	v_add_co_u32_e32 v2, vcc, s44, v148
	s_nop 1
	v_addc_co_u32_e32 v3, vcc, 0, v149, vcc
	v_add_co_u32_e32 v4, vcc, 0x60000, v148
	s_nop 1
	v_addc_co_u32_e32 v5, vcc, 0, v149, vcc
	global_load_dwordx4 v[54:57], v[2:3], off
	global_load_dwordx4 v[58:61], v[4:5], off
	v_mov_b32_e32 v2, 0
	v_mov_b32_e32 v3, v2
	v_mov_b32_e32 v4, v2
	v_mov_b32_e32 v5, v2
	v_mov_b32_e32 v6, v2
	v_mov_b32_e32 v7, v2
	v_mov_b32_e32 v8, v2
	v_mov_b32_e32 v9, v2
	v_mov_b32_e32 v10, v2
	v_mov_b32_e32 v11, v2
	v_mov_b32_e32 v12, v2
	v_mov_b32_e32 v13, v2
	v_mov_b32_e32 v14, v2
	v_mov_b32_e32 v15, v2
	v_mov_b32_e32 v16, v2
	v_mov_b32_e32 v17, v2
	v_mov_b32_e32 v18, v2
	v_mov_b32_e32 v19, v2
	v_mov_b32_e32 v20, v2
	v_mov_b32_e32 v21, v2
	v_mov_b32_e32 v22, v2
	v_mov_b32_e32 v23, v2
	v_mov_b32_e32 v24, v2
	v_mov_b32_e32 v25, v2
	v_mov_b32_e32 v26, v2
	v_mov_b32_e32 v27, v2
	v_mov_b32_e32 v28, v2
	v_mov_b32_e32 v29, v2
	v_mov_b32_e32 v62, v2
	v_mov_b32_e32 v63, v2
	v_mov_b32_e32 v64, v2
	v_mov_b32_e32 v65, v2
	v_mov_b32_e32 v66, v2
	v_mov_b32_e32 v67, v2
	v_mov_b32_e32 v68, v2
	v_mov_b32_e32 v69, v2
	v_mov_b32_e32 v70, v2
	v_mov_b32_e32 v71, v2
	v_mov_b32_e32 v72, v2
	v_mov_b32_e32 v73, v2
	v_mov_b32_e32 v74, v2
	v_mov_b32_e32 v75, v2
	v_mov_b32_e32 v76, v2
	v_mov_b32_e32 v77, v2
	v_mov_b32_e32 v78, v2
	v_mov_b32_e32 v79, v2
	v_mov_b32_e32 v80, v2
	v_mov_b32_e32 v81, v2
	v_mov_b32_e32 v82, v2
	v_mov_b32_e32 v83, v2
	s_waitcnt vmcnt(7)
	ds_write_b128 v137, v[30:33]
	s_waitcnt vmcnt(6)
	ds_write_b128 v137, v[34:37] offset:8192
	s_waitcnt vmcnt(5)
	ds_write_b128 v137, v[38:41] offset:16384
	s_waitcnt vmcnt(4)
	ds_write_b128 v137, v[42:45] offset:24576
	s_waitcnt vmcnt(3)
	ds_write_b128 v145, v[46:49]
	s_waitcnt vmcnt(2)
	ds_write_b128 v145, v[50:53] offset:8192
	s_waitcnt vmcnt(1)
	ds_write_b128 v145, v[54:57] offset:16384
	s_waitcnt vmcnt(0)
	ds_write_b128 v145, v[58:61] offset:24576
	v_mov_b32_e32 v30, v2
	v_mov_b32_e32 v31, v2
	v_mov_b32_e32 v32, v2
	v_mov_b32_e32 v33, v2
	v_mov_b32_e32 v34, v2
	v_mov_b32_e32 v35, v2
	v_mov_b32_e32 v36, v2
	v_mov_b32_e32 v37, v2
	v_mov_b32_e32 v38, v2
	v_mov_b32_e32 v39, v2
	v_mov_b32_e32 v40, v2
	v_mov_b32_e32 v41, v2
	v_mov_b32_e32 v42, v2
	v_mov_b32_e32 v43, v2
	v_mov_b32_e32 v44, v2
	v_mov_b32_e32 v45, v2
	v_mov_b32_e32 v46, v2
	v_mov_b32_e32 v47, v2
	v_mov_b32_e32 v48, v2
	v_mov_b32_e32 v49, v2
	v_mov_b32_e32 v50, v2
	v_mov_b32_e32 v51, v2
	v_mov_b32_e32 v52, v2
	v_mov_b32_e32 v53, v2
	v_mov_b32_e32 v54, v2
	v_mov_b32_e32 v55, v2
	v_mov_b32_e32 v56, v2
	v_mov_b32_e32 v57, v2
	v_mov_b32_e32 v58, v2
	v_mov_b32_e32 v59, v2
	v_mov_b32_e32 v60, v2
	v_mov_b32_e32 v61, v2
	v_mov_b32_e32 v84, v2
	v_mov_b32_e32 v85, v2
	v_mov_b32_e32 v86, v2
	v_mov_b32_e32 v87, v2
	v_mov_b32_e32 v88, v2
	v_mov_b32_e32 v89, v2
	v_mov_b32_e32 v90, v2
	v_mov_b32_e32 v91, v2
	v_mov_b32_e32 v92, v2
	v_mov_b32_e32 v93, v2
	v_mov_b32_e32 v94, v2
	v_mov_b32_e32 v95, v2
	v_mov_b32_e32 v96, v2
	v_mov_b32_e32 v97, v2
	v_mov_b32_e32 v98, v2
	v_mov_b32_e32 v99, v2
	v_mov_b32_e32 v100, v2
	v_mov_b32_e32 v101, v2
	v_mov_b32_e32 v102, v2
	v_mov_b32_e32 v103, v2
	v_mov_b32_e32 v104, v2
	v_mov_b32_e32 v105, v2
	v_mov_b32_e32 v106, v2
	v_mov_b32_e32 v107, v2
	v_mov_b32_e32 v108, v2
	v_mov_b32_e32 v109, v2
	v_mov_b32_e32 v110, v2
	v_mov_b32_e32 v111, v2
	v_mov_b32_e32 v112, v2
	v_mov_b32_e32 v113, v2
	v_mov_b32_e32 v114, v2
	v_mov_b32_e32 v115, v2
	v_mov_b32_e32 v116, v2
	v_mov_b32_e32 v117, v2
	v_mov_b32_e32 v118, v2
	v_mov_b32_e32 v119, v2
	v_mov_b32_e32 v120, v2
	v_mov_b32_e32 v121, v2
	v_mov_b32_e32 v122, v2
	v_mov_b32_e32 v123, v2
	v_mov_b32_e32 v124, v2
	v_mov_b32_e32 v125, v2
	v_mov_b32_e32 v126, v2
	v_mov_b32_e32 v127, v2
	v_mov_b32_e32 v128, v2
	v_mov_b32_e32 v129, v2
	s_waitcnt lgkmcnt(0)
	s_barrier
	s_movk_i32 s97, 0x70
	v_readfirstlane_b32 s98, v150
	v_readfirstlane_b32 s99, v151
	v_subrev_u32_e32 v157, s98, v150
	v_bfi_b32 v157, s97, v137, v157
	v_add_u32_e32 v160, s46, v157
	v_add_u32_e32 v161, s47, v157
	v_add_u32_e32 v162, s52, v157
	v_add_u32_e32 v163, s53, v157
	s_add_u32 s98, s98, s0
	s_addc_u32 s99, s99, s1
	s_add_u32 s98, s98, 0x80
	s_addc_u32 s99, s99, 0
	v_readfirstlane_b32 s100, v148
	v_readfirstlane_b32 s101, v149
	v_subrev_u32_e32 v159, s100, v148
	v_bfi_b32 v159, s97, v137, v159
	v_add_u32_e32 v164, 0, v159
	v_add_u32_e32 v165, s43, v159
	v_add_u32_e32 v166, s44, v159
	v_add_u32_e32 v167, s45, v159
	s_add_u32 s100, s100, s0
	s_addc_u32 s101, s101, s1
	s_add_u32 s100, s100, 0x80
	s_addc_u32 s101, s101, 0
	v_readfirstlane_b32 s96, v137
	s_and_b32 s96, s96, 0xfc00
	s_cmp_lt_u32 s96, 0x1000
	s_cbranch_scc1 .Lg2_p2_np
	s_setprio 1
.Lg2_p2_np:
	s_add_u32 m0, s96, 0x8000
	s_nop 0
	global_load_lds_dwordx4 v160, s[98:99]
	s_add_u32 m0, m0, 0x2000
	s_nop 0
	global_load_lds_dwordx4 v161, s[98:99]
	s_add_u32 m0, m0, 0x2000
	s_nop 0
	global_load_lds_dwordx4 v162, s[98:99]
	s_add_u32 m0, m0, 0x2000
	s_nop 0
	global_load_lds_dwordx4 v163, s[98:99]
	s_add_u32 m0, m0, 0xa000
	s_nop 0
	global_load_lds_dwordx4 v164, s[100:101]
	s_add_u32 m0, m0, 0x2000
	s_nop 0
	global_load_lds_dwordx4 v165, s[100:101]
	s_add_u32 m0, m0, 0x2000
	s_nop 0
	global_load_lds_dwordx4 v166, s[100:101]
	s_add_u32 m0, m0, 0x2000
	s_nop 0
	global_load_lds_dwordx4 v167, s[100:101]
	ds_read_b128 v[192:195], v172
	ds_read_b128 v[196:199], v172 offset:2048
	ds_read_b128 v[200:203], v172 offset:4096
	ds_read_b128 v[204:207], v172 offset:6144
	ds_read_b128 v[228:231], v173
	ds_read_b128 v[232:235], v173 offset:2048
	ds_read_b128 v[236:239], v173 offset:4096
	ds_read_b128 v[240:243], v173 offset:6144

.Lg2_p2_tail:
	s_setprio 0
	s_nop 0
	v_mfma_f32_16x16x32_bf16 v[62:65], v[244:247], v[208:211], v[62:65]
	v_mfma_f32_16x16x32_bf16 v[58:61], v[248:251], v[208:211], v[58:61]
	v_mfma_f32_16x16x32_bf16 v[54:57], v[252:255], v[208:211], v[54:57]
	v_mfma_f32_16x16x32_bf16 v[50:53], v[152:155], v[208:211], v[50:53]
	v_mfma_f32_16x16x32_bf16 v[46:49], v[244:247], v[212:215], v[46:49]
	v_mfma_f32_16x16x32_bf16 v[42:45], v[248:251], v[212:215], v[42:45]
	v_mfma_f32_16x16x32_bf16 v[38:41], v[252:255], v[212:215], v[38:41]
	v_mfma_f32_16x16x32_bf16 v[34:37], v[152:155], v[212:215], v[34:37]
	v_mfma_f32_16x16x32_bf16 v[30:33], v[244:247], v[218:221], v[30:33]
	v_mfma_f32_16x16x32_bf16 v[26:29], v[248:251], v[218:221], v[26:29]
	v_mfma_f32_16x16x32_bf16 v[22:25], v[252:255], v[218:221], v[22:25]
	v_mfma_f32_16x16x32_bf16 v[18:21], v[152:155], v[218:221], v[18:21]
	v_mfma_f32_16x16x32_bf16 v[14:17], v[244:247], v[224:227], v[14:17]
	v_mfma_f32_16x16x32_bf16 v[10:13], v[248:251], v[224:227], v[10:13]
	v_mfma_f32_16x16x32_bf16 v[6:9], v[252:255], v[224:227], v[6:9]
	v_mfma_f32_16x16x32_bf16 v[2:5], v[152:155], v[224:227], v[2:5]
	ds_read_b128 v[148:151], v173 offset:32768
	ds_read_b128 v[152:155], v173 offset:34816
	ds_read_b128 v[156:159], v173 offset:36864
	ds_read_b128 v[160:163], v173 offset:38912
	ds_read_b128 v[164:167], v172 offset:32768
	ds_read_b128 v[168:171], v172 offset:34816
	ds_read_b128 v[180:183], v172 offset:36864
	ds_read_b128 v[184:187], v172 offset:38912
	s_setprio 1
	s_waitcnt lgkmcnt(3)
	v_mfma_f32_16x16x32_bf16 v[126:129], v[148:151], v[164:167], v[126:129]
	v_mfma_f32_16x16x32_bf16 v[122:125], v[152:155], v[164:167], v[122:125]
	v_mfma_f32_16x16x32_bf16 v[118:121], v[156:159], v[164:167], v[118:121]
	v_mfma_f32_16x16x32_bf16 v[114:117], v[160:163], v[164:167], v[114:117]
	s_waitcnt lgkmcnt(2)
	v_mfma_f32_16x16x32_bf16 v[110:113], v[148:151], v[168:171], v[110:113]
	v_mfma_f32_16x16x32_bf16 v[106:109], v[152:155], v[168:171], v[106:109]
	v_mfma_f32_16x16x32_bf16 v[102:105], v[156:159], v[168:171], v[102:105]
	v_mfma_f32_16x16x32_bf16 v[98:101], v[160:163], v[168:171], v[98:101]
	s_waitcnt lgkmcnt(1)
	v_mfma_f32_16x16x32_bf16 v[94:97], v[148:151], v[180:183], v[94:97]
	v_mfma_f32_16x16x32_bf16 v[90:93], v[152:155], v[180:183], v[90:93]
	v_mfma_f32_16x16x32_bf16 v[86:89], v[156:159], v[180:183], v[86:89]
	v_mfma_f32_16x16x32_bf16 v[82:85], v[160:163], v[180:183], v[82:85]
	s_waitcnt lgkmcnt(0)
	v_mfma_f32_16x16x32_bf16 v[78:81], v[148:151], v[184:187], v[78:81]
	v_mfma_f32_16x16x32_bf16 v[74:77], v[152:155], v[184:187], v[74:77]
	v_mfma_f32_16x16x32_bf16 v[70:73], v[156:159], v[184:187], v[70:73]
	v_mfma_f32_16x16x32_bf16 v[66:69], v[160:163], v[184:187], v[66:69]
	s_setprio 0
	ds_read_b128 v[164:167], v172 offset:40960
	ds_read_b128 v[168:171], v172 offset:43008
	ds_read_b128 v[180:183], v172 offset:45056
	ds_read_b128 v[184:187], v172 offset:47104
	s_setprio 1
	s_waitcnt lgkmcnt(3)
	v_mfma_f32_16x16x32_bf16 v[62:65], v[148:151], v[164:167], v[62:65]
	v_mfma_f32_16x16x32_bf16 v[58:61], v[152:155], v[164:167], v[58:61]
	v_mfma_f32_16x16x32_bf16 v[54:57], v[156:159], v[164:167], v[54:57]
	v_mfma_f32_16x16x32_bf16 v[50:53], v[160:163], v[164:167], v[50:53]
	s_waitcnt lgkmcnt(2)
	v_mfma_f32_16x16x32_bf16 v[46:49], v[148:151], v[168:171], v[46:49]
	v_mfma_f32_16x16x32_bf16 v[42:45], v[152:155], v[168:171], v[42:45]
	v_mfma_f32_16x16x32_bf16 v[38:41], v[156:159], v[168:171], v[38:41]
	v_mfma_f32_16x16x32_bf16 v[34:37], v[160:163], v[168:171], v[34:37]
	s_waitcnt lgkmcnt(1)
	v_mfma_f32_16x16x32_bf16 v[30:33], v[148:151], v[180:183], v[30:33]
	v_mfma_f32_16x16x32_bf16 v[26:29], v[152:155], v[180:183], v[26:29]
	v_mfma_f32_16x16x32_bf16 v[22:25], v[156:159], v[180:183], v[22:25]
	v_mfma_f32_16x16x32_bf16 v[18:21], v[160:163], v[180:183], v[18:21]
	s_waitcnt lgkmcnt(0)
	v_mfma_f32_16x16x32_bf16 v[148:151], v[148:151], v[184:187], v[14:17]
	v_mfma_f32_16x16x32_bf16 v[152:155], v[152:155], v[184:187], v[10:13]
	v_mfma_f32_16x16x32_bf16 v[156:159], v[156:159], v[184:187], v[6:9]
	v_mfma_f32_16x16x32_bf16 v[160:163], v[160:163], v[184:187], v[2:5]
	s_setprio 0
	ds_read_b128 v[164:167], v217 offset:32768
	ds_read_b128 v[168:171], v217 offset:34816
	ds_read_b128 v[180:183], v217 offset:36864
	ds_read_b128 v[184:187], v217 offset:38912
	ds_read_b128 v[2:5], v216 offset:32768
	ds_read_b128 v[188:191], v216 offset:34816
	ds_read_b128 v[192:195], v216 offset:36864
	ds_read_b128 v[196:199], v216 offset:38912
	s_setprio 1
	s_waitcnt lgkmcnt(3)
	v_mfma_f32_16x16x32_bf16 v[14:17], v[164:167], v[2:5], v[126:129]
	v_mfma_f32_16x16x32_bf16 v[10:13], v[168:171], v[2:5], v[122:125]
	v_mfma_f32_16x16x32_bf16 v[6:9], v[180:183], v[2:5], v[118:121]
	v_mfma_f32_16x16x32_bf16 v[2:5], v[184:187], v[2:5], v[114:117]
	s_waitcnt lgkmcnt(2)
	v_mfma_f32_16x16x32_bf16 v[126:129], v[164:167], v[188:191], v[110:113]
	v_mfma_f32_16x16x32_bf16 v[122:125], v[168:171], v[188:191], v[106:109]
	v_mfma_f32_16x16x32_bf16 v[118:121], v[180:183], v[188:191], v[102:105]
	v_mfma_f32_16x16x32_bf16 v[114:117], v[184:187], v[188:191], v[98:101]
	s_waitcnt lgkmcnt(1)
	v_mfma_f32_16x16x32_bf16 v[110:113], v[164:167], v[192:195], v[94:97]
	v_mfma_f32_16x16x32_bf16 v[106:109], v[168:171], v[192:195], v[90:93]
	v_mfma_f32_16x16x32_bf16 v[102:105], v[180:183], v[192:195], v[86:89]
	v_mfma_f32_16x16x32_bf16 v[98:101], v[184:187], v[192:195], v[82:85]
	s_waitcnt lgkmcnt(0)
	v_mfma_f32_16x16x32_bf16 v[94:97], v[164:167], v[196:199], v[78:81]
	v_mfma_f32_16x16x32_bf16 v[90:93], v[168:171], v[196:199], v[74:77]
	v_mfma_f32_16x16x32_bf16 v[86:89], v[180:183], v[196:199], v[70:73]
	v_mfma_f32_16x16x32_bf16 v[82:85], v[184:187], v[196:199], v[66:69]
	s_setprio 0
	s_nop 1
	ds_read_b128 v[66:69], v216 offset:40960
	ds_read_b128 v[188:191], v216 offset:43008
	ds_read_b128 v[192:195], v216 offset:45056
	ds_read_b128 v[196:199], v216 offset:47104
	s_setprio 1
	s_waitcnt lgkmcnt(3)
	v_mfma_f32_16x16x32_bf16 v[78:81], v[164:167], v[66:69], v[62:65]
	v_mfma_f32_16x16x32_bf16 v[74:77], v[168:171], v[66:69], v[58:61]
	v_mfma_f32_16x16x32_bf16 v[70:73], v[180:183], v[66:69], v[54:57]
	v_mfma_f32_16x16x32_bf16 v[66:69], v[184:187], v[66:69], v[50:53]
	s_waitcnt lgkmcnt(2)
	v_mfma_f32_16x16x32_bf16 v[62:65], v[164:167], v[188:191], v[46:49]
	v_mfma_f32_16x16x32_bf16 v[58:61], v[168:171], v[188:191], v[42:45]
	v_mfma_f32_16x16x32_bf16 v[54:57], v[180:183], v[188:191], v[38:41]
	v_mfma_f32_16x16x32_bf16 v[50:53], v[184:187], v[188:191], v[34:37]
	s_waitcnt lgkmcnt(1)
	v_mfma_f32_16x16x32_bf16 v[46:49], v[164:167], v[192:195], v[30:33]
	v_mfma_f32_16x16x32_bf16 v[42:45], v[168:171], v[192:195], v[26:29]
	v_mfma_f32_16x16x32_bf16 v[38:41], v[180:183], v[192:195], v[22:25]
	v_mfma_f32_16x16x32_bf16 v[34:37], v[184:187], v[192:195], v[18:21]
	s_waitcnt lgkmcnt(0)
	v_mfma_f32_16x16x32_bf16 v[30:33], v[164:167], v[196:199], v[148:151]
	v_mfma_f32_16x16x32_bf16 v[26:29], v[168:171], v[196:199], v[152:155]
	v_mfma_f32_16x16x32_bf16 v[22:25], v[180:183], v[196:199], v[156:159]
	v_mfma_f32_16x16x32_bf16 v[18:21], v[184:187], v[196:199], v[160:163]
	s_setprio 0
	v_add_u32_e32 v179, s4, v174
	v_or_b32_e32 v130, s5, v175
	v_ashrrev_i32_e32 v149, 31, v130
	v_mov_b32_e32 v148, v130
	v_or_b32_e32 v154, v179, v176
	v_cmp_gt_i32_e64 s[4:5], s56, v130
	v_cmp_gt_i32_e64 s[6:7], s57, v130
	v_cmp_lt_i32_e64 s[0:1], s58, v130
	v_lshl_add_u64 v[150:151], v[130:131], 1, s[10:11]
	v_lshl_add_u64 v[148:149], v[148:149], 1, v[142:143]
	v_lshlrev_b32_e32 v152, 2, v136
	v_mul_hi_i32 v155, v154, s62
	s_barrier
	s_and_saveexec_b64 s[28:29], s[4:5]
	s_xor_b64 s[28:29], exec, s[28:29]
	s_cbranch_execz .LBB0_171
	v_mov_b32_e32 v153, s79
	v_mov_b32_e32 v156, s77
	v_cndmask_b32_e64 v157, v153, v156, s[6:7]
	v_mov_b32_e32 v153, s78
	v_mov_b32_e32 v156, s76
	v_cndmask_b32_e64 v156, v153, v156, s[6:7]
	v_mov_b32_e32 v153, v131
	v_lshl_add_u64 v[156:157], v[156:157], 0, v[152:153]
	global_load_dwordx4 v[158:161], v[156:157], off
	global_load_dwordx4 v[164:167], v[156:157], off offset:64
	global_load_dwordx4 v[182:185], v[156:157], off offset:128
	global_load_dwordx4 v[186:189], v[156:157], off offset:192
	v_mul_f32_e32 v191, v15, v15
	v_fmac_f32_e32 v191, v14, v14
	v_fmac_f32_e32 v191, v16, v16
	v_fmac_f32_e32 v191, v17, v17
	v_fmac_f32_e32 v191, v10, v10
	v_fmac_f32_e32 v191, v11, v11
	v_fmac_f32_e32 v191, v12, v12
	v_pk_mul_f32 v[168:169], v[6:7], v[6:7]
	v_fmac_f32_e32 v191, v13, v13
	v_add_f32_e32 v168, v168, v191
	v_pk_mul_f32 v[162:163], v[8:9], v[8:9]
	v_add_f32_e32 v168, v169, v168
	v_add_f32_e32 v162, v162, v168
	v_and_b32_e32 v190, 64, v178
	v_pk_mul_f32 v[180:181], v[2:3], v[2:3]
	v_add_f32_e32 v162, v163, v162
	v_xor_b32_e32 v153, 16, v178
	v_add_u32_e32 v190, 64, v190
	v_add_f32_e32 v162, v180, v162
	v_pk_mul_f32 v[170:171], v[4:5], v[4:5]
	v_cmp_lt_i32_e32 vcc, v153, v190
	v_add_f32_e32 v162, v181, v162
	v_add_f32_e32 v162, v170, v162
	v_cndmask_b32_e32 v153, v178, v153, vcc
	v_lshlrev_b32_e32 v153, 2, v153
	v_add_f32_e32 v162, v171, v162
	ds_bpermute_b32 v163, v153, v162
	v_xor_b32_e32 v168, 32, v178
	v_cmp_lt_i32_e32 vcc, v168, v190
	s_waitcnt lgkmcnt(0)
	v_add_f32_e32 v162, v162, v163
	v_cndmask_b32_e32 v168, v178, v168, vcc
	v_lshlrev_b32_e32 v180, 2, v168
	ds_bpermute_b32 v163, v180, v162
	v_lshrrev_b32_e32 v168, 31, v155
	v_ashrrev_i32_e32 v155, 11, v155
	v_add_u32_e32 v155, v155, v168
	v_mul_i32_i24_e32 v155, 0x2100, v155
	s_waitcnt lgkmcnt(0)
	v_add_f32_e32 v162, v162, v163
	v_fmamk_f32 v162, v162, 0x3c800000, v177
	v_mul_f32_e32 v163, 0x4b800000, v162
	v_cmp_gt_f32_e32 vcc, s59, v162
	v_sub_u32_e32 v155, v154, v155
	s_nop 0
	v_cndmask_b32_e32 v162, v162, v163, vcc
	v_rsq_f32_e32 v162, v162
	s_nop 0
	v_mul_f32_e32 v163, 0x45800000, v162
	v_cndmask_b32_e32 v162, v162, v163, vcc
	v_pk_mul_f32 v[14:15], v[14:15], v[162:163] op_sel_hi:[1,0]
	v_pk_mul_f32 v[16:17], v[16:17], v[162:163] op_sel_hi:[1,0]
	v_pk_mul_f32 v[10:11], v[10:11], v[162:163] op_sel_hi:[1,0]
	v_pk_mul_f32 v[12:13], v[12:13], v[162:163] op_sel_hi:[1,0]
	v_pk_mul_f32 v[6:7], v[6:7], v[162:163] op_sel_hi:[1,0]
	v_pk_mul_f32 v[8:9], v[8:9], v[162:163] op_sel_hi:[1,0]
	v_pk_mul_f32 v[170:171], v[2:3], v[162:163] op_sel_hi:[1,0]
	v_pk_mul_f32 v[4:5], v[4:5], v[162:163] op_sel_hi:[1,0]
	v_cmp_lt_i32_e32 vcc, s63, v155
	s_waitcnt vmcnt(3)
	v_pk_mul_f32 v[168:169], v[160:161], v[16:17]
	v_pk_mul_f32 v[2:3], v[158:159], v[14:15]
	s_waitcnt vmcnt(2)
	v_pk_mul_f32 v[162:163], v[166:167], v[12:13]
	v_pk_mul_f32 v[160:161], v[164:165], v[10:11]
	s_waitcnt vmcnt(1)
	v_pk_mul_f32 v[166:167], v[184:185], v[8:9]
	v_pk_mul_f32 v[164:165], v[182:183], v[6:7]
	s_waitcnt vmcnt(0)
	v_pk_mul_f32 v[158:159], v[188:189], v[4:5]
	v_pk_mul_f32 v[4:5], v[186:187], v[170:171]
	s_and_saveexec_b64 s[38:39], vcc
	s_cbranch_execz .LBB0_148
	v_add_u32_e32 v6, 0xffffff00, v155
	v_lshlrev_b32_e32 v10, 6, v155
	v_and_b32_e32 v14, 0xffffffc0, v6
	v_mov_b32_e32 v15, v131
	v_and_b32_e32 v170, 0x3c0, v10
	v_mov_b32_e32 v171, v131
	v_lshl_add_u64 v[6:7], v[140:141], 0, v[14:15]
	v_lshl_add_u64 v[10:11], v[140:141], 0, v[170:171]
	global_load_dwordx4 v[6:9], v[6:7], off
	v_lshl_add_u64 v[14:15], v[138:139], 0, v[14:15]
	global_load_dwordx4 v[10:13], v[10:11], off
	v_lshl_add_u64 v[170:171], v[138:139], 0, v[170:171]
	global_load_dwordx4 v[14:17], v[14:15], off
	s_waitcnt vmcnt(2)
	v_pk_mul_f32 v[186:187], v[160:161], v[6:7]
	global_load_dwordx4 v[182:185], v[170:171], off
	v_pk_mul_f32 v[170:171], v[162:163], v[8:9]
	v_pk_mul_f32 v[8:9], v[168:169], v[8:9]
	v_pk_mul_f32 v[6:7], v[2:3], v[6:7]
	s_waitcnt vmcnt(2)
	v_pk_mul_f32 v[188:189], v[158:159], v[12:13]
	v_pk_mul_f32 v[190:191], v[4:5], v[10:11]
	v_pk_mul_f32 v[12:13], v[166:167], v[12:13]
	v_pk_mul_f32 v[10:11], v[164:165], v[10:11]
	s_waitcnt vmcnt(1)
	v_pk_fma_f32 v[168:169], v[168:169], v[16:17], v[170:171] neg_lo:[0,0,1] neg_hi:[0,0,1]
	v_pk_fma_f32 v[2:3], v[2:3], v[14:15], v[186:187] neg_lo:[0,0,1] neg_hi:[0,0,1]
	v_pk_fma_f32 v[162:163], v[162:163], v[16:17], v[8:9]
	v_pk_fma_f32 v[160:161], v[160:161], v[14:15], v[6:7]
	s_waitcnt vmcnt(0)
	v_pk_fma_f32 v[166:167], v[166:167], v[184:185], v[188:189] neg_lo:[0,0,1] neg_hi:[0,0,1]
	v_pk_fma_f32 v[164:165], v[164:165], v[182:183], v[190:191] neg_lo:[0,0,1] neg_hi:[0,0,1]
	v_pk_fma_f32 v[158:159], v[158:159], v[184:185], v[12:13]
	v_pk_fma_f32 v[4:5], v[4:5], v[182:183], v[10:11]

.LBB0_248:
	s_lshl_b32 s56, s52, 8
	v_or_b32_e32 v2, s56, v1
	v_ashrrev_i32_e32 v3, 31, v2
	v_lshlrev_b64 v[62:63], 11, v[2:3]
	v_lshl_add_u64 v[2:3], v[130:131], 0, v[62:63]
	v_add_co_u32_e32 v6, vcc, 0x20000, v2
	s_lshl_b32 s53, s47, 8
	s_nop 0
	v_addc_co_u32_e32 v7, vcc, 0, v3, vcc
	v_or_b32_e32 v4, s53, v1
	global_load_dwordx4 v[30:33], v[2:3], off
	global_load_dwordx4 v[34:37], v[6:7], off
	v_add_co_u32_e32 v6, vcc, 0x40000, v2
	v_ashrrev_i32_e32 v5, 31, v4
	s_nop 0
	v_addc_co_u32_e32 v7, vcc, 0, v3, vcc
	v_lshlrev_b64 v[64:65], 11, v[4:5]
	v_add_co_u32_e32 v2, vcc, 0x60000, v2
	v_lshl_add_u64 v[4:5], v[132:133], 0, v[64:65]
	s_nop 0
	v_addc_co_u32_e32 v3, vcc, 0, v3, vcc
	global_load_dwordx4 v[38:41], v[6:7], off
	global_load_dwordx4 v[42:45], v[2:3], off
	v_add_co_u32_e32 v2, vcc, s12, v4
	s_waitcnt vmcnt(63) expcnt(7) lgkmcnt(15)
	s_nop 0
	v_addc_co_u32_e32 v3, vcc, 0, v5, vcc
	s_barrier
	global_load_dwordx4 v[46:49], v[4:5], off
	global_load_dwordx4 v[50:53], v[2:3], off
	v_add_co_u32_e32 v2, vcc, s13, v4
	s_mov_b32 s57, 0
	s_nop 0
	v_addc_co_u32_e32 v3, vcc, 0, v5, vcc
	v_add_co_u32_e32 v4, vcc, s14, v4
	s_mov_b64 s[8:9], 0
	s_nop 0
	v_addc_co_u32_e32 v5, vcc, 0, v5, vcc
	global_load_dwordx4 v[54:57], v[2:3], off
	global_load_dwordx4 v[58:61], v[4:5], off
	v_mov_b32_e32 v2, 0
	v_mov_b32_e32 v3, v2
	v_mov_b32_e32 v4, v2
	v_mov_b32_e32 v5, v2
	v_mov_b32_e32 v6, v2
	v_mov_b32_e32 v7, v2
	v_mov_b32_e32 v8, v2
	v_mov_b32_e32 v9, v2
	v_mov_b32_e32 v10, v2
	v_mov_b32_e32 v11, v2
	v_mov_b32_e32 v12, v2
	v_mov_b32_e32 v13, v2
	v_mov_b32_e32 v14, v2
	v_mov_b32_e32 v15, v2
	v_mov_b32_e32 v16, v2
	v_mov_b32_e32 v17, v2
	v_mov_b32_e32 v18, v2
	v_mov_b32_e32 v19, v2
	v_mov_b32_e32 v20, v2
	v_mov_b32_e32 v21, v2
	v_mov_b32_e32 v22, v2
	v_mov_b32_e32 v23, v2
	v_mov_b32_e32 v24, v2
	v_mov_b32_e32 v25, v2
	v_mov_b32_e32 v26, v2
	v_mov_b32_e32 v27, v2
	v_mov_b32_e32 v28, v2
	v_lshl_add_u64 v[136:137], v[134:135], 0, v[62:63]
	v_lshl_add_u64 v[138:139], v[134:135], 0, v[64:65]
	v_mov_b32_e32 v29, v2
	v_mov_b32_e32 v62, v2
	v_mov_b32_e32 v63, v2
	v_mov_b32_e32 v64, v2
	v_mov_b32_e32 v65, v2
	v_mov_b32_e32 v66, v2
	v_mov_b32_e32 v67, v2
	v_mov_b32_e32 v68, v2
	v_mov_b32_e32 v69, v2
	v_mov_b32_e32 v70, v2
	v_mov_b32_e32 v71, v2
	v_mov_b32_e32 v72, v2
	v_mov_b32_e32 v73, v2
	v_mov_b32_e32 v74, v2
	v_mov_b32_e32 v75, v2
	v_mov_b32_e32 v76, v2
	v_mov_b32_e32 v77, v2
	v_mov_b32_e32 v78, v2
	v_mov_b32_e32 v79, v2
	v_mov_b32_e32 v80, v2
	v_mov_b32_e32 v81, v2
	v_mov_b32_e32 v82, v2
	v_mov_b32_e32 v83, v2
	v_mov_b32_e32 v84, v2
	s_waitcnt vmcnt(7)
	ds_write_b128 v146, v[30:33]
	s_waitcnt vmcnt(6)
	ds_write_b128 v146, v[34:37] offset:8192
	s_waitcnt vmcnt(5)
	ds_write_b128 v146, v[38:41] offset:16384
	s_waitcnt vmcnt(4)
	ds_write_b128 v146, v[42:45] offset:24576
	s_waitcnt vmcnt(3)
	ds_write_b128 v147, v[46:49]
	s_waitcnt vmcnt(2)
	ds_write_b128 v147, v[50:53] offset:8192
	s_waitcnt vmcnt(1)
	ds_write_b128 v147, v[54:57] offset:16384
	s_waitcnt vmcnt(0)
	ds_write_b128 v147, v[58:61] offset:24576
	v_mov_b32_e32 v30, v2
	v_mov_b32_e32 v31, v2
	v_mov_b32_e32 v32, v2
	v_mov_b32_e32 v33, v2
	v_mov_b32_e32 v34, v2
	v_mov_b32_e32 v35, v2
	v_mov_b32_e32 v36, v2
	v_mov_b32_e32 v37, v2
	v_mov_b32_e32 v38, v2
	v_mov_b32_e32 v39, v2
	v_mov_b32_e32 v40, v2
	v_mov_b32_e32 v41, v2
	v_mov_b32_e32 v42, v2
	v_mov_b32_e32 v43, v2
	v_mov_b32_e32 v44, v2
	v_mov_b32_e32 v45, v2
	v_mov_b32_e32 v46, v2
	v_mov_b32_e32 v47, v2
	v_mov_b32_e32 v48, v2
	v_mov_b32_e32 v49, v2
	v_mov_b32_e32 v50, v2
	v_mov_b32_e32 v51, v2
	v_mov_b32_e32 v52, v2
	v_mov_b32_e32 v53, v2
	v_mov_b32_e32 v54, v2
	v_mov_b32_e32 v55, v2
	v_mov_b32_e32 v56, v2
	v_mov_b32_e32 v57, v2
	v_mov_b32_e32 v58, v2
	v_mov_b32_e32 v59, v2
	v_mov_b32_e32 v60, v2
	v_mov_b32_e32 v61, v2
	v_mov_b32_e32 v85, v2
	v_mov_b32_e32 v86, v2
	v_mov_b32_e32 v87, v2
	v_mov_b32_e32 v88, v2
	v_mov_b32_e32 v89, v2
	v_mov_b32_e32 v90, v2
	v_mov_b32_e32 v91, v2
	v_mov_b32_e32 v92, v2
	v_mov_b32_e32 v93, v2
	v_mov_b32_e32 v94, v2
	v_mov_b32_e32 v95, v2
	v_mov_b32_e32 v96, v2
	v_mov_b32_e32 v97, v2
	v_mov_b32_e32 v98, v2
	v_mov_b32_e32 v99, v2
	v_mov_b32_e32 v100, v2
	v_mov_b32_e32 v101, v2
	v_mov_b32_e32 v102, v2
	v_mov_b32_e32 v103, v2
	v_mov_b32_e32 v104, v2
	v_mov_b32_e32 v105, v2
	v_mov_b32_e32 v106, v2
	v_mov_b32_e32 v107, v2
	v_mov_b32_e32 v108, v2
	v_mov_b32_e32 v109, v2
	v_mov_b32_e32 v110, v2
	v_mov_b32_e32 v111, v2
	v_mov_b32_e32 v112, v2
	v_mov_b32_e32 v113, v2
	v_mov_b32_e32 v114, v2
	v_mov_b32_e32 v115, v2
	v_mov_b32_e32 v116, v2
	v_mov_b32_e32 v117, v2
	v_mov_b32_e32 v118, v2
	v_mov_b32_e32 v119, v2
	v_mov_b32_e32 v120, v2
	v_mov_b32_e32 v121, v2
	v_mov_b32_e32 v122, v2
	v_mov_b32_e32 v123, v2
	v_mov_b32_e32 v124, v2
	v_mov_b32_e32 v125, v2
	v_mov_b32_e32 v126, v2
	v_mov_b32_e32 v127, v2
	v_mov_b32_e32 v128, v2
	v_mov_b32_e32 v129, v2
	s_waitcnt lgkmcnt(0)
	s_barrier
	s_movk_i32 s97, 0x70
	v_readfirstlane_b32 s98, v136
	v_readfirstlane_b32 s99, v137
	v_subrev_u32_e32 v248, s98, v136
	v_bfi_b32 v248, s97, v146, v248
	v_add_u32_e32 v140, s15, v248
	v_add_u32_e32 v152, s16, v248
	v_add_u32_e32 v156, s17, v248
	v_add_u32_e32 v160, s28, v248
	s_add_u32 s98, s98, s8
	s_addc_u32 s99, s99, s9
	s_add_u32 s98, s98, 0x80
	s_addc_u32 s99, s99, 0
	v_readfirstlane_b32 s100, v138
	v_readfirstlane_b32 s101, v139
	v_subrev_u32_e32 v250, s100, v138
	v_bfi_b32 v250, s97, v146, v250
	v_add_u32_e32 v164, s29, v250
	v_add_u32_e32 v168, s38, v250
	v_add_u32_e32 v172, s39, v250
	v_add_u32_e32 v176, s42, v250
	s_add_u32 s100, s100, s8
	s_addc_u32 s101, s101, s9
	s_add_u32 s100, s100, 0x80
	s_addc_u32 s101, s101, 0
	v_readfirstlane_b32 s96, v146
	s_and_b32 s96, s96, 0xfc00
	s_cmp_lt_u32 s96, 0x1000
	s_cbranch_scc1 .Lg2_p4_np
	s_setprio 1
.Lg2_p4_np:
	s_add_u32 m0, s96, 0x8000
	s_nop 0
	global_load_lds_dwordx4 v140, s[98:99]
	s_add_u32 m0, m0, 0x2000
	s_nop 0
	global_load_lds_dwordx4 v152, s[98:99]
	s_add_u32 m0, m0, 0x2000
	s_nop 0
	global_load_lds_dwordx4 v156, s[98:99]
	s_add_u32 m0, m0, 0x2000
	s_nop 0
	global_load_lds_dwordx4 v160, s[98:99]
	s_add_u32 m0, m0, 0xa000
	s_nop 0
	global_load_lds_dwordx4 v164, s[100:101]
	s_add_u32 m0, m0, 0x2000
	s_nop 0
	global_load_lds_dwordx4 v168, s[100:101]
	s_add_u32 m0, m0, 0x2000
	s_nop 0
	global_load_lds_dwordx4 v172, s[100:101]
	s_add_u32 m0, m0, 0x2000
	s_nop 0
	global_load_lds_dwordx4 v176, s[100:101]
	ds_read_b128 v[180:183], v148
	ds_read_b128 v[184:187], v148 offset:2048
	ds_read_b128 v[188:191], v148 offset:4096
	ds_read_b128 v[192:195], v148 offset:6144
	ds_read_b128 v[212:215], v149
	ds_read_b128 v[218:221], v149 offset:2048
	ds_read_b128 v[224:227], v149 offset:4096
	ds_read_b128 v[228:231], v149 offset:6144

.Lg2_p4_tail:
	s_setprio 0
	s_nop 0
	v_mfma_f32_16x16x32_bf16 v[62:65], v[232:235], v[196:199], v[62:65]
	v_mfma_f32_16x16x32_bf16 v[58:61], v[236:239], v[196:199], v[58:61]
	v_mfma_f32_16x16x32_bf16 v[54:57], v[240:243], v[196:199], v[54:57]
	v_mfma_f32_16x16x32_bf16 v[50:53], v[244:247], v[196:199], v[50:53]
	v_mfma_f32_16x16x32_bf16 v[46:49], v[232:235], v[200:203], v[46:49]
	v_mfma_f32_16x16x32_bf16 v[42:45], v[236:239], v[200:203], v[42:45]
	v_mfma_f32_16x16x32_bf16 v[38:41], v[240:243], v[200:203], v[38:41]
	v_mfma_f32_16x16x32_bf16 v[34:37], v[244:247], v[200:203], v[34:37]
	v_mfma_f32_16x16x32_bf16 v[30:33], v[232:235], v[204:207], v[30:33]
	v_mfma_f32_16x16x32_bf16 v[26:29], v[236:239], v[204:207], v[26:29]
	v_mfma_f32_16x16x32_bf16 v[22:25], v[240:243], v[204:207], v[22:25]
	v_mfma_f32_16x16x32_bf16 v[18:21], v[244:247], v[204:207], v[18:21]
	v_mfma_f32_16x16x32_bf16 v[14:17], v[232:235], v[208:211], v[14:17]
	v_mfma_f32_16x16x32_bf16 v[10:13], v[236:239], v[208:211], v[10:13]
	v_mfma_f32_16x16x32_bf16 v[6:9], v[240:243], v[208:211], v[6:9]
	v_mfma_f32_16x16x32_bf16 v[2:5], v[244:247], v[208:211], v[2:5]
	ds_read_b128 v[136:139], v149 offset:32768
	ds_read_b128 v[140:143], v149 offset:34816
	ds_read_b128 v[152:155], v149 offset:36864
	ds_read_b128 v[156:159], v149 offset:38912
	ds_read_b128 v[160:163], v148 offset:32768
	ds_read_b128 v[164:167], v148 offset:34816
	ds_read_b128 v[168:171], v148 offset:36864
	ds_read_b128 v[172:175], v148 offset:38912
	s_setprio 1
	s_waitcnt lgkmcnt(3)
	v_mfma_f32_16x16x32_bf16 v[126:129], v[136:139], v[160:163], v[126:129]
	v_mfma_f32_16x16x32_bf16 v[122:125], v[140:143], v[160:163], v[122:125]
	v_mfma_f32_16x16x32_bf16 v[118:121], v[152:155], v[160:163], v[118:121]
	v_mfma_f32_16x16x32_bf16 v[114:117], v[156:159], v[160:163], v[114:117]
	s_waitcnt lgkmcnt(2)
	v_mfma_f32_16x16x32_bf16 v[110:113], v[136:139], v[164:167], v[110:113]
	v_mfma_f32_16x16x32_bf16 v[106:109], v[140:143], v[164:167], v[106:109]
	v_mfma_f32_16x16x32_bf16 v[102:105], v[152:155], v[164:167], v[102:105]
	v_mfma_f32_16x16x32_bf16 v[98:101], v[156:159], v[164:167], v[98:101]
	s_waitcnt lgkmcnt(1)
	v_mfma_f32_16x16x32_bf16 v[94:97], v[136:139], v[168:171], v[94:97]
	v_mfma_f32_16x16x32_bf16 v[90:93], v[140:143], v[168:171], v[90:93]
	v_mfma_f32_16x16x32_bf16 v[86:89], v[152:155], v[168:171], v[86:89]
	v_mfma_f32_16x16x32_bf16 v[82:85], v[156:159], v[168:171], v[82:85]
	s_waitcnt lgkmcnt(0)
	v_mfma_f32_16x16x32_bf16 v[78:81], v[136:139], v[172:175], v[78:81]
	v_mfma_f32_16x16x32_bf16 v[74:77], v[140:143], v[172:175], v[74:77]
	v_mfma_f32_16x16x32_bf16 v[70:73], v[152:155], v[172:175], v[70:73]
	v_mfma_f32_16x16x32_bf16 v[66:69], v[156:159], v[172:175], v[66:69]
	s_setprio 0
	ds_read_b128 v[160:163], v148 offset:40960
	ds_read_b128 v[164:167], v148 offset:43008
	ds_read_b128 v[168:171], v148 offset:45056
	ds_read_b128 v[172:175], v148 offset:47104
	s_setprio 1
	s_waitcnt lgkmcnt(3)
	v_mfma_f32_16x16x32_bf16 v[62:65], v[136:139], v[160:163], v[62:65]
	v_mfma_f32_16x16x32_bf16 v[58:61], v[140:143], v[160:163], v[58:61]
	v_mfma_f32_16x16x32_bf16 v[54:57], v[152:155], v[160:163], v[54:57]
	v_mfma_f32_16x16x32_bf16 v[50:53], v[156:159], v[160:163], v[50:53]
	s_waitcnt lgkmcnt(2)
	v_mfma_f32_16x16x32_bf16 v[46:49], v[136:139], v[164:167], v[46:49]
	v_mfma_f32_16x16x32_bf16 v[42:45], v[140:143], v[164:167], v[42:45]
	v_mfma_f32_16x16x32_bf16 v[38:41], v[152:155], v[164:167], v[38:41]
	v_mfma_f32_16x16x32_bf16 v[34:37], v[156:159], v[164:167], v[34:37]
	s_waitcnt lgkmcnt(1)
	v_mfma_f32_16x16x32_bf16 v[30:33], v[136:139], v[168:171], v[30:33]
	v_mfma_f32_16x16x32_bf16 v[26:29], v[140:143], v[168:171], v[26:29]
	v_mfma_f32_16x16x32_bf16 v[22:25], v[152:155], v[168:171], v[22:25]
	v_mfma_f32_16x16x32_bf16 v[18:21], v[156:159], v[168:171], v[18:21]
	s_waitcnt lgkmcnt(0)
	v_mfma_f32_16x16x32_bf16 v[14:17], v[136:139], v[172:175], v[14:17]
	v_mfma_f32_16x16x32_bf16 v[10:13], v[140:143], v[172:175], v[10:13]
	v_mfma_f32_16x16x32_bf16 v[6:9], v[152:155], v[172:175], v[6:9]
	v_mfma_f32_16x16x32_bf16 v[2:5], v[156:159], v[172:175], v[2:5]
	s_setprio 0
	ds_read_b128 v[136:139], v217 offset:32768
	ds_read_b128 v[140:143], v217 offset:34816
	ds_read_b128 v[152:155], v217 offset:36864
	ds_read_b128 v[156:159], v217 offset:38912
	ds_read_b128 v[160:163], v216 offset:32768
	ds_read_b128 v[164:167], v216 offset:34816
	ds_read_b128 v[168:171], v216 offset:36864
	ds_read_b128 v[172:175], v216 offset:38912
	s_setprio 1
	s_waitcnt lgkmcnt(3)
	v_mfma_f32_16x16x32_bf16 v[126:129], v[136:139], v[160:163], v[126:129]
	v_mfma_f32_16x16x32_bf16 v[122:125], v[140:143], v[160:163], v[122:125]
	v_mfma_f32_16x16x32_bf16 v[118:121], v[152:155], v[160:163], v[118:121]
	v_mfma_f32_16x16x32_bf16 v[114:117], v[156:159], v[160:163], v[114:117]
	s_waitcnt lgkmcnt(2)
	v_mfma_f32_16x16x32_bf16 v[110:113], v[136:139], v[164:167], v[110:113]
	v_mfma_f32_16x16x32_bf16 v[106:109], v[140:143], v[164:167], v[106:109]
	v_mfma_f32_16x16x32_bf16 v[102:105], v[152:155], v[164:167], v[102:105]
	v_mfma_f32_16x16x32_bf16 v[98:101], v[156:159], v[164:167], v[98:101]
	s_waitcnt lgkmcnt(1)
	v_mfma_f32_16x16x32_bf16 v[94:97], v[136:139], v[168:171], v[94:97]
	v_mfma_f32_16x16x32_bf16 v[90:93], v[140:143], v[168:171], v[90:93]
	v_mfma_f32_16x16x32_bf16 v[86:89], v[152:155], v[168:171], v[86:89]
	v_mfma_f32_16x16x32_bf16 v[82:85], v[156:159], v[168:171], v[82:85]
	s_waitcnt lgkmcnt(0)
	v_mfma_f32_16x16x32_bf16 v[78:81], v[136:139], v[172:175], v[78:81]
	v_mfma_f32_16x16x32_bf16 v[74:77], v[140:143], v[172:175], v[74:77]
	v_mfma_f32_16x16x32_bf16 v[70:73], v[152:155], v[172:175], v[70:73]
	v_mfma_f32_16x16x32_bf16 v[66:69], v[156:159], v[172:175], v[66:69]
	s_setprio 0
	ds_read_b128 v[160:163], v216 offset:40960
	ds_read_b128 v[164:167], v216 offset:43008
	ds_read_b128 v[168:171], v216 offset:45056
	ds_read_b128 v[172:175], v216 offset:47104
	s_setprio 1
	s_waitcnt lgkmcnt(3)
	v_mfma_f32_16x16x32_bf16 v[62:65], v[136:139], v[160:163], v[62:65]
	v_mfma_f32_16x16x32_bf16 v[58:61], v[140:143], v[160:163], v[58:61]
	v_mfma_f32_16x16x32_bf16 v[54:57], v[152:155], v[160:163], v[54:57]
	v_mfma_f32_16x16x32_bf16 v[50:53], v[156:159], v[160:163], v[50:53]
	s_waitcnt lgkmcnt(2)
	v_mfma_f32_16x16x32_bf16 v[46:49], v[136:139], v[164:167], v[46:49]
	v_mfma_f32_16x16x32_bf16 v[42:45], v[140:143], v[164:167], v[42:45]
	v_mfma_f32_16x16x32_bf16 v[38:41], v[152:155], v[164:167], v[38:41]
	v_mfma_f32_16x16x32_bf16 v[34:37], v[156:159], v[164:167], v[34:37]
	s_waitcnt lgkmcnt(1)
	v_mfma_f32_16x16x32_bf16 v[30:33], v[136:139], v[168:171], v[30:33]
	v_mfma_f32_16x16x32_bf16 v[26:29], v[140:143], v[168:171], v[26:29]
	v_mfma_f32_16x16x32_bf16 v[22:25], v[152:155], v[168:171], v[22:25]
	v_mfma_f32_16x16x32_bf16 v[18:21], v[156:159], v[168:171], v[18:21]
	s_waitcnt lgkmcnt(0)
	v_mfma_f32_16x16x32_bf16 v[14:17], v[136:139], v[172:175], v[14:17]
	v_mfma_f32_16x16x32_bf16 v[10:13], v[140:143], v[172:175], v[10:13]
	v_mfma_f32_16x16x32_bf16 v[6:9], v[152:155], v[172:175], v[6:9]
	v_mfma_f32_16x16x32_bf16 v[2:5], v[156:159], v[172:175], v[2:5]
	s_setprio 0
	v_add_u32_e32 v152, s56, v150
	v_mul_hi_i32 v136, v152, s43
	v_lshrrev_b32_e32 v137, 31, v136
	v_ashrrev_i32_e32 v136, 11, v136
	v_add_u32_e32 v139, v136, v137
	v_mad_i32_i24 v142, v139, s44, v152
	v_lshlrev_b32_e32 v141, 13, v139
	v_cmp_lt_i32_e32 vcc, s45, v142
	v_mov_b64_e32 v[136:137], s[40:41]
	v_add3_u32 v138, v141, v142, s46
	s_barrier
	s_and_saveexec_b64 s[8:9], vcc
	s_xor_b64 s[8:9], exec, s[8:9]
	s_cbranch_execz .LBB0_252
	v_add3_u32 v140, v141, v142, s46
	v_mov_b64_e32 v[136:137], s[36:37]
	s_or_saveexec_b64 s[8:9], s[8:9]
	v_lshl_add_u32 v141, v139, 8, v142
	s_xor_b64 exec, exec, s[8:9]
	s_branch .LBB0_253

.LBB0_354:
	s_mul_hi_i32 s0, s3, 0x2e8ba2e9
	s_lshr_b32 s1, s0, 31
	s_ashr_i32 s0, s0, 4
	s_add_i32 s40, s0, s1
	s_lshl_b32 s0, s40, 2
	s_sub_i32 s1, 33, s0
	s_min_u32 s1, s1, 4
	v_cvt_f32_ubyte0_e32 v2, s1
	v_rcp_iflag_f32_e32 v2, v2
	s_sub_i32 s41, 0, s1
	s_mul_i32 s37, s40, 0xffffffa8
	s_add_i32 s37, s37, s3
	v_mul_f32_e32 v2, 0x4f7ffffe, v2
	v_cvt_u32_f32_e32 v2, v2
	s_abs_i32 s39, s37
	s_ashr_i32 s38, s37, 31
	s_mulk_i32 s40, 0x54
	v_readfirstlane_b32 s42, v2
	s_mul_i32 s41, s41, s42
	s_mul_hi_u32 s41, s42, s41
	s_add_i32 s42, s42, s41
	s_mul_hi_u32 s41, s39, s42
	s_mul_i32 s42, s41, s1
	s_sub_i32 s39, s39, s42
	s_add_i32 s42, s41, 1
	s_sub_i32 s43, s39, s1
	s_cmp_ge_u32 s39, s1
	s_cselect_b32 s41, s42, s41
	s_cselect_b32 s39, s43, s39
	s_add_i32 s42, s41, 1
	s_cmp_ge_u32 s39, s1
	s_cselect_b32 s39, s42, s41
	s_xor_b32 s39, s39, s38
	s_sub_i32 s38, s39, s38
	s_add_i32 s0, s0, s6
	s_mul_i32 s41, s1, s38
	s_add_i32 s0, s0, s37
	s_sub_i32 s0, s0, s41
	s_lshl_b32 s37, s0, 8
	v_or_b32_e32 v2, s37, v1
	v_ashrrev_i32_e32 v3, 31, v2
	v_lshlrev_b64 v[2:3], 11, v[2:3]
	v_lshl_add_u64 v[2:3], v[132:133], 0, v[2:3]
	v_add_co_u32_e32 v6, vcc, s9, v2
	s_lshl_b32 s38, s38, 8
	s_nop 0
	v_addc_co_u32_e32 v7, vcc, 0, v3, vcc
	v_or_b32_e32 v4, s38, v1
	global_load_dwordx4 v[20:23], v[2:3], off
	global_load_dwordx4 v[24:27], v[6:7], off
	v_add_co_u32_e32 v6, vcc, s10, v2
	v_ashrrev_i32_e32 v5, 31, v4
	s_nop 0
	v_addc_co_u32_e32 v7, vcc, 0, v3, vcc
	v_lshlrev_b64 v[52:53], 11, v[4:5]
	v_add_co_u32_e32 v2, vcc, s11, v2
	v_lshl_add_u64 v[4:5], v[134:135], 0, v[52:53]
	s_nop 0
	v_addc_co_u32_e32 v3, vcc, 0, v3, vcc
	global_load_dwordx4 v[28:31], v[6:7], off
	global_load_dwordx4 v[32:35], v[2:3], off
	v_add_co_u32_e32 v2, vcc, s9, v4
	s_waitcnt vmcnt(63) expcnt(7) lgkmcnt(15)
	s_nop 0
	v_addc_co_u32_e32 v3, vcc, 0, v5, vcc
	s_barrier
	global_load_dwordx4 v[36:39], v[4:5], off
	global_load_dwordx4 v[40:43], v[2:3], off
	v_add_co_u32_e32 v2, vcc, s10, v4
	s_sub_i32 s41, s8, s41
	s_nop 0
	v_addc_co_u32_e32 v3, vcc, 0, v5, vcc
	v_add_co_u32_e32 v4, vcc, s11, v4
	s_sub_i32 s40, s41, s40
	s_nop 0
	v_addc_co_u32_e32 v5, vcc, 0, v5, vcc
	global_load_dwordx4 v[44:47], v[2:3], off
	global_load_dwordx4 v[48:51], v[4:5], off
	v_lshl_add_u32 v54, s40, 8, v1
	v_ashrrev_i32_e32 v55, 31, v54
	v_lshl_add_u64 v[140:141], v[138:139], 0, v[52:53]
	v_lshlrev_b64 v[52:53], 11, v[54:55]
	s_mov_b64 s[0:1], 0
	s_mov_b32 s39, 0
	v_mov_b32_e32 v2, 0
	v_mov_b32_e32 v3, v131
	v_mov_b32_e32 v4, v131
	v_mov_b32_e32 v5, v131
	v_mov_b32_e32 v6, 0
	v_mov_b32_e32 v7, v131
	v_mov_b32_e32 v8, v131
	v_mov_b32_e32 v9, v131
	v_mov_b32_e32 v10, 0
	v_mov_b32_e32 v11, v131
	v_mov_b32_e32 v12, v131
	v_mov_b32_e32 v13, v131
	v_mov_b32_e32 v14, 0
	v_mov_b32_e32 v15, v131
	v_mov_b32_e32 v16, v131
	v_mov_b32_e32 v17, v131
	v_mov_b32_e32 v18, 0
	v_lshl_add_u64 v[142:143], v[138:139], 0, v[52:53]
	v_mov_b32_e32 v19, v131
	v_mov_b32_e32 v52, v131
	v_mov_b32_e32 v53, v131
	v_mov_b32_e32 v54, 0
	v_mov_b32_e32 v55, v131
	v_mov_b32_e32 v56, v131
	v_mov_b32_e32 v57, v131
	v_mov_b32_e32 v58, 0
	v_mov_b32_e32 v59, v131
	v_mov_b32_e32 v60, v131
	v_mov_b32_e32 v61, v131
	v_mov_b32_e32 v62, 0
	v_mov_b32_e32 v63, v131
	v_mov_b32_e32 v64, v131
	v_mov_b32_e32 v65, v131
	v_mov_b32_e32 v66, 0
	v_mov_b32_e32 v67, v131
	v_mov_b32_e32 v68, v131
	v_mov_b32_e32 v69, v131
	v_mov_b32_e32 v70, 0
	v_mov_b32_e32 v71, v131
	v_mov_b32_e32 v72, v131
	v_mov_b32_e32 v73, v131
	v_mov_b32_e32 v74, 0
	s_waitcnt vmcnt(7)
	ds_write_b128 v144, v[20:23]
	s_waitcnt vmcnt(6)
	ds_write_b128 v144, v[24:27] offset:8192
	s_waitcnt vmcnt(5)
	ds_write_b128 v144, v[28:31] offset:16384
	s_waitcnt vmcnt(4)
	ds_write_b128 v144, v[32:35] offset:24576
	s_waitcnt vmcnt(3)
	ds_write_b128 v145, v[36:39]
	s_waitcnt vmcnt(2)
	ds_write_b128 v145, v[40:43] offset:8192
	s_waitcnt vmcnt(1)
	ds_write_b128 v145, v[44:47] offset:16384
	s_waitcnt vmcnt(0)
	ds_write_b128 v145, v[48:51] offset:24576
	v_mov_b32_e32 v20, v131
	v_mov_b32_e32 v21, v131
	v_mov_b32_e32 v22, 0
	v_mov_b32_e32 v23, v131
	v_mov_b32_e32 v24, v131
	v_mov_b32_e32 v25, v131
	v_mov_b32_e32 v26, 0
	v_mov_b32_e32 v27, v131
	v_mov_b32_e32 v28, v131
	v_mov_b32_e32 v29, v131
	v_mov_b32_e32 v30, 0
	v_mov_b32_e32 v31, v131
	v_mov_b32_e32 v32, v131
	v_mov_b32_e32 v33, v131
	v_mov_b32_e32 v34, 0
	v_mov_b32_e32 v35, v131
	v_mov_b32_e32 v36, v131
	v_mov_b32_e32 v37, v131
	v_mov_b32_e32 v38, 0
	v_mov_b32_e32 v39, v131
	v_mov_b32_e32 v40, v131
	v_mov_b32_e32 v41, v131
	v_mov_b32_e32 v42, 0
	v_mov_b32_e32 v43, v131
	v_mov_b32_e32 v44, v131
	v_mov_b32_e32 v45, v131
	v_mov_b32_e32 v46, 0
	v_mov_b32_e32 v47, v131
	v_mov_b32_e32 v48, v131
	v_mov_b32_e32 v49, v131
	v_mov_b32_e32 v50, 0
	v_mov_b32_e32 v51, v131
	v_mov_b32_e32 v75, v131
	v_mov_b32_e32 v76, v131
	v_mov_b32_e32 v77, v131
	v_mov_b32_e32 v78, 0
	v_mov_b32_e32 v79, v131
	v_mov_b32_e32 v80, v131
	v_mov_b32_e32 v81, v131
	v_mov_b32_e32 v82, 0
	v_mov_b32_e32 v83, v131
	v_mov_b32_e32 v84, v131
	v_mov_b32_e32 v85, v131
	v_mov_b32_e32 v86, 0
	v_mov_b32_e32 v87, v131
	v_mov_b32_e32 v88, v131
	v_mov_b32_e32 v89, v131
	v_mov_b32_e32 v90, 0
	v_mov_b32_e32 v91, v131
	v_mov_b32_e32 v92, v131
	v_mov_b32_e32 v93, v131
	v_mov_b32_e32 v94, 0
	v_mov_b32_e32 v95, v131
	v_mov_b32_e32 v96, v131
	v_mov_b32_e32 v97, v131
	v_mov_b32_e32 v98, 0
	v_mov_b32_e32 v99, v131
	v_mov_b32_e32 v100, v131
	v_mov_b32_e32 v101, v131
	v_mov_b32_e32 v102, 0
	v_mov_b32_e32 v103, v131
	v_mov_b32_e32 v104, v131
	v_mov_b32_e32 v105, v131
	v_mov_b32_e32 v106, 0
	v_mov_b32_e32 v107, v131
	v_mov_b32_e32 v108, v131
	v_mov_b32_e32 v109, v131
	v_mov_b32_e32 v110, 0
	v_mov_b32_e32 v111, v131
	v_mov_b32_e32 v112, v131
	v_mov_b32_e32 v113, v131
	v_mov_b32_e32 v114, 0
	v_mov_b32_e32 v115, v131
	v_mov_b32_e32 v116, v131
	v_mov_b32_e32 v117, v131
	v_mov_b32_e32 v118, 0
	v_mov_b32_e32 v119, v131
	v_mov_b32_e32 v120, v131
	v_mov_b32_e32 v121, v131
	v_mov_b32_e32 v122, 0
	v_mov_b32_e32 v123, v131
	v_mov_b32_e32 v124, v131
	v_mov_b32_e32 v125, v131
	v_mov_b32_e32 v126, 0
	v_mov_b32_e32 v127, v131
	v_mov_b32_e32 v128, v131
	v_mov_b32_e32 v129, v131
	s_waitcnt lgkmcnt(0)
	s_barrier
	s_movk_i32 s97, 0x70
	v_readfirstlane_b32 s98, v142
	v_readfirstlane_b32 s99, v143
	v_subrev_u32_e32 v215, s98, v142
	v_bfi_b32 v215, s97, v144, v215
	v_add_u32_e32 v150, s12, v215
	v_add_u32_e32 v154, s13, v215
	v_add_u32_e32 v158, s14, v215
	v_add_u32_e32 v162, s15, v215
	s_add_u32 s98, s98, s0
	s_addc_u32 s99, s99, s1
	s_add_u32 s98, s98, 0x80
	s_addc_u32 s99, s99, 0
	v_readfirstlane_b32 s100, v140
	v_readfirstlane_b32 s101, v141
	v_subrev_u32_e32 v252, s100, v140
	v_bfi_b32 v252, s97, v144, v252
	v_add_u32_e32 v166, s16, v252
	v_add_u32_e32 v170, s17, v252
	v_add_u32_e32 v174, s28, v252
	v_add_u32_e32 v178, s29, v252
	s_add_u32 s100, s100, s0
	s_addc_u32 s101, s101, s1
	s_add_u32 s100, s100, 0x80
	s_addc_u32 s101, s101, 0
	v_readfirstlane_b32 s96, v144
	s_and_b32 s96, s96, 0xfc00
	s_cmp_lt_u32 s96, 0x1000
	s_cbranch_scc1 .Lg2_p6_np
	s_setprio 1
.Lg2_p6_np:
	s_add_u32 m0, s96, 0x8000
	s_nop 0
	global_load_lds_dwordx4 v150, s[98:99]
	s_add_u32 m0, m0, 0x2000
	s_nop 0
	global_load_lds_dwordx4 v154, s[98:99]
	s_add_u32 m0, m0, 0x2000
	s_nop 0
	global_load_lds_dwordx4 v158, s[98:99]
	s_add_u32 m0, m0, 0x2000
	s_nop 0
	global_load_lds_dwordx4 v162, s[98:99]
	s_add_u32 m0, m0, 0xa000
	s_nop 0
	global_load_lds_dwordx4 v166, s[100:101]
	s_add_u32 m0, m0, 0x2000
	s_nop 0
	global_load_lds_dwordx4 v170, s[100:101]
	s_add_u32 m0, m0, 0x2000
	s_nop 0
	global_load_lds_dwordx4 v174, s[100:101]
	s_add_u32 m0, m0, 0x2000
	s_nop 0
	global_load_lds_dwordx4 v178, s[100:101]
	ds_read_b128 v[182:185], v146
	ds_read_b128 v[186:189], v146 offset:2048
	ds_read_b128 v[190:193], v146 offset:4096
	ds_read_b128 v[194:197], v146 offset:6144
	ds_read_b128 v[218:221], v147
	ds_read_b128 v[224:227], v147 offset:2048
	ds_read_b128 v[228:231], v147 offset:4096
	ds_read_b128 v[232:235], v147 offset:6144

.Lg2_p6_tail:
	s_setprio 0
	s_nop 0
	v_mfma_f32_16x16x32_bf16 v[62:65], v[236:239], v[198:201], v[62:65]
	v_mfma_f32_16x16x32_bf16 v[58:61], v[240:243], v[198:201], v[58:61]
	v_mfma_f32_16x16x32_bf16 v[54:57], v[244:247], v[198:201], v[54:57]
	v_mfma_f32_16x16x32_bf16 v[50:53], v[248:251], v[198:201], v[50:53]
	v_mfma_f32_16x16x32_bf16 v[46:49], v[236:239], v[202:205], v[46:49]
	v_mfma_f32_16x16x32_bf16 v[42:45], v[240:243], v[202:205], v[42:45]
	v_mfma_f32_16x16x32_bf16 v[38:41], v[244:247], v[202:205], v[38:41]
	v_mfma_f32_16x16x32_bf16 v[34:37], v[248:251], v[202:205], v[34:37]
	v_mfma_f32_16x16x32_bf16 v[30:33], v[236:239], v[206:209], v[30:33]
	v_mfma_f32_16x16x32_bf16 v[26:29], v[240:243], v[206:209], v[26:29]
	v_mfma_f32_16x16x32_bf16 v[22:25], v[244:247], v[206:209], v[22:25]
	v_mfma_f32_16x16x32_bf16 v[18:21], v[248:251], v[206:209], v[18:21]
	v_mfma_f32_16x16x32_bf16 v[14:17], v[236:239], v[210:213], v[14:17]
	v_mfma_f32_16x16x32_bf16 v[10:13], v[240:243], v[210:213], v[10:13]
	v_mfma_f32_16x16x32_bf16 v[6:9], v[244:247], v[210:213], v[6:9]
	v_mfma_f32_16x16x32_bf16 v[2:5], v[248:251], v[210:213], v[2:5]
	ds_read_b128 v[140:143], v147 offset:32768
	ds_read_b128 v[150:153], v147 offset:34816
	ds_read_b128 v[154:157], v147 offset:36864
	ds_read_b128 v[158:161], v147 offset:38912
	ds_read_b128 v[162:165], v146 offset:32768
	ds_read_b128 v[166:169], v146 offset:34816
	ds_read_b128 v[170:173], v146 offset:36864
	ds_read_b128 v[174:177], v146 offset:38912
	s_setprio 1
	s_waitcnt lgkmcnt(3)
	v_mfma_f32_16x16x32_bf16 v[126:129], v[140:143], v[162:165], v[126:129]
	v_mfma_f32_16x16x32_bf16 v[122:125], v[150:153], v[162:165], v[122:125]
	v_mfma_f32_16x16x32_bf16 v[118:121], v[154:157], v[162:165], v[118:121]
	v_mfma_f32_16x16x32_bf16 v[114:117], v[158:161], v[162:165], v[114:117]
	s_waitcnt lgkmcnt(2)
	v_mfma_f32_16x16x32_bf16 v[110:113], v[140:143], v[166:169], v[110:113]
	v_mfma_f32_16x16x32_bf16 v[106:109], v[150:153], v[166:169], v[106:109]
	v_mfma_f32_16x16x32_bf16 v[102:105], v[154:157], v[166:169], v[102:105]
	v_mfma_f32_16x16x32_bf16 v[98:101], v[158:161], v[166:169], v[98:101]
	s_waitcnt lgkmcnt(1)
	v_mfma_f32_16x16x32_bf16 v[94:97], v[140:143], v[170:173], v[94:97]
	v_mfma_f32_16x16x32_bf16 v[90:93], v[150:153], v[170:173], v[90:93]
	v_mfma_f32_16x16x32_bf16 v[86:89], v[154:157], v[170:173], v[86:89]
	v_mfma_f32_16x16x32_bf16 v[82:85], v[158:161], v[170:173], v[82:85]
	s_waitcnt lgkmcnt(0)
	v_mfma_f32_16x16x32_bf16 v[78:81], v[140:143], v[174:177], v[78:81]
	v_mfma_f32_16x16x32_bf16 v[74:77], v[150:153], v[174:177], v[74:77]
	v_mfma_f32_16x16x32_bf16 v[70:73], v[154:157], v[174:177], v[70:73]
	v_mfma_f32_16x16x32_bf16 v[66:69], v[158:161], v[174:177], v[66:69]
	s_setprio 0
	ds_read_b128 v[162:165], v146 offset:40960
	ds_read_b128 v[166:169], v146 offset:43008
	ds_read_b128 v[170:173], v146 offset:45056
	ds_read_b128 v[174:177], v146 offset:47104
	s_setprio 1
	s_waitcnt lgkmcnt(3)
	v_mfma_f32_16x16x32_bf16 v[62:65], v[140:143], v[162:165], v[62:65]
	v_mfma_f32_16x16x32_bf16 v[58:61], v[150:153], v[162:165], v[58:61]
	v_mfma_f32_16x16x32_bf16 v[54:57], v[154:157], v[162:165], v[54:57]
	v_mfma_f32_16x16x32_bf16 v[50:53], v[158:161], v[162:165], v[50:53]
	s_waitcnt lgkmcnt(2)
	v_mfma_f32_16x16x32_bf16 v[46:49], v[140:143], v[166:169], v[46:49]
	v_mfma_f32_16x16x32_bf16 v[42:45], v[150:153], v[166:169], v[42:45]
	v_mfma_f32_16x16x32_bf16 v[38:41], v[154:157], v[166:169], v[38:41]
	v_mfma_f32_16x16x32_bf16 v[34:37], v[158:161], v[166:169], v[34:37]
	s_waitcnt lgkmcnt(1)
	v_mfma_f32_16x16x32_bf16 v[30:33], v[140:143], v[170:173], v[30:33]
	v_mfma_f32_16x16x32_bf16 v[26:29], v[150:153], v[170:173], v[26:29]
	v_mfma_f32_16x16x32_bf16 v[22:25], v[154:157], v[170:173], v[22:25]
	v_mfma_f32_16x16x32_bf16 v[18:21], v[158:161], v[170:173], v[18:21]
	s_waitcnt lgkmcnt(0)
	v_mfma_f32_16x16x32_bf16 v[14:17], v[140:143], v[174:177], v[14:17]
	v_mfma_f32_16x16x32_bf16 v[10:13], v[150:153], v[174:177], v[10:13]
	v_mfma_f32_16x16x32_bf16 v[6:9], v[154:157], v[174:177], v[6:9]
	v_mfma_f32_16x16x32_bf16 v[2:5], v[158:161], v[174:177], v[2:5]
	s_setprio 0
	ds_read_b128 v[140:143], v217 offset:32768
	ds_read_b128 v[150:153], v217 offset:34816
	ds_read_b128 v[154:157], v217 offset:36864
	ds_read_b128 v[158:161], v217 offset:38912
	ds_read_b128 v[162:165], v216 offset:32768
	ds_read_b128 v[166:169], v216 offset:34816
	ds_read_b128 v[170:173], v216 offset:36864
	ds_read_b128 v[174:177], v216 offset:38912
	s_setprio 1
	s_waitcnt lgkmcnt(3)
	v_mfma_f32_16x16x32_bf16 v[126:129], v[140:143], v[162:165], v[126:129]
	v_mfma_f32_16x16x32_bf16 v[122:125], v[150:153], v[162:165], v[122:125]
	v_mfma_f32_16x16x32_bf16 v[118:121], v[154:157], v[162:165], v[118:121]
	v_mfma_f32_16x16x32_bf16 v[114:117], v[158:161], v[162:165], v[114:117]
	s_waitcnt lgkmcnt(2)
	v_mfma_f32_16x16x32_bf16 v[110:113], v[140:143], v[166:169], v[110:113]
	v_mfma_f32_16x16x32_bf16 v[106:109], v[150:153], v[166:169], v[106:109]
	v_mfma_f32_16x16x32_bf16 v[102:105], v[154:157], v[166:169], v[102:105]
	v_mfma_f32_16x16x32_bf16 v[98:101], v[158:161], v[166:169], v[98:101]
	s_waitcnt lgkmcnt(1)
	v_mfma_f32_16x16x32_bf16 v[94:97], v[140:143], v[170:173], v[94:97]
	v_mfma_f32_16x16x32_bf16 v[162:165], v[150:153], v[170:173], v[90:93]
	v_mfma_f32_16x16x32_bf16 v[86:89], v[154:157], v[170:173], v[86:89]
	v_mfma_f32_16x16x32_bf16 v[82:85], v[158:161], v[170:173], v[82:85]
	s_waitcnt lgkmcnt(0)
	v_mfma_f32_16x16x32_bf16 v[78:81], v[140:143], v[174:177], v[78:81]
	v_mfma_f32_16x16x32_bf16 v[74:77], v[150:153], v[174:177], v[74:77]
	v_mfma_f32_16x16x32_bf16 v[70:73], v[154:157], v[174:177], v[70:73]
	v_mfma_f32_16x16x32_bf16 v[66:69], v[158:161], v[174:177], v[66:69]
	s_setprio 0
	ds_read_b128 v[90:93], v216 offset:40960
	ds_read_b128 v[166:169], v216 offset:43008
	ds_read_b128 v[170:173], v216 offset:45056
	ds_read_b128 v[174:177], v216 offset:47104
	s_setprio 1
	s_waitcnt lgkmcnt(3)
	v_mfma_f32_16x16x32_bf16 v[62:65], v[140:143], v[90:93], v[62:65]
	v_mfma_f32_16x16x32_bf16 v[58:61], v[150:153], v[90:93], v[58:61]
	v_mfma_f32_16x16x32_bf16 v[54:57], v[154:157], v[90:93], v[54:57]
	v_mfma_f32_16x16x32_bf16 v[50:53], v[158:161], v[90:93], v[50:53]
	s_waitcnt lgkmcnt(2)
	v_mfma_f32_16x16x32_bf16 v[46:49], v[140:143], v[166:169], v[46:49]
	v_mfma_f32_16x16x32_bf16 v[42:45], v[150:153], v[166:169], v[42:45]
	v_mfma_f32_16x16x32_bf16 v[38:41], v[154:157], v[166:169], v[38:41]
	v_mfma_f32_16x16x32_bf16 v[34:37], v[158:161], v[166:169], v[34:37]
	s_waitcnt lgkmcnt(1)
	v_mfma_f32_16x16x32_bf16 v[30:33], v[140:143], v[170:173], v[30:33]
	v_mfma_f32_16x16x32_bf16 v[26:29], v[150:153], v[170:173], v[26:29]
	v_mfma_f32_16x16x32_bf16 v[22:25], v[154:157], v[170:173], v[22:25]
	v_mfma_f32_16x16x32_bf16 v[18:21], v[158:161], v[170:173], v[18:21]
	s_waitcnt lgkmcnt(0)
	v_mfma_f32_16x16x32_bf16 v[14:17], v[140:143], v[174:177], v[14:17]
	v_mfma_f32_16x16x32_bf16 v[10:13], v[150:153], v[174:177], v[10:13]
	v_mfma_f32_16x16x32_bf16 v[6:9], v[154:157], v[174:177], v[6:9]
	v_mfma_f32_16x16x32_bf16 v[2:5], v[158:161], v[174:177], v[2:5]
	s_setprio 0
	v_mul_f32_e32 v93, 0xbfb8aa3b, v126
	v_exp_f32_e32 v93, v93
	v_mul_f32_e32 v130, 0xbfb8aa3b, v127
	v_exp_f32_e32 v130, v130
	v_mul_f32_e32 v141, 0xbfb8aa3b, v129
	v_add_f32_e32 v93, 1.0, v93
	v_rcp_f32_e32 v140, v93
	v_add_f32_e32 v93, 1.0, v130
	v_mul_f32_e32 v130, 0xbfb8aa3b, v128
	v_exp_f32_e32 v130, v130
	v_exp_f32_e32 v143, v141
	v_rcp_f32_e32 v141, v93
	v_or_b32_e32 v90, s38, v148
	v_add_f32_e32 v93, 1.0, v130
	v_rcp_f32_e32 v142, v93
	v_add_f32_e32 v93, 1.0, v143
	v_rcp_f32_e32 v143, v93
	v_pk_mul_f32 v[126:127], v[126:127], v[140:141]
	v_mul_f32_e32 v93, 0xbfb8aa3b, v118
	v_pk_mul_f32 v[122:123], v[122:123], v[126:127]
	v_pk_mul_f32 v[126:127], v[128:129], v[142:143]
	v_cvt_pk_bf16_f32 v122, v122, v123
	v_exp_f32_e32 v93, v93
	v_mul_f32_e32 v123, 0xbfb8aa3b, v119
	v_pk_mul_f32 v[124:125], v[124:125], v[126:127]
	v_exp_f32_e32 v126, v123
	v_cvt_pk_bf16_f32 v123, v124, v125
	v_add_f32_e32 v93, 1.0, v93
	v_mul_f32_e32 v125, 0xbfb8aa3b, v120
	v_rcp_f32_e32 v124, v93
	v_add_f32_e32 v93, 1.0, v126
	v_exp_f32_e32 v126, v125
	v_mul_f32_e32 v125, 0xbfb8aa3b, v121
	v_exp_f32_e32 v127, v125
	v_rcp_f32_e32 v125, v93
	v_add_f32_e32 v93, 1.0, v126
	v_rcp_f32_e32 v126, v93
	v_add_f32_e32 v93, 1.0, v127
	v_rcp_f32_e32 v127, v93
	v_ashrrev_i32_e32 v90, 1, v90
	v_pk_mul_f32 v[118:119], v[118:119], v[124:125]
	v_ashrrev_i32_e32 v91, 31, v90
	v_pk_mul_f32 v[114:115], v[114:115], v[118:119]
	v_pk_mul_f32 v[118:119], v[120:121], v[126:127]
	v_add_u32_e32 v92, s37, v149
	v_lshl_add_u64 v[90:91], v[90:91], 1, v[136:137]
	v_pk_mul_f32 v[116:117], v[116:117], v[118:119]
	v_mad_i64_i32 v[150:151], s[0:1], v92, s36, v[90:91]
	v_cvt_pk_bf16_f32 v114, v114, v115
	v_cvt_pk_bf16_f32 v115, v116, v117
	v_mul_f32_e32 v93, 0xbfb8aa3b, v110
	s_barrier
	global_store_dwordx2 v[150:151], v[114:115], off offset:32
	v_exp_f32_e32 v93, v93
	v_mul_f32_e32 v114, 0xbfb8aa3b, v111
	v_exp_f32_e32 v115, v114
	v_or_b32_e32 v118, 16, v92
	v_add_f32_e32 v93, 1.0, v93
	v_rcp_f32_e32 v114, v93
	v_add_f32_e32 v93, 1.0, v115
	v_mul_f32_e32 v115, 0xbfb8aa3b, v112
	v_exp_f32_e32 v116, v115
	v_mul_f32_e32 v115, 0xbfb8aa3b, v113
	v_exp_f32_e32 v117, v115
	v_rcp_f32_e32 v115, v93
	v_add_f32_e32 v93, 1.0, v116
	v_rcp_f32_e32 v116, v93
	v_add_f32_e32 v93, 1.0, v117
	v_rcp_f32_e32 v117, v93
	v_pk_mul_f32 v[110:111], v[110:111], v[114:115]
	v_mul_f32_e32 v93, 0xbfb8aa3b, v102
	v_pk_mul_f32 v[106:107], v[106:107], v[110:111]
	v_pk_mul_f32 v[110:111], v[112:113], v[116:117]
	v_cvt_pk_bf16_f32 v106, v106, v107
	v_exp_f32_e32 v93, v93
	v_mul_f32_e32 v107, 0xbfb8aa3b, v103
	v_pk_mul_f32 v[108:109], v[108:109], v[110:111]
	v_exp_f32_e32 v110, v107
	v_cvt_pk_bf16_f32 v107, v108, v109
	v_add_f32_e32 v93, 1.0, v93
	v_mul_f32_e32 v109, 0xbfb8aa3b, v104
	v_rcp_f32_e32 v108, v93
	v_add_f32_e32 v93, 1.0, v110
	v_exp_f32_e32 v110, v109
	v_mul_f32_e32 v109, 0xbfb8aa3b, v105
	v_exp_f32_e32 v111, v109
	v_rcp_f32_e32 v109, v93
	v_add_f32_e32 v93, 1.0, v110
	v_rcp_f32_e32 v110, v93
	v_add_f32_e32 v93, 1.0, v111
	v_rcp_f32_e32 v111, v93
	v_pk_mul_f32 v[102:103], v[102:103], v[108:109]
	v_mad_i64_i32 v[118:119], s[0:1], v118, s36, v[90:91]
	v_pk_mul_f32 v[98:99], v[98:99], v[102:103]
	v_pk_mul_f32 v[102:103], v[104:105], v[110:111]
	v_cvt_pk_bf16_f32 v98, v98, v99
	v_pk_mul_f32 v[100:101], v[100:101], v[102:103]
	v_mul_f32_e32 v93, 0xbfb8aa3b, v94
	v_cvt_pk_bf16_f32 v99, v100, v101
	global_store_dwordx2 v[118:119], v[98:99], off offset:32
	v_exp_f32_e32 v93, v93
	v_mul_f32_e32 v98, 0xbfb8aa3b, v95
	v_exp_f32_e32 v99, v98
	v_or_b32_e32 v102, 32, v92
	v_add_f32_e32 v93, 1.0, v93
	v_rcp_f32_e32 v98, v93
	v_add_f32_e32 v93, 1.0, v99
	v_mul_f32_e32 v99, 0xbfb8aa3b, v96
	v_exp_f32_e32 v100, v99
	v_mul_f32_e32 v99, 0xbfb8aa3b, v97
	v_exp_f32_e32 v101, v99
	v_rcp_f32_e32 v99, v93
	v_add_f32_e32 v93, 1.0, v100
	v_rcp_f32_e32 v100, v93
	v_add_f32_e32 v93, 1.0, v101
	v_rcp_f32_e32 v101, v93
	v_pk_mul_f32 v[94:95], v[94:95], v[98:99]
	v_mul_f32_e32 v93, 0xbfb8aa3b, v86
	v_pk_mul_f32 v[94:95], v[162:163], v[94:95]
	v_exp_f32_e32 v93, v93
	v_cvt_pk_bf16_f32 v94, v94, v95
	v_mul_f32_e32 v95, 0xbfb8aa3b, v87
	v_exp_f32_e32 v98, v95
	v_pk_mul_f32 v[96:97], v[96:97], v[100:101]
	v_add_f32_e32 v93, 1.0, v93
	v_pk_mul_f32 v[96:97], v[164:165], v[96:97]
	v_mad_i64_i32 v[102:103], s[0:1], v102, s36, v[90:91]
	v_cvt_pk_bf16_f32 v95, v96, v97
	v_mul_f32_e32 v97, 0xbfb8aa3b, v88
	v_rcp_f32_e32 v96, v93
	v_add_f32_e32 v93, 1.0, v98
	v_exp_f32_e32 v98, v97
	v_mul_f32_e32 v97, 0xbfb8aa3b, v89
	v_exp_f32_e32 v99, v97
	v_rcp_f32_e32 v97, v93
	v_add_f32_e32 v93, 1.0, v98
	v_rcp_f32_e32 v98, v93
	v_add_f32_e32 v93, 1.0, v99
	v_rcp_f32_e32 v99, v93
	v_pk_mul_f32 v[86:87], v[86:87], v[96:97]
	s_add_i32 s3, s3, s7
	v_pk_mul_f32 v[82:83], v[82:83], v[86:87]
	v_pk_mul_f32 v[86:87], v[88:89], v[98:99]
	v_cvt_pk_bf16_f32 v82, v82, v83
	v_pk_mul_f32 v[84:85], v[84:85], v[86:87]
	v_or_b32_e32 v86, 48, v92
	v_cvt_pk_bf16_f32 v83, v84, v85
	global_store_dwordx2 v[102:103], v[82:83], off offset:32
	v_mul_f32_e32 v82, 0xbfb8aa3b, v78
	v_mul_f32_e32 v83, 0xbfb8aa3b, v79
	v_exp_f32_e32 v82, v82
	v_exp_f32_e32 v83, v83
	v_mul_f32_e32 v84, 0xbfb8aa3b, v80
	v_mul_f32_e32 v85, 0xbfb8aa3b, v81
	v_exp_f32_e32 v84, v84
	v_exp_f32_e32 v85, v85
	v_add_f32_e32 v82, 1.0, v82
	v_add_f32_e32 v83, 1.0, v83
	v_rcp_f32_e32 v82, v82
	v_rcp_f32_e32 v83, v83
	v_add_f32_e32 v84, 1.0, v84
	v_add_f32_e32 v85, 1.0, v85
	v_rcp_f32_e32 v84, v84
	v_rcp_f32_e32 v85, v85
	v_pk_mul_f32 v[78:79], v[78:79], v[82:83]
	v_mad_i64_i32 v[86:87], s[0:1], v86, s36, v[90:91]
	v_pk_mul_f32 v[74:75], v[74:75], v[78:79]
	v_pk_mul_f32 v[78:79], v[80:81], v[84:85]
	v_cvt_pk_bf16_f32 v74, v74, v75
	v_mul_f32_e32 v75, 0xbfb8aa3b, v70
	v_pk_mul_f32 v[76:77], v[76:77], v[78:79]
	v_exp_f32_e32 v78, v75
	v_mul_f32_e32 v75, 0xbfb8aa3b, v71
	v_exp_f32_e32 v79, v75
	v_cvt_pk_bf16_f32 v75, v76, v77
	v_add_f32_e32 v76, 1.0, v78
	v_mul_f32_e32 v78, 0xbfb8aa3b, v72
	v_add_f32_e32 v77, 1.0, v79
	v_mul_f32_e32 v79, 0xbfb8aa3b, v73
	v_exp_f32_e32 v78, v78
	v_exp_f32_e32 v79, v79
	v_rcp_f32_e32 v76, v76
	v_rcp_f32_e32 v77, v77
	v_add_f32_e32 v78, 1.0, v78
	v_add_f32_e32 v79, 1.0, v79
	v_rcp_f32_e32 v78, v78
	v_rcp_f32_e32 v79, v79
	v_pk_mul_f32 v[70:71], v[70:71], v[76:77]
	s_add_i32 s8, s8, s7
	v_pk_mul_f32 v[66:67], v[66:67], v[70:71]
	v_pk_mul_f32 v[70:71], v[72:73], v[78:79]
	v_cvt_pk_bf16_f32 v66, v66, v67
	v_pk_mul_f32 v[68:69], v[68:69], v[70:71]
	v_or_b32_e32 v70, 64, v92
	v_cvt_pk_bf16_f32 v67, v68, v69
	global_store_dwordx2 v[86:87], v[66:67], off offset:32
	v_mul_f32_e32 v66, 0xbfb8aa3b, v62
	v_mul_f32_e32 v67, 0xbfb8aa3b, v63
	v_exp_f32_e32 v66, v66
	v_exp_f32_e32 v67, v67
	v_mul_f32_e32 v68, 0xbfb8aa3b, v64
	v_mul_f32_e32 v69, 0xbfb8aa3b, v65
	v_exp_f32_e32 v68, v68
	v_exp_f32_e32 v69, v69
	v_add_f32_e32 v66, 1.0, v66
	v_add_f32_e32 v67, 1.0, v67
	v_rcp_f32_e32 v66, v66
	v_rcp_f32_e32 v67, v67
	v_add_f32_e32 v68, 1.0, v68
	v_add_f32_e32 v69, 1.0, v69
	v_rcp_f32_e32 v68, v68
	v_rcp_f32_e32 v69, v69
	v_pk_mul_f32 v[62:63], v[62:63], v[66:67]
	v_mad_i64_i32 v[70:71], s[0:1], v70, s36, v[90:91]
	v_pk_mul_f32 v[58:59], v[58:59], v[62:63]
	v_pk_mul_f32 v[62:63], v[64:65], v[68:69]
	v_cvt_pk_bf16_f32 v58, v58, v59
	v_mul_f32_e32 v59, 0xbfb8aa3b, v54
	v_pk_mul_f32 v[60:61], v[60:61], v[62:63]
	v_exp_f32_e32 v62, v59
	v_mul_f32_e32 v59, 0xbfb8aa3b, v55
	v_exp_f32_e32 v63, v59
	v_cvt_pk_bf16_f32 v59, v60, v61
	v_add_f32_e32 v60, 1.0, v62
	v_mul_f32_e32 v62, 0xbfb8aa3b, v56
	v_add_f32_e32 v61, 1.0, v63
	v_mul_f32_e32 v63, 0xbfb8aa3b, v57
	v_exp_f32_e32 v62, v62
	v_exp_f32_e32 v63, v63
	v_rcp_f32_e32 v60, v60
	v_rcp_f32_e32 v61, v61
	v_add_f32_e32 v62, 1.0, v62
	v_add_f32_e32 v63, 1.0, v63
	v_rcp_f32_e32 v62, v62
	v_rcp_f32_e32 v63, v63
	v_pk_mul_f32 v[54:55], v[54:55], v[60:61]
	s_cmpk_gt_i32 s3, 0x2d5
	v_pk_mul_f32 v[50:51], v[50:51], v[54:55]
	v_pk_mul_f32 v[54:55], v[56:57], v[62:63]
	v_cvt_pk_bf16_f32 v50, v50, v51
	v_pk_mul_f32 v[52:53], v[52:53], v[54:55]
	v_or_b32_e32 v54, 0x50, v92
	v_cvt_pk_bf16_f32 v51, v52, v53
	global_store_dwordx2 v[70:71], v[50:51], off offset:32
	v_mul_f32_e32 v50, 0xbfb8aa3b, v46
	v_mul_f32_e32 v51, 0xbfb8aa3b, v47
	v_exp_f32_e32 v50, v50
	v_exp_f32_e32 v51, v51
	v_mul_f32_e32 v52, 0xbfb8aa3b, v48
	v_mul_f32_e32 v53, 0xbfb8aa3b, v49
	v_exp_f32_e32 v52, v52
	v_exp_f32_e32 v53, v53
	v_add_f32_e32 v50, 1.0, v50
	v_add_f32_e32 v51, 1.0, v51
	v_rcp_f32_e32 v50, v50
	v_rcp_f32_e32 v51, v51
	v_add_f32_e32 v52, 1.0, v52
	v_add_f32_e32 v53, 1.0, v53
	v_rcp_f32_e32 v52, v52
	v_rcp_f32_e32 v53, v53
	v_pk_mul_f32 v[46:47], v[46:47], v[50:51]
	v_mad_i64_i32 v[54:55], s[0:1], v54, s36, v[90:91]
	v_pk_mul_f32 v[42:43], v[42:43], v[46:47]
	v_pk_mul_f32 v[46:47], v[48:49], v[52:53]
	v_cvt_pk_bf16_f32 v42, v42, v43
	v_mul_f32_e32 v43, 0xbfb8aa3b, v38
	v_pk_mul_f32 v[44:45], v[44:45], v[46:47]
	v_exp_f32_e32 v46, v43
	v_mul_f32_e32 v43, 0xbfb8aa3b, v39
	v_exp_f32_e32 v47, v43
	v_cvt_pk_bf16_f32 v43, v44, v45
	v_add_f32_e32 v44, 1.0, v46
	v_mul_f32_e32 v46, 0xbfb8aa3b, v40
	v_add_f32_e32 v45, 1.0, v47
	v_mul_f32_e32 v47, 0xbfb8aa3b, v41
	v_exp_f32_e32 v46, v46
	v_exp_f32_e32 v47, v47
	v_rcp_f32_e32 v44, v44
	v_rcp_f32_e32 v45, v45
	v_add_f32_e32 v46, 1.0, v46
	v_add_f32_e32 v47, 1.0, v47
	v_rcp_f32_e32 v46, v46
	v_rcp_f32_e32 v47, v47
	v_pk_mul_f32 v[38:39], v[38:39], v[44:45]
	global_store_dwordx2 v[150:151], v[122:123], off
	v_pk_mul_f32 v[34:35], v[34:35], v[38:39]
	v_pk_mul_f32 v[38:39], v[40:41], v[46:47]
	v_cvt_pk_bf16_f32 v34, v34, v35
	v_pk_mul_f32 v[36:37], v[36:37], v[38:39]
	v_or_b32_e32 v38, 0x60, v92
	v_cvt_pk_bf16_f32 v35, v36, v37
	global_store_dwordx2 v[54:55], v[34:35], off offset:32
	v_mul_f32_e32 v34, 0xbfb8aa3b, v30
	v_mul_f32_e32 v35, 0xbfb8aa3b, v31
	v_exp_f32_e32 v34, v34
	v_exp_f32_e32 v35, v35
	v_mul_f32_e32 v36, 0xbfb8aa3b, v32
	v_mul_f32_e32 v37, 0xbfb8aa3b, v33
	v_exp_f32_e32 v36, v36
	v_exp_f32_e32 v37, v37
	v_add_f32_e32 v34, 1.0, v34
	v_add_f32_e32 v35, 1.0, v35
	v_rcp_f32_e32 v34, v34
	v_rcp_f32_e32 v35, v35
	v_add_f32_e32 v36, 1.0, v36
	v_add_f32_e32 v37, 1.0, v37
	v_rcp_f32_e32 v36, v36
	v_rcp_f32_e32 v37, v37
	v_pk_mul_f32 v[30:31], v[30:31], v[34:35]
	v_mad_i64_i32 v[38:39], s[0:1], v38, s36, v[90:91]
	v_pk_mul_f32 v[26:27], v[26:27], v[30:31]
	v_pk_mul_f32 v[30:31], v[32:33], v[36:37]
	v_cvt_pk_bf16_f32 v26, v26, v27
	v_mul_f32_e32 v27, 0xbfb8aa3b, v22
	v_pk_mul_f32 v[28:29], v[28:29], v[30:31]
	v_exp_f32_e32 v30, v27
	v_mul_f32_e32 v27, 0xbfb8aa3b, v23
	v_exp_f32_e32 v31, v27
	v_cvt_pk_bf16_f32 v27, v28, v29
	v_add_f32_e32 v28, 1.0, v30
	v_mul_f32_e32 v30, 0xbfb8aa3b, v24
	v_add_f32_e32 v29, 1.0, v31
	v_mul_f32_e32 v31, 0xbfb8aa3b, v25
	v_exp_f32_e32 v30, v30
	v_exp_f32_e32 v31, v31
	v_rcp_f32_e32 v28, v28
	v_rcp_f32_e32 v29, v29
	v_add_f32_e32 v30, 1.0, v30
	v_add_f32_e32 v31, 1.0, v31
	v_rcp_f32_e32 v30, v30
	v_rcp_f32_e32 v31, v31
	v_pk_mul_f32 v[22:23], v[22:23], v[28:29]
	global_store_dwordx2 v[118:119], v[106:107], off
	v_pk_mul_f32 v[18:19], v[18:19], v[22:23]
	v_pk_mul_f32 v[22:23], v[24:25], v[30:31]
	v_cvt_pk_bf16_f32 v18, v18, v19
	v_pk_mul_f32 v[20:21], v[20:21], v[22:23]
	v_or_b32_e32 v22, 0x70, v92
	v_cvt_pk_bf16_f32 v19, v20, v21
	global_store_dwordx2 v[38:39], v[18:19], off offset:32
	v_mul_f32_e32 v18, 0xbfb8aa3b, v14
	v_mul_f32_e32 v19, 0xbfb8aa3b, v15
	v_exp_f32_e32 v18, v18
	v_exp_f32_e32 v19, v19
	v_mul_f32_e32 v20, 0xbfb8aa3b, v16
	v_mul_f32_e32 v21, 0xbfb8aa3b, v17
	v_exp_f32_e32 v20, v20
	v_exp_f32_e32 v21, v21
	v_add_f32_e32 v18, 1.0, v18
	v_add_f32_e32 v19, 1.0, v19
	v_rcp_f32_e32 v18, v18
	v_rcp_f32_e32 v19, v19
	v_add_f32_e32 v20, 1.0, v20
	v_add_f32_e32 v21, 1.0, v21
	v_rcp_f32_e32 v20, v20
	v_rcp_f32_e32 v21, v21
	v_pk_mul_f32 v[14:15], v[14:15], v[18:19]
	v_mad_i64_i32 v[22:23], s[0:1], v22, s36, v[90:91]
	v_pk_mul_f32 v[10:11], v[10:11], v[14:15]
	v_pk_mul_f32 v[14:15], v[16:17], v[20:21]
	v_cvt_pk_bf16_f32 v10, v10, v11
	v_mul_f32_e32 v11, 0xbfb8aa3b, v6
	v_pk_mul_f32 v[12:13], v[12:13], v[14:15]
	v_exp_f32_e32 v14, v11
	v_mul_f32_e32 v11, 0xbfb8aa3b, v7
	v_exp_f32_e32 v15, v11
	v_cvt_pk_bf16_f32 v11, v12, v13
	v_add_f32_e32 v12, 1.0, v14
	v_mul_f32_e32 v14, 0xbfb8aa3b, v8
	v_add_f32_e32 v13, 1.0, v15
	v_mul_f32_e32 v15, 0xbfb8aa3b, v9
	v_exp_f32_e32 v14, v14
	v_exp_f32_e32 v15, v15
	v_rcp_f32_e32 v12, v12
	v_rcp_f32_e32 v13, v13
	v_add_f32_e32 v14, 1.0, v14
	v_add_f32_e32 v15, 1.0, v15
	v_rcp_f32_e32 v14, v14
	v_rcp_f32_e32 v15, v15
	v_pk_mul_f32 v[6:7], v[6:7], v[12:13]
	global_store_dwordx2 v[102:103], v[94:95], off
	v_pk_mul_f32 v[2:3], v[2:3], v[6:7]
	v_pk_mul_f32 v[6:7], v[8:9], v[14:15]
	v_cvt_pk_bf16_f32 v2, v2, v3
	v_pk_mul_f32 v[4:5], v[4:5], v[6:7]
	global_store_dwordx2 v[86:87], v[74:75], off
	v_cvt_pk_bf16_f32 v3, v4, v5
	global_store_dwordx2 v[70:71], v[58:59], off
	global_store_dwordx2 v[54:55], v[42:43], off
	global_store_dwordx2 v[38:39], v[26:27], off
	global_store_dwordx2 v[22:23], v[10:11], off
	global_store_dwordx2 v[22:23], v[2:3], off offset:32
	s_cbranch_scc0 .LBB0_354

.LBB0_378:
	s_lshl_b32 s47, s45, 8
	v_or_b32_e32 v27, s47, v1
	v_mad_i64_i32 v[2:3], s[8:9], v27, s12, v[130:131]
	v_add_co_u32_e32 v6, vcc, 0x58000, v2
	s_lshl_b32 s46, s44, 8
	s_nop 0
	v_addc_co_u32_e32 v7, vcc, 0, v3, vcc
	global_load_dwordx4 v[28:31], v[2:3], off
	global_load_dwordx4 v[32:35], v[6:7], off
	v_add_co_u32_e32 v6, vcc, 0xb0000, v2
	v_or_b32_e32 v60, s46, v1
	s_nop 0
	v_addc_co_u32_e32 v7, vcc, 0, v3, vcc
	v_add_co_u32_e32 v2, vcc, 0x108000, v2
	v_mad_i64_i32 v[4:5], s[8:9], v60, s12, v[132:133]
	s_nop 0
	v_addc_co_u32_e32 v3, vcc, 0, v3, vcc
	global_load_dwordx4 v[36:39], v[6:7], off
	global_load_dwordx4 v[40:43], v[2:3], off
	v_add_co_u32_e32 v2, vcc, s13, v4
	s_waitcnt vmcnt(63) expcnt(7) lgkmcnt(15)
	s_nop 0
	v_addc_co_u32_e32 v3, vcc, 0, v5, vcc
	s_barrier
	global_load_dwordx4 v[44:47], v[4:5], off
	global_load_dwordx4 v[48:51], v[2:3], off
	v_add_co_u32_e32 v2, vcc, s14, v4
	s_mov_b32 s52, 0
	s_nop 0
	v_addc_co_u32_e32 v3, vcc, 0, v5, vcc
	v_add_co_u32_e32 v4, vcc, s15, v4
	s_mov_b64 s[8:9], 0
	s_nop 0
	v_addc_co_u32_e32 v5, vcc, 0, v5, vcc
	global_load_dwordx4 v[52:55], v[2:3], off
	global_load_dwordx4 v[56:59], v[4:5], off
	v_mov_b32_e32 v2, 0
	v_mov_b32_e32 v3, v2
	v_mov_b32_e32 v4, v2
	v_mov_b32_e32 v5, v2
	v_mov_b32_e32 v6, v2
	v_mov_b32_e32 v7, v2
	v_mov_b32_e32 v8, v2
	v_mov_b32_e32 v9, v2
	v_mov_b32_e32 v10, v2
	v_mov_b32_e32 v11, v2
	v_mov_b32_e32 v12, v2
	v_mov_b32_e32 v13, v2
	v_mov_b32_e32 v14, v2
	v_mov_b32_e32 v15, v2
	v_mov_b32_e32 v16, v2
	v_mov_b32_e32 v17, v2
	v_mov_b32_e32 v18, v2
	v_mov_b32_e32 v19, v2
	v_mov_b32_e32 v20, v2
	v_mov_b32_e32 v21, v2
	v_mov_b32_e32 v22, v2
	v_mov_b32_e32 v23, v2
	v_mov_b32_e32 v24, v2
	v_mov_b32_e32 v25, v2
	v_mov_b32_e32 v26, v2
	v_mad_i64_i32 v[136:137], s[56:57], v27, s12, v[134:135]
	v_mad_i64_i32 v[138:139], s[56:57], v60, s12, v[134:135]
	v_mov_b32_e32 v27, v2
	v_mov_b32_e32 v60, v2
	v_mov_b32_e32 v61, v2
	v_mov_b32_e32 v62, v2
	v_mov_b32_e32 v63, v2
	v_mov_b32_e32 v64, v2
	v_mov_b32_e32 v65, v2
	v_mov_b32_e32 v66, v2
	v_mov_b32_e32 v67, v2
	v_mov_b32_e32 v68, v2
	v_mov_b32_e32 v69, v2
	v_mov_b32_e32 v70, v2
	v_mov_b32_e32 v71, v2
	v_mov_b32_e32 v72, v2
	v_mov_b32_e32 v73, v2
	v_mov_b32_e32 v74, v2
	v_mov_b32_e32 v75, v2
	v_mov_b32_e32 v76, v2
	v_mov_b32_e32 v77, v2
	v_mov_b32_e32 v78, v2
	v_mov_b32_e32 v79, v2
	v_mov_b32_e32 v80, v2
	v_mov_b32_e32 v81, v2
	v_mov_b32_e32 v82, v2
	s_waitcnt vmcnt(7)
	ds_write_b128 v146, v[28:31]
	s_waitcnt vmcnt(6)
	ds_write_b128 v146, v[32:35] offset:8192
	s_waitcnt vmcnt(5)
	ds_write_b128 v146, v[36:39] offset:16384
	s_waitcnt vmcnt(4)
	ds_write_b128 v146, v[40:43] offset:24576
	s_waitcnt vmcnt(3)
	ds_write_b128 v147, v[44:47]
	s_waitcnt vmcnt(2)
	ds_write_b128 v147, v[48:51] offset:8192
	s_waitcnt vmcnt(1)
	ds_write_b128 v147, v[52:55] offset:16384
	s_waitcnt vmcnt(0)
	ds_write_b128 v147, v[56:59] offset:24576
	v_mov_b32_e32 v28, v2
	v_mov_b32_e32 v29, v2
	v_mov_b32_e32 v30, v2
	v_mov_b32_e32 v31, v2
	v_mov_b32_e32 v32, v2
	v_mov_b32_e32 v33, v2
	v_mov_b32_e32 v34, v2
	v_mov_b32_e32 v35, v2
	v_mov_b32_e32 v36, v2
	v_mov_b32_e32 v37, v2
	v_mov_b32_e32 v38, v2
	v_mov_b32_e32 v39, v2
	v_mov_b32_e32 v40, v2
	v_mov_b32_e32 v41, v2
	v_mov_b32_e32 v42, v2
	v_mov_b32_e32 v43, v2
	v_mov_b32_e32 v44, v2
	v_mov_b32_e32 v45, v2
	v_mov_b32_e32 v46, v2
	v_mov_b32_e32 v47, v2
	v_mov_b32_e32 v48, v2
	v_mov_b32_e32 v49, v2
	v_mov_b32_e32 v50, v2
	v_mov_b32_e32 v51, v2
	v_mov_b32_e32 v52, v2
	v_mov_b32_e32 v53, v2
	v_mov_b32_e32 v54, v2
	v_mov_b32_e32 v55, v2
	v_mov_b32_e32 v56, v2
	v_mov_b32_e32 v57, v2
	v_mov_b32_e32 v58, v2
	v_mov_b32_e32 v59, v2
	v_mov_b32_e32 v83, v2
	v_mov_b32_e32 v84, v2
	v_mov_b32_e32 v85, v2
	v_mov_b32_e32 v86, v2
	v_mov_b32_e32 v87, v2
	v_mov_b32_e32 v88, v2
	v_mov_b32_e32 v89, v2
	v_mov_b32_e32 v90, v2
	v_mov_b32_e32 v91, v2
	v_mov_b32_e32 v92, v2
	v_mov_b32_e32 v93, v2
	v_mov_b32_e32 v94, v2
	v_mov_b32_e32 v95, v2
	v_mov_b32_e32 v96, v2
	v_mov_b32_e32 v97, v2
	v_mov_b32_e32 v98, v2
	v_mov_b32_e32 v99, v2
	v_mov_b32_e32 v100, v2
	v_mov_b32_e32 v101, v2
	v_mov_b32_e32 v102, v2
	v_mov_b32_e32 v103, v2
	v_mov_b32_e32 v104, v2
	v_mov_b32_e32 v105, v2
	v_mov_b32_e32 v106, v2
	v_mov_b32_e32 v107, v2
	v_mov_b32_e32 v108, v2
	v_mov_b32_e32 v109, v2
	v_mov_b32_e32 v110, v2
	v_mov_b32_e32 v111, v2
	v_mov_b32_e32 v112, v2
	v_mov_b32_e32 v113, v2
	v_mov_b32_e32 v114, v2
	v_mov_b32_e32 v115, v2
	v_mov_b32_e32 v116, v2
	v_mov_b32_e32 v117, v2
	v_mov_b32_e32 v118, v2
	v_mov_b32_e32 v119, v2
	v_mov_b32_e32 v120, v2
	v_mov_b32_e32 v121, v2
	v_mov_b32_e32 v122, v2
	v_mov_b32_e32 v123, v2
	v_mov_b32_e32 v124, v2
	v_mov_b32_e32 v125, v2
	v_mov_b32_e32 v126, v2
	v_mov_b32_e32 v127, v2
	v_mov_b32_e32 v128, v2
	v_mov_b32_e32 v129, v2
	s_waitcnt lgkmcnt(0)
	s_barrier
	s_movk_i32 s97, 0x70
	v_readfirstlane_b32 s98, v136
	v_readfirstlane_b32 s99, v137
	v_subrev_u32_e32 v248, s98, v136
	v_bfi_b32 v248, s97, v146, v248
	v_add_u32_e32 v140, s16, v248
	v_add_u32_e32 v152, s17, v248
	v_add_u32_e32 v156, s28, v248
	v_add_u32_e32 v160, s29, v248
	s_add_u32 s98, s98, s8
	s_addc_u32 s99, s99, s9
	s_add_u32 s98, s98, 0x80
	s_addc_u32 s99, s99, 0
	v_readfirstlane_b32 s100, v138
	v_readfirstlane_b32 s101, v139
	v_subrev_u32_e32 v250, s100, v138
	v_bfi_b32 v250, s97, v146, v250
	v_add_u32_e32 v164, s36, v250
	v_add_u32_e32 v168, s37, v250
	v_add_u32_e32 v172, s38, v250
	v_add_u32_e32 v176, s39, v250
	s_add_u32 s100, s100, s8
	s_addc_u32 s101, s101, s9
	s_add_u32 s100, s100, 0x80
	s_addc_u32 s101, s101, 0
	v_readfirstlane_b32 s96, v146
	s_and_b32 s96, s96, 0xfc00
	s_cmp_lt_u32 s96, 0x1000
	s_cbranch_scc1 .Lg2_p7_np
	s_setprio 1

.Lg2_p7_tail:
	s_setprio 0
	s_nop 0
	v_mfma_f32_16x16x32_bf16 v[62:65], v[232:235], v[196:199], v[62:65]
	v_mfma_f32_16x16x32_bf16 v[58:61], v[236:239], v[196:199], v[58:61]
	v_mfma_f32_16x16x32_bf16 v[54:57], v[240:243], v[196:199], v[54:57]
	v_mfma_f32_16x16x32_bf16 v[50:53], v[244:247], v[196:199], v[50:53]
	v_mfma_f32_16x16x32_bf16 v[46:49], v[232:235], v[200:203], v[46:49]
	v_mfma_f32_16x16x32_bf16 v[42:45], v[236:239], v[200:203], v[42:45]
	v_mfma_f32_16x16x32_bf16 v[38:41], v[240:243], v[200:203], v[38:41]
	v_mfma_f32_16x16x32_bf16 v[34:37], v[244:247], v[200:203], v[34:37]
	v_mfma_f32_16x16x32_bf16 v[30:33], v[232:235], v[204:207], v[30:33]
	v_mfma_f32_16x16x32_bf16 v[26:29], v[236:239], v[204:207], v[26:29]
	v_mfma_f32_16x16x32_bf16 v[22:25], v[240:243], v[204:207], v[22:25]
	v_mfma_f32_16x16x32_bf16 v[18:21], v[244:247], v[204:207], v[18:21]
	v_mfma_f32_16x16x32_bf16 v[14:17], v[232:235], v[208:211], v[14:17]
	v_mfma_f32_16x16x32_bf16 v[10:13], v[236:239], v[208:211], v[10:13]
	v_mfma_f32_16x16x32_bf16 v[6:9], v[240:243], v[208:211], v[6:9]
	v_mfma_f32_16x16x32_bf16 v[2:5], v[244:247], v[208:211], v[2:5]
	ds_read_b128 v[136:139], v149 offset:32768
	ds_read_b128 v[140:143], v149 offset:34816
	ds_read_b128 v[152:155], v149 offset:36864
	ds_read_b128 v[156:159], v149 offset:38912
	ds_read_b128 v[160:163], v148 offset:32768
	ds_read_b128 v[164:167], v148 offset:34816
	ds_read_b128 v[168:171], v148 offset:36864
	ds_read_b128 v[172:175], v148 offset:38912
	s_setprio 1
	s_waitcnt lgkmcnt(3)
	v_mfma_f32_16x16x32_bf16 v[126:129], v[136:139], v[160:163], v[126:129]
	v_mfma_f32_16x16x32_bf16 v[122:125], v[140:143], v[160:163], v[122:125]
	v_mfma_f32_16x16x32_bf16 v[118:121], v[152:155], v[160:163], v[118:121]
	v_mfma_f32_16x16x32_bf16 v[114:117], v[156:159], v[160:163], v[114:117]
	s_waitcnt lgkmcnt(2)
	v_mfma_f32_16x16x32_bf16 v[110:113], v[136:139], v[164:167], v[110:113]
	v_mfma_f32_16x16x32_bf16 v[106:109], v[140:143], v[164:167], v[106:109]
	v_mfma_f32_16x16x32_bf16 v[102:105], v[152:155], v[164:167], v[102:105]
	v_mfma_f32_16x16x32_bf16 v[98:101], v[156:159], v[164:167], v[98:101]
	s_waitcnt lgkmcnt(1)
	v_mfma_f32_16x16x32_bf16 v[94:97], v[136:139], v[168:171], v[94:97]
	v_mfma_f32_16x16x32_bf16 v[90:93], v[140:143], v[168:171], v[90:93]
	v_mfma_f32_16x16x32_bf16 v[86:89], v[152:155], v[168:171], v[86:89]
	v_mfma_f32_16x16x32_bf16 v[82:85], v[156:159], v[168:171], v[82:85]
	s_waitcnt lgkmcnt(0)
	v_mfma_f32_16x16x32_bf16 v[78:81], v[136:139], v[172:175], v[78:81]
	v_mfma_f32_16x16x32_bf16 v[74:77], v[140:143], v[172:175], v[74:77]
	v_mfma_f32_16x16x32_bf16 v[70:73], v[152:155], v[172:175], v[70:73]
	v_mfma_f32_16x16x32_bf16 v[66:69], v[156:159], v[172:175], v[66:69]
	s_setprio 0
	ds_read_b128 v[160:163], v148 offset:40960
	ds_read_b128 v[164:167], v148 offset:43008
	ds_read_b128 v[168:171], v148 offset:45056
	ds_read_b128 v[172:175], v148 offset:47104
	s_setprio 1
	s_waitcnt lgkmcnt(3)
	v_mfma_f32_16x16x32_bf16 v[62:65], v[136:139], v[160:163], v[62:65]
	v_mfma_f32_16x16x32_bf16 v[58:61], v[140:143], v[160:163], v[58:61]
	v_mfma_f32_16x16x32_bf16 v[54:57], v[152:155], v[160:163], v[54:57]
	v_mfma_f32_16x16x32_bf16 v[50:53], v[156:159], v[160:163], v[50:53]
	s_waitcnt lgkmcnt(2)
	v_mfma_f32_16x16x32_bf16 v[46:49], v[136:139], v[164:167], v[46:49]
	v_mfma_f32_16x16x32_bf16 v[42:45], v[140:143], v[164:167], v[42:45]
	v_mfma_f32_16x16x32_bf16 v[38:41], v[152:155], v[164:167], v[38:41]
	v_mfma_f32_16x16x32_bf16 v[34:37], v[156:159], v[164:167], v[34:37]
	s_waitcnt lgkmcnt(1)
	v_mfma_f32_16x16x32_bf16 v[30:33], v[136:139], v[168:171], v[30:33]
	v_mfma_f32_16x16x32_bf16 v[26:29], v[140:143], v[168:171], v[26:29]
	v_mfma_f32_16x16x32_bf16 v[22:25], v[152:155], v[168:171], v[22:25]
	v_mfma_f32_16x16x32_bf16 v[18:21], v[156:159], v[168:171], v[18:21]
	s_waitcnt lgkmcnt(0)
	v_mfma_f32_16x16x32_bf16 v[14:17], v[136:139], v[172:175], v[14:17]
	v_mfma_f32_16x16x32_bf16 v[10:13], v[140:143], v[172:175], v[10:13]
	v_mfma_f32_16x16x32_bf16 v[6:9], v[152:155], v[172:175], v[6:9]
	v_mfma_f32_16x16x32_bf16 v[2:5], v[156:159], v[172:175], v[2:5]
	s_setprio 0
	ds_read_b128 v[136:139], v217 offset:32768
	ds_read_b128 v[140:143], v217 offset:34816
	ds_read_b128 v[152:155], v217 offset:36864
	ds_read_b128 v[156:159], v217 offset:38912
	ds_read_b128 v[160:163], v216 offset:32768
	ds_read_b128 v[164:167], v216 offset:34816
	ds_read_b128 v[168:171], v216 offset:36864
	ds_read_b128 v[172:175], v216 offset:38912
	s_setprio 1
	s_waitcnt lgkmcnt(3)
	v_mfma_f32_16x16x32_bf16 v[126:129], v[136:139], v[160:163], v[126:129]
	v_mfma_f32_16x16x32_bf16 v[122:125], v[140:143], v[160:163], v[122:125]
	v_mfma_f32_16x16x32_bf16 v[118:121], v[152:155], v[160:163], v[118:121]
	v_mfma_f32_16x16x32_bf16 v[114:117], v[156:159], v[160:163], v[114:117]
	s_waitcnt lgkmcnt(2)
	v_mfma_f32_16x16x32_bf16 v[110:113], v[136:139], v[164:167], v[110:113]
	v_mfma_f32_16x16x32_bf16 v[106:109], v[140:143], v[164:167], v[106:109]
	v_mfma_f32_16x16x32_bf16 v[102:105], v[152:155], v[164:167], v[102:105]
	v_mfma_f32_16x16x32_bf16 v[98:101], v[156:159], v[164:167], v[98:101]
	s_waitcnt lgkmcnt(1)
	v_mfma_f32_16x16x32_bf16 v[94:97], v[136:139], v[168:171], v[94:97]
	v_mfma_f32_16x16x32_bf16 v[90:93], v[140:143], v[168:171], v[90:93]
	v_mfma_f32_16x16x32_bf16 v[86:89], v[152:155], v[168:171], v[86:89]
	v_mfma_f32_16x16x32_bf16 v[82:85], v[156:159], v[168:171], v[82:85]
	s_waitcnt lgkmcnt(0)
	v_mfma_f32_16x16x32_bf16 v[78:81], v[136:139], v[172:175], v[78:81]
	v_mfma_f32_16x16x32_bf16 v[74:77], v[140:143], v[172:175], v[74:77]
	v_mfma_f32_16x16x32_bf16 v[70:73], v[152:155], v[172:175], v[70:73]
	v_mfma_f32_16x16x32_bf16 v[66:69], v[156:159], v[172:175], v[66:69]
	s_setprio 0
	ds_read_b128 v[160:163], v216 offset:40960
	ds_read_b128 v[164:167], v216 offset:43008
	ds_read_b128 v[168:171], v216 offset:45056
	ds_read_b128 v[172:175], v216 offset:47104
	s_setprio 1
	s_waitcnt lgkmcnt(3)
	v_mfma_f32_16x16x32_bf16 v[62:65], v[136:139], v[160:163], v[62:65]
	v_mfma_f32_16x16x32_bf16 v[58:61], v[140:143], v[160:163], v[58:61]
	v_mfma_f32_16x16x32_bf16 v[54:57], v[152:155], v[160:163], v[54:57]
	v_mfma_f32_16x16x32_bf16 v[50:53], v[156:159], v[160:163], v[50:53]
	s_waitcnt lgkmcnt(2)
	v_mfma_f32_16x16x32_bf16 v[46:49], v[136:139], v[164:167], v[46:49]
	v_mfma_f32_16x16x32_bf16 v[42:45], v[140:143], v[164:167], v[42:45]
	v_mfma_f32_16x16x32_bf16 v[38:41], v[152:155], v[164:167], v[38:41]
	v_mfma_f32_16x16x32_bf16 v[34:37], v[156:159], v[164:167], v[34:37]
	s_waitcnt lgkmcnt(1)
	v_mfma_f32_16x16x32_bf16 v[30:33], v[136:139], v[168:171], v[30:33]
	v_mfma_f32_16x16x32_bf16 v[26:29], v[140:143], v[168:171], v[26:29]
	v_mfma_f32_16x16x32_bf16 v[22:25], v[152:155], v[168:171], v[22:25]
	v_mfma_f32_16x16x32_bf16 v[18:21], v[156:159], v[168:171], v[18:21]
	s_waitcnt lgkmcnt(0)
	v_mfma_f32_16x16x32_bf16 v[14:17], v[136:139], v[172:175], v[14:17]
	v_mfma_f32_16x16x32_bf16 v[10:13], v[140:143], v[172:175], v[10:13]
	v_mfma_f32_16x16x32_bf16 v[6:9], v[152:155], v[172:175], v[6:9]
	v_mfma_f32_16x16x32_bf16 v[2:5], v[156:159], v[172:175], v[2:5]
	s_setprio 0
	v_add_u32_e32 v152, s47, v150
	v_mul_hi_i32 v136, v152, s40
	v_lshrrev_b32_e32 v137, 31, v136
	v_ashrrev_i32_e32 v136, 11, v136
	v_add_u32_e32 v137, v136, v137
	v_mad_i32_i24 v142, v137, s41, v152
	v_lshlrev_b32_e32 v139, 13, v137
	v_cmp_lt_i32_e32 vcc, s42, v142
	v_add3_u32 v138, v139, v142, s43
	s_barrier
	s_and_saveexec_b64 s[8:9], vcc
	s_xor_b64 s[8:9], exec, s[8:9]
	v_add3_u32 v136, v139, v142, s43
	s_or_saveexec_b64 s[8:9], s[8:9]
	v_mov_b64_e32 v[140:141], s[84:85]
	v_lshl_add_u32 v139, v137, 8, v142
	s_xor_b64 exec, exec, s[8:9]
	v_lshl_add_u32 v136, v137, 8, v142
	v_mov_b64_e32 v[140:141], s[4:5]
	s_or_b64 exec, exec, s[8:9]
	s_and_saveexec_b64 s[8:9], vcc
	s_xor_b64 s[8:9], exec, s[8:9]
	s_cbranch_execz .LBB0_386
	v_mul_hi_i32_i24_e32 v143, 0x6000, v137
	v_mul_i32_i24_e32 v142, 0x6000, v137
	s_or_saveexec_b64 s[8:9], s[8:9]
	v_mov_b64_e32 v[144:145], s[84:85]
	s_xor_b64 exec, exec, s[8:9]
	s_cbranch_execnz .LBB0_387
	s_branch .LBB0_388

.LBB0_645:
	s_lshl_b32 s36, s28, 8
	v_or_b32_e32 v2, s36, v1
	v_ashrrev_i32_e32 v3, 31, v2
	v_lshlrev_b64 v[62:63], 11, v[2:3]
	v_lshl_add_u64 v[2:3], v[130:131], 0, v[62:63]
	v_add_co_u32_e32 v6, vcc, 0x20000, v2
	s_lshl_b32 s29, s27, 8
	s_nop 0
	v_addc_co_u32_e32 v7, vcc, 0, v3, vcc
	v_or_b32_e32 v4, s29, v1
	global_load_dwordx4 v[30:33], v[2:3], off
	global_load_dwordx4 v[34:37], v[6:7], off
	v_add_co_u32_e32 v6, vcc, 0x40000, v2
	v_ashrrev_i32_e32 v5, 31, v4
	s_nop 0
	v_addc_co_u32_e32 v7, vcc, 0, v3, vcc
	v_lshlrev_b64 v[64:65], 11, v[4:5]
	v_add_co_u32_e32 v2, vcc, 0x60000, v2
	v_lshl_add_u64 v[4:5], v[132:133], 0, v[64:65]
	s_nop 0
	v_addc_co_u32_e32 v3, vcc, 0, v3, vcc
	global_load_dwordx4 v[38:41], v[6:7], off
	global_load_dwordx4 v[42:45], v[2:3], off
	v_add_co_u32_e32 v2, vcc, s12, v4
	s_waitcnt vmcnt(63) expcnt(7) lgkmcnt(15)
	s_nop 0
	v_addc_co_u32_e32 v3, vcc, 0, v5, vcc
	s_barrier
	global_load_dwordx4 v[46:49], v[4:5], off
	global_load_dwordx4 v[50:53], v[2:3], off
	v_add_co_u32_e32 v2, vcc, s13, v4
	s_mov_b32 s37, 0
	s_nop 0
	v_addc_co_u32_e32 v3, vcc, 0, v5, vcc
	v_add_co_u32_e32 v4, vcc, s14, v4
	s_mov_b64 s[8:9], 0
	s_nop 0
	v_addc_co_u32_e32 v5, vcc, 0, v5, vcc
	global_load_dwordx4 v[54:57], v[2:3], off
	global_load_dwordx4 v[58:61], v[4:5], off
	v_mov_b32_e32 v2, 0
	v_mov_b32_e32 v3, v2
	v_mov_b32_e32 v4, v2
	v_mov_b32_e32 v5, v2
	v_mov_b32_e32 v6, v2
	v_mov_b32_e32 v7, v2
	v_mov_b32_e32 v8, v2
	v_mov_b32_e32 v9, v2
	v_mov_b32_e32 v10, v2
	v_mov_b32_e32 v11, v2
	v_mov_b32_e32 v12, v2
	v_mov_b32_e32 v13, v2
	v_mov_b32_e32 v14, v2
	v_mov_b32_e32 v15, v2
	v_mov_b32_e32 v16, v2
	v_mov_b32_e32 v17, v2
	v_mov_b32_e32 v18, v2
	v_mov_b32_e32 v19, v2
	v_mov_b32_e32 v20, v2
	v_mov_b32_e32 v21, v2
	v_mov_b32_e32 v22, v2
	v_mov_b32_e32 v23, v2
	v_mov_b32_e32 v24, v2
	v_mov_b32_e32 v25, v2
	v_mov_b32_e32 v26, v2
	v_mov_b32_e32 v27, v2
	v_mov_b32_e32 v28, v2
	v_lshl_add_u64 v[136:137], v[134:135], 0, v[62:63]
	v_lshl_add_u64 v[138:139], v[134:135], 0, v[64:65]
	v_mov_b32_e32 v29, v2
	v_mov_b32_e32 v62, v2
	v_mov_b32_e32 v63, v2
	v_mov_b32_e32 v64, v2
	v_mov_b32_e32 v65, v2
	v_mov_b32_e32 v66, v2
	v_mov_b32_e32 v67, v2
	v_mov_b32_e32 v68, v2
	v_mov_b32_e32 v69, v2
	v_mov_b32_e32 v70, v2
	v_mov_b32_e32 v71, v2
	v_mov_b32_e32 v72, v2
	v_mov_b32_e32 v73, v2
	v_mov_b32_e32 v74, v2
	v_mov_b32_e32 v75, v2
	v_mov_b32_e32 v76, v2
	v_mov_b32_e32 v77, v2
	v_mov_b32_e32 v78, v2
	v_mov_b32_e32 v79, v2
	v_mov_b32_e32 v80, v2
	v_mov_b32_e32 v81, v2
	v_mov_b32_e32 v82, v2
	v_mov_b32_e32 v83, v2
	v_mov_b32_e32 v84, v2
	s_waitcnt vmcnt(7)
	ds_write_b128 v146, v[30:33]
	s_waitcnt vmcnt(6)
	ds_write_b128 v146, v[34:37] offset:8192
	s_waitcnt vmcnt(5)
	ds_write_b128 v146, v[38:41] offset:16384
	s_waitcnt vmcnt(4)
	ds_write_b128 v146, v[42:45] offset:24576
	s_waitcnt vmcnt(3)
	ds_write_b128 v147, v[46:49]
	s_waitcnt vmcnt(2)
	ds_write_b128 v147, v[50:53] offset:8192
	s_waitcnt vmcnt(1)
	ds_write_b128 v147, v[54:57] offset:16384
	s_waitcnt vmcnt(0)
	ds_write_b128 v147, v[58:61] offset:24576
	v_mov_b32_e32 v30, v2
	v_mov_b32_e32 v31, v2
	v_mov_b32_e32 v32, v2
	v_mov_b32_e32 v33, v2
	v_mov_b32_e32 v34, v2
	v_mov_b32_e32 v35, v2
	v_mov_b32_e32 v36, v2
	v_mov_b32_e32 v37, v2
	v_mov_b32_e32 v38, v2
	v_mov_b32_e32 v39, v2
	v_mov_b32_e32 v40, v2
	v_mov_b32_e32 v41, v2
	v_mov_b32_e32 v42, v2
	v_mov_b32_e32 v43, v2
	v_mov_b32_e32 v44, v2
	v_mov_b32_e32 v45, v2
	v_mov_b32_e32 v46, v2
	v_mov_b32_e32 v47, v2
	v_mov_b32_e32 v48, v2
	v_mov_b32_e32 v49, v2
	v_mov_b32_e32 v50, v2
	v_mov_b32_e32 v51, v2
	v_mov_b32_e32 v52, v2
	v_mov_b32_e32 v53, v2
	v_mov_b32_e32 v54, v2
	v_mov_b32_e32 v55, v2
	v_mov_b32_e32 v56, v2
	v_mov_b32_e32 v57, v2
	v_mov_b32_e32 v58, v2
	v_mov_b32_e32 v59, v2
	v_mov_b32_e32 v60, v2
	v_mov_b32_e32 v61, v2
	v_mov_b32_e32 v85, v2
	v_mov_b32_e32 v86, v2
	v_mov_b32_e32 v87, v2
	v_mov_b32_e32 v88, v2
	v_mov_b32_e32 v89, v2
	v_mov_b32_e32 v90, v2
	v_mov_b32_e32 v91, v2
	v_mov_b32_e32 v92, v2
	v_mov_b32_e32 v93, v2
	v_mov_b32_e32 v94, v2
	v_mov_b32_e32 v95, v2
	v_mov_b32_e32 v96, v2
	v_mov_b32_e32 v97, v2
	v_mov_b32_e32 v98, v2
	v_mov_b32_e32 v99, v2
	v_mov_b32_e32 v100, v2
	v_mov_b32_e32 v101, v2
	v_mov_b32_e32 v102, v2
	v_mov_b32_e32 v103, v2
	v_mov_b32_e32 v104, v2
	v_mov_b32_e32 v105, v2
	v_mov_b32_e32 v106, v2
	v_mov_b32_e32 v107, v2
	v_mov_b32_e32 v108, v2
	v_mov_b32_e32 v109, v2
	v_mov_b32_e32 v110, v2
	v_mov_b32_e32 v111, v2
	v_mov_b32_e32 v112, v2
	v_mov_b32_e32 v113, v2
	v_mov_b32_e32 v114, v2
	v_mov_b32_e32 v115, v2
	v_mov_b32_e32 v116, v2
	v_mov_b32_e32 v117, v2
	v_mov_b32_e32 v118, v2
	v_mov_b32_e32 v119, v2
	v_mov_b32_e32 v120, v2
	v_mov_b32_e32 v121, v2
	v_mov_b32_e32 v122, v2
	v_mov_b32_e32 v123, v2
	v_mov_b32_e32 v124, v2
	v_mov_b32_e32 v125, v2
	v_mov_b32_e32 v126, v2
	v_mov_b32_e32 v127, v2
	v_mov_b32_e32 v128, v2
	v_mov_b32_e32 v129, v2
	s_waitcnt lgkmcnt(0)
	s_barrier
	s_movk_i32 s97, 0x70
	v_readfirstlane_b32 s98, v136
	v_readfirstlane_b32 s99, v137
	v_subrev_u32_e32 v248, s98, v136
	v_bfi_b32 v248, s97, v146, v248
	v_add_u32_e32 v140, s15, v248
	v_add_u32_e32 v152, s16, v248
	v_add_u32_e32 v156, s17, v248
	v_add_u32_e32 v160, s18, v248
	s_add_u32 s98, s98, s8
	s_addc_u32 s99, s99, s9
	s_add_u32 s98, s98, 0x80
	s_addc_u32 s99, s99, 0
	v_readfirstlane_b32 s100, v138
	v_readfirstlane_b32 s101, v139
	v_subrev_u32_e32 v250, s100, v138
	v_bfi_b32 v250, s97, v146, v250
	v_add_u32_e32 v164, s19, v250
	v_add_u32_e32 v168, s20, v250
	v_add_u32_e32 v172, s21, v250
	v_add_u32_e32 v176, s22, v250
	s_add_u32 s100, s100, s8
	s_addc_u32 s101, s101, s9
	s_add_u32 s100, s100, 0x80
	s_addc_u32 s101, s101, 0
	v_readfirstlane_b32 s96, v146
	s_and_b32 s96, s96, 0xfc00
	s_cmp_lt_u32 s96, 0x1000
	s_cbranch_scc1 .Lg2_p12_np
	s_setprio 1

.Lg2_p12_tail:
	s_setprio 0
	s_nop 0
	v_mfma_f32_16x16x32_bf16 v[62:65], v[232:235], v[196:199], v[62:65]
	v_mfma_f32_16x16x32_bf16 v[58:61], v[236:239], v[196:199], v[58:61]
	v_mfma_f32_16x16x32_bf16 v[54:57], v[240:243], v[196:199], v[54:57]
	v_mfma_f32_16x16x32_bf16 v[50:53], v[244:247], v[196:199], v[50:53]
	v_mfma_f32_16x16x32_bf16 v[46:49], v[232:235], v[200:203], v[46:49]
	v_mfma_f32_16x16x32_bf16 v[42:45], v[236:239], v[200:203], v[42:45]
	v_mfma_f32_16x16x32_bf16 v[38:41], v[240:243], v[200:203], v[38:41]
	v_mfma_f32_16x16x32_bf16 v[34:37], v[244:247], v[200:203], v[34:37]
	v_mfma_f32_16x16x32_bf16 v[30:33], v[232:235], v[204:207], v[30:33]
	v_mfma_f32_16x16x32_bf16 v[26:29], v[236:239], v[204:207], v[26:29]
	v_mfma_f32_16x16x32_bf16 v[22:25], v[240:243], v[204:207], v[22:25]
	v_mfma_f32_16x16x32_bf16 v[18:21], v[244:247], v[204:207], v[18:21]
	v_mfma_f32_16x16x32_bf16 v[14:17], v[232:235], v[208:211], v[14:17]
	v_mfma_f32_16x16x32_bf16 v[10:13], v[236:239], v[208:211], v[10:13]
	v_mfma_f32_16x16x32_bf16 v[6:9], v[240:243], v[208:211], v[6:9]
	v_mfma_f32_16x16x32_bf16 v[2:5], v[244:247], v[208:211], v[2:5]
	ds_read_b128 v[136:139], v149 offset:32768
	ds_read_b128 v[140:143], v149 offset:34816
	ds_read_b128 v[152:155], v149 offset:36864
	ds_read_b128 v[156:159], v149 offset:38912
	ds_read_b128 v[160:163], v148 offset:32768
	ds_read_b128 v[164:167], v148 offset:34816
	ds_read_b128 v[168:171], v148 offset:36864
	ds_read_b128 v[172:175], v148 offset:38912
	s_setprio 1
	s_waitcnt lgkmcnt(3)
	v_mfma_f32_16x16x32_bf16 v[126:129], v[136:139], v[160:163], v[126:129]
	v_mfma_f32_16x16x32_bf16 v[122:125], v[140:143], v[160:163], v[122:125]
	v_mfma_f32_16x16x32_bf16 v[118:121], v[152:155], v[160:163], v[118:121]
	v_mfma_f32_16x16x32_bf16 v[114:117], v[156:159], v[160:163], v[114:117]
	s_waitcnt lgkmcnt(2)
	v_mfma_f32_16x16x32_bf16 v[110:113], v[136:139], v[164:167], v[110:113]
	v_mfma_f32_16x16x32_bf16 v[106:109], v[140:143], v[164:167], v[106:109]
	v_mfma_f32_16x16x32_bf16 v[102:105], v[152:155], v[164:167], v[102:105]
	v_mfma_f32_16x16x32_bf16 v[98:101], v[156:159], v[164:167], v[98:101]
	s_waitcnt lgkmcnt(1)
	v_mfma_f32_16x16x32_bf16 v[94:97], v[136:139], v[168:171], v[94:97]
	v_mfma_f32_16x16x32_bf16 v[90:93], v[140:143], v[168:171], v[90:93]
	v_mfma_f32_16x16x32_bf16 v[86:89], v[152:155], v[168:171], v[86:89]
	v_mfma_f32_16x16x32_bf16 v[82:85], v[156:159], v[168:171], v[82:85]
	s_waitcnt lgkmcnt(0)
	v_mfma_f32_16x16x32_bf16 v[78:81], v[136:139], v[172:175], v[78:81]
	v_mfma_f32_16x16x32_bf16 v[74:77], v[140:143], v[172:175], v[74:77]
	v_mfma_f32_16x16x32_bf16 v[70:73], v[152:155], v[172:175], v[70:73]
	v_mfma_f32_16x16x32_bf16 v[66:69], v[156:159], v[172:175], v[66:69]
	s_setprio 0
	ds_read_b128 v[160:163], v148 offset:40960
	ds_read_b128 v[164:167], v148 offset:43008
	ds_read_b128 v[168:171], v148 offset:45056
	ds_read_b128 v[172:175], v148 offset:47104
	s_setprio 1
	s_waitcnt lgkmcnt(3)
	v_mfma_f32_16x16x32_bf16 v[62:65], v[136:139], v[160:163], v[62:65]
	v_mfma_f32_16x16x32_bf16 v[58:61], v[140:143], v[160:163], v[58:61]
	v_mfma_f32_16x16x32_bf16 v[54:57], v[152:155], v[160:163], v[54:57]
	v_mfma_f32_16x16x32_bf16 v[50:53], v[156:159], v[160:163], v[50:53]
	s_waitcnt lgkmcnt(2)
	v_mfma_f32_16x16x32_bf16 v[46:49], v[136:139], v[164:167], v[46:49]
	v_mfma_f32_16x16x32_bf16 v[42:45], v[140:143], v[164:167], v[42:45]
	v_mfma_f32_16x16x32_bf16 v[38:41], v[152:155], v[164:167], v[38:41]
	v_mfma_f32_16x16x32_bf16 v[34:37], v[156:159], v[164:167], v[34:37]
	s_waitcnt lgkmcnt(1)
	v_mfma_f32_16x16x32_bf16 v[30:33], v[136:139], v[168:171], v[30:33]
	v_mfma_f32_16x16x32_bf16 v[26:29], v[140:143], v[168:171], v[26:29]
	v_mfma_f32_16x16x32_bf16 v[22:25], v[152:155], v[168:171], v[22:25]
	v_mfma_f32_16x16x32_bf16 v[18:21], v[156:159], v[168:171], v[18:21]
	s_waitcnt lgkmcnt(0)
	v_mfma_f32_16x16x32_bf16 v[14:17], v[136:139], v[172:175], v[14:17]
	v_mfma_f32_16x16x32_bf16 v[10:13], v[140:143], v[172:175], v[10:13]
	v_mfma_f32_16x16x32_bf16 v[6:9], v[152:155], v[172:175], v[6:9]
	v_mfma_f32_16x16x32_bf16 v[2:5], v[156:159], v[172:175], v[2:5]
	s_setprio 0
	ds_read_b128 v[136:139], v217 offset:32768
	ds_read_b128 v[140:143], v217 offset:34816
	ds_read_b128 v[152:155], v217 offset:36864
	ds_read_b128 v[156:159], v217 offset:38912
	ds_read_b128 v[160:163], v216 offset:32768
	ds_read_b128 v[164:167], v216 offset:34816
	ds_read_b128 v[168:171], v216 offset:36864
	ds_read_b128 v[172:175], v216 offset:38912
	s_setprio 1
	s_waitcnt lgkmcnt(3)
	v_mfma_f32_16x16x32_bf16 v[126:129], v[136:139], v[160:163], v[126:129]
	v_mfma_f32_16x16x32_bf16 v[122:125], v[140:143], v[160:163], v[122:125]
	v_mfma_f32_16x16x32_bf16 v[118:121], v[152:155], v[160:163], v[118:121]
	v_mfma_f32_16x16x32_bf16 v[114:117], v[156:159], v[160:163], v[114:117]
	s_waitcnt lgkmcnt(2)
	v_mfma_f32_16x16x32_bf16 v[110:113], v[136:139], v[164:167], v[110:113]
	v_mfma_f32_16x16x32_bf16 v[106:109], v[140:143], v[164:167], v[106:109]
	v_mfma_f32_16x16x32_bf16 v[102:105], v[152:155], v[164:167], v[102:105]
	v_mfma_f32_16x16x32_bf16 v[98:101], v[156:159], v[164:167], v[98:101]
	s_waitcnt lgkmcnt(1)
	v_mfma_f32_16x16x32_bf16 v[94:97], v[136:139], v[168:171], v[94:97]
	v_mfma_f32_16x16x32_bf16 v[90:93], v[140:143], v[168:171], v[90:93]
	v_mfma_f32_16x16x32_bf16 v[86:89], v[152:155], v[168:171], v[86:89]
	v_mfma_f32_16x16x32_bf16 v[82:85], v[156:159], v[168:171], v[82:85]
	s_waitcnt lgkmcnt(0)
	v_mfma_f32_16x16x32_bf16 v[78:81], v[136:139], v[172:175], v[78:81]
	v_mfma_f32_16x16x32_bf16 v[74:77], v[140:143], v[172:175], v[74:77]
	v_mfma_f32_16x16x32_bf16 v[70:73], v[152:155], v[172:175], v[70:73]
	v_mfma_f32_16x16x32_bf16 v[66:69], v[156:159], v[172:175], v[66:69]
	s_setprio 0
	ds_read_b128 v[160:163], v216 offset:40960
	ds_read_b128 v[164:167], v216 offset:43008
	ds_read_b128 v[168:171], v216 offset:45056
	ds_read_b128 v[172:175], v216 offset:47104
	s_setprio 1
	s_waitcnt lgkmcnt(3)
	v_mfma_f32_16x16x32_bf16 v[62:65], v[136:139], v[160:163], v[62:65]
	v_mfma_f32_16x16x32_bf16 v[58:61], v[140:143], v[160:163], v[58:61]
	v_mfma_f32_16x16x32_bf16 v[54:57], v[152:155], v[160:163], v[54:57]
	v_mfma_f32_16x16x32_bf16 v[50:53], v[156:159], v[160:163], v[50:53]
	s_waitcnt lgkmcnt(2)
	v_mfma_f32_16x16x32_bf16 v[46:49], v[136:139], v[164:167], v[46:49]
	v_mfma_f32_16x16x32_bf16 v[42:45], v[140:143], v[164:167], v[42:45]
	v_mfma_f32_16x16x32_bf16 v[38:41], v[152:155], v[164:167], v[38:41]
	v_mfma_f32_16x16x32_bf16 v[34:37], v[156:159], v[164:167], v[34:37]
	s_waitcnt lgkmcnt(1)
	v_mfma_f32_16x16x32_bf16 v[30:33], v[136:139], v[168:171], v[30:33]
	v_mfma_f32_16x16x32_bf16 v[26:29], v[140:143], v[168:171], v[26:29]
	v_mfma_f32_16x16x32_bf16 v[22:25], v[152:155], v[168:171], v[22:25]
	v_mfma_f32_16x16x32_bf16 v[18:21], v[156:159], v[168:171], v[18:21]
	s_waitcnt lgkmcnt(0)
	v_mfma_f32_16x16x32_bf16 v[14:17], v[136:139], v[172:175], v[14:17]
	v_mfma_f32_16x16x32_bf16 v[10:13], v[140:143], v[172:175], v[10:13]
	v_mfma_f32_16x16x32_bf16 v[6:9], v[152:155], v[172:175], v[6:9]
	v_mfma_f32_16x16x32_bf16 v[2:5], v[156:159], v[172:175], v[2:5]
	s_setprio 0
	v_add_u32_e32 v152, s36, v150
	v_mul_hi_i32 v136, v152, s23
	v_lshrrev_b32_e32 v137, 31, v136
	v_ashrrev_i32_e32 v136, 11, v136
	v_add_u32_e32 v137, v136, v137
	v_mad_i32_i24 v142, v137, s24, v152
	v_lshlrev_b32_e32 v139, 13, v137
	v_cmp_lt_i32_e32 vcc, s25, v142
	v_add3_u32 v138, v139, v142, s26
	s_barrier
	s_and_saveexec_b64 s[8:9], vcc
	s_xor_b64 s[8:9], exec, s[8:9]
	v_add3_u32 v136, v139, v142, s26
	s_or_saveexec_b64 s[8:9], s[8:9]
	v_mov_b64_e32 v[140:141], s[84:85]
	v_lshl_add_u32 v139, v137, 8, v142
	s_xor_b64 exec, exec, s[8:9]
	v_lshl_add_u32 v136, v137, 8, v142
	v_mov_b64_e32 v[140:141], s[0:1]
	s_or_b64 exec, exec, s[8:9]
	s_and_saveexec_b64 s[8:9], vcc
	s_xor_b64 s[8:9], exec, s[8:9]
	s_cbranch_execz .LBB0_653
	v_mul_hi_i32_i24_e32 v143, 0x6000, v137
	v_mul_i32_i24_e32 v142, 0x6000, v137
	s_or_saveexec_b64 s[8:9], s[8:9]
	v_mov_b64_e32 v[144:145], s[84:85]
	s_xor_b64 exec, exec, s[8:9]
	s_cbranch_execnz .LBB0_654
	s_branch .LBB0_655

.LBB0_749:
	s_mul_hi_i32 s0, s3, 0x2e8ba2e9
	s_lshr_b32 s1, s0, 31
	s_ashr_i32 s0, s0, 4
	s_add_i32 s24, s0, s1
	s_mul_i32 s1, s24, 0xffffffa8
	s_add_i32 s1, s1, s3
	s_ashr_i32 s21, s1, 31
	s_lshl_b32 s0, s24, 2
	s_lshr_b32 s21, s21, 30
	s_add_i32 s21, s1, s21
	s_add_i32 s0, s6, s0
	s_ashr_i32 s22, s21, 2
	s_add_i32 s0, s0, s1
	s_lshl_b32 s25, s22, 10
	s_lshl_b32 s0, s0, 8
	s_sub_i32 s21, s0, s25
	v_or_b32_e32 v2, s21, v1
	v_ashrrev_i32_e32 v3, 31, v2
	v_lshlrev_b64 v[2:3], 11, v[2:3]
	v_lshl_add_u64 v[2:3], v[132:133], 0, v[2:3]
	v_add_co_u32_e32 v6, vcc, s9, v2
	s_lshl_b32 s22, s22, 8
	s_nop 0
	v_addc_co_u32_e32 v7, vcc, 0, v3, vcc
	v_or_b32_e32 v4, s22, v1
	global_load_dwordx4 v[20:23], v[2:3], off
	global_load_dwordx4 v[24:27], v[6:7], off
	v_add_co_u32_e32 v6, vcc, s10, v2
	v_ashrrev_i32_e32 v5, 31, v4
	s_nop 0
	v_addc_co_u32_e32 v7, vcc, 0, v3, vcc
	v_lshlrev_b64 v[52:53], 11, v[4:5]
	v_add_co_u32_e32 v2, vcc, s11, v2
	v_lshl_add_u64 v[4:5], v[134:135], 0, v[52:53]
	s_nop 0
	v_addc_co_u32_e32 v3, vcc, 0, v3, vcc
	global_load_dwordx4 v[28:31], v[6:7], off
	global_load_dwordx4 v[32:35], v[2:3], off
	v_add_co_u32_e32 v2, vcc, s9, v4
	s_waitcnt vmcnt(63) expcnt(7) lgkmcnt(15)
	s_nop 0
	v_addc_co_u32_e32 v3, vcc, 0, v5, vcc
	s_barrier
	global_load_dwordx4 v[36:39], v[4:5], off
	global_load_dwordx4 v[40:43], v[2:3], off
	v_add_co_u32_e32 v2, vcc, s10, v4
	s_mulk_i32 s24, 0x5400
	s_nop 0
	v_addc_co_u32_e32 v3, vcc, 0, v5, vcc
	v_add_co_u32_e32 v4, vcc, s11, v4
	v_subrev_u32_e32 v19, s25, v130
	s_nop 0
	v_addc_co_u32_e32 v5, vcc, 0, v5, vcc
	global_load_dwordx4 v[44:47], v[2:3], off
	global_load_dwordx4 v[48:51], v[4:5], off
	v_subrev_u32_e32 v54, s24, v19
	v_ashrrev_i32_e32 v55, 31, v54
	v_lshlrev_b64 v[54:55], 11, v[54:55]
	s_mov_b64 s[0:1], 0
	s_mov_b32 s23, 0
	v_mov_b32_e32 v2, 0
	v_mov_b32_e32 v3, v131
	v_mov_b32_e32 v4, v131
	v_mov_b32_e32 v5, v131
	v_mov_b32_e32 v6, 0
	v_mov_b32_e32 v7, v131
	v_mov_b32_e32 v8, v131
	v_mov_b32_e32 v9, v131
	v_mov_b32_e32 v10, 0
	v_mov_b32_e32 v11, v131
	v_mov_b32_e32 v12, v131
	v_mov_b32_e32 v13, v131
	v_mov_b32_e32 v14, 0
	v_mov_b32_e32 v15, v131
	v_mov_b32_e32 v16, v131
	v_mov_b32_e32 v17, v131
	v_mov_b32_e32 v18, 0
	v_lshl_add_u64 v[140:141], v[138:139], 0, v[52:53]
	v_lshl_add_u64 v[142:143], v[138:139], 0, v[54:55]
	v_mov_b32_e32 v19, v131
	v_mov_b32_e32 v52, v131
	v_mov_b32_e32 v53, v131
	v_mov_b32_e32 v54, 0
	v_mov_b32_e32 v55, v131
	v_mov_b32_e32 v56, v131
	v_mov_b32_e32 v57, v131
	v_mov_b32_e32 v58, 0
	v_mov_b32_e32 v59, v131
	v_mov_b32_e32 v60, v131
	v_mov_b32_e32 v61, v131
	v_mov_b32_e32 v62, 0
	v_mov_b32_e32 v63, v131
	v_mov_b32_e32 v64, v131
	v_mov_b32_e32 v65, v131
	v_mov_b32_e32 v66, 0
	v_mov_b32_e32 v67, v131
	v_mov_b32_e32 v68, v131
	v_mov_b32_e32 v69, v131
	v_mov_b32_e32 v70, 0
	v_mov_b32_e32 v71, v131
	v_mov_b32_e32 v72, v131
	v_mov_b32_e32 v73, v131
	v_mov_b32_e32 v74, 0
	s_waitcnt vmcnt(7)
	ds_write_b128 v144, v[20:23]
	s_waitcnt vmcnt(6)
	ds_write_b128 v144, v[24:27] offset:8192
	s_waitcnt vmcnt(5)
	ds_write_b128 v144, v[28:31] offset:16384
	s_waitcnt vmcnt(4)
	ds_write_b128 v144, v[32:35] offset:24576
	s_waitcnt vmcnt(3)
	ds_write_b128 v145, v[36:39]
	s_waitcnt vmcnt(2)
	ds_write_b128 v145, v[40:43] offset:8192
	s_waitcnt vmcnt(1)
	ds_write_b128 v145, v[44:47] offset:16384
	s_waitcnt vmcnt(0)
	ds_write_b128 v145, v[48:51] offset:24576
	v_mov_b32_e32 v20, v131
	v_mov_b32_e32 v21, v131
	v_mov_b32_e32 v22, 0
	v_mov_b32_e32 v23, v131
	v_mov_b32_e32 v24, v131
	v_mov_b32_e32 v25, v131
	v_mov_b32_e32 v26, 0
	v_mov_b32_e32 v27, v131
	v_mov_b32_e32 v28, v131
	v_mov_b32_e32 v29, v131
	v_mov_b32_e32 v30, 0
	v_mov_b32_e32 v31, v131
	v_mov_b32_e32 v32, v131
	v_mov_b32_e32 v33, v131
	v_mov_b32_e32 v34, 0
	v_mov_b32_e32 v35, v131
	v_mov_b32_e32 v36, v131
	v_mov_b32_e32 v37, v131
	v_mov_b32_e32 v38, 0
	v_mov_b32_e32 v39, v131
	v_mov_b32_e32 v40, v131
	v_mov_b32_e32 v41, v131
	v_mov_b32_e32 v42, 0
	v_mov_b32_e32 v43, v131
	v_mov_b32_e32 v44, v131
	v_mov_b32_e32 v45, v131
	v_mov_b32_e32 v46, 0
	v_mov_b32_e32 v47, v131
	v_mov_b32_e32 v48, v131
	v_mov_b32_e32 v49, v131
	v_mov_b32_e32 v50, 0
	v_mov_b32_e32 v51, v131
	v_mov_b32_e32 v75, v131
	v_mov_b32_e32 v76, v131
	v_mov_b32_e32 v77, v131
	v_mov_b32_e32 v78, 0
	v_mov_b32_e32 v79, v131
	v_mov_b32_e32 v80, v131
	v_mov_b32_e32 v81, v131
	v_mov_b32_e32 v82, 0
	v_mov_b32_e32 v83, v131
	v_mov_b32_e32 v84, v131
	v_mov_b32_e32 v85, v131
	v_mov_b32_e32 v86, 0
	v_mov_b32_e32 v87, v131
	v_mov_b32_e32 v88, v131
	v_mov_b32_e32 v89, v131
	v_mov_b32_e32 v90, 0
	v_mov_b32_e32 v91, v131
	v_mov_b32_e32 v92, v131
	v_mov_b32_e32 v93, v131
	v_mov_b32_e32 v94, 0
	v_mov_b32_e32 v95, v131
	v_mov_b32_e32 v96, v131
	v_mov_b32_e32 v97, v131
	v_mov_b32_e32 v98, 0
	v_mov_b32_e32 v99, v131
	v_mov_b32_e32 v100, v131
	v_mov_b32_e32 v101, v131
	v_mov_b32_e32 v102, 0
	v_mov_b32_e32 v103, v131
	v_mov_b32_e32 v104, v131
	v_mov_b32_e32 v105, v131
	v_mov_b32_e32 v106, 0
	v_mov_b32_e32 v107, v131
	v_mov_b32_e32 v108, v131
	v_mov_b32_e32 v109, v131
	v_mov_b32_e32 v110, 0
	v_mov_b32_e32 v111, v131
	v_mov_b32_e32 v112, v131
	v_mov_b32_e32 v113, v131
	v_mov_b32_e32 v114, 0
	v_mov_b32_e32 v115, v131
	v_mov_b32_e32 v116, v131
	v_mov_b32_e32 v117, v131
	v_mov_b32_e32 v118, 0
	v_mov_b32_e32 v119, v131
	v_mov_b32_e32 v120, v131
	v_mov_b32_e32 v121, v131
	v_mov_b32_e32 v122, 0
	v_mov_b32_e32 v123, v131
	v_mov_b32_e32 v124, v131
	v_mov_b32_e32 v125, v131
	v_mov_b32_e32 v126, 0
	v_mov_b32_e32 v127, v131
	v_mov_b32_e32 v128, v131
	v_mov_b32_e32 v129, v131
	s_waitcnt lgkmcnt(0)
	s_barrier
	s_movk_i32 s97, 0x70
	v_readfirstlane_b32 s98, v142
	v_readfirstlane_b32 s99, v143
	v_subrev_u32_e32 v215, s98, v142
	v_bfi_b32 v215, s97, v144, v215
	v_add_u32_e32 v150, s12, v215
	v_add_u32_e32 v154, s13, v215
	v_add_u32_e32 v158, s14, v215
	v_add_u32_e32 v162, s15, v215
	s_add_u32 s98, s98, s0
	s_addc_u32 s99, s99, s1
	s_add_u32 s98, s98, 0x80
	s_addc_u32 s99, s99, 0
	v_readfirstlane_b32 s100, v140
	v_readfirstlane_b32 s101, v141
	v_subrev_u32_e32 v252, s100, v140
	v_bfi_b32 v252, s97, v144, v252
	v_add_u32_e32 v166, s16, v252
	v_add_u32_e32 v170, s17, v252
	v_add_u32_e32 v174, s18, v252
	v_add_u32_e32 v178, s19, v252
	s_add_u32 s100, s100, s0
	s_addc_u32 s101, s101, s1
	s_add_u32 s100, s100, 0x80
	s_addc_u32 s101, s101, 0
	v_readfirstlane_b32 s96, v144
	s_and_b32 s96, s96, 0xfc00
	s_cmp_lt_u32 s96, 0x1000
	s_cbranch_scc1 .Lg2_p14_np
	s_setprio 1

.Lg2_p14_tail:
	s_setprio 0
	s_nop 0
	v_mfma_f32_16x16x32_bf16 v[62:65], v[236:239], v[198:201], v[62:65]
	v_mfma_f32_16x16x32_bf16 v[58:61], v[240:243], v[198:201], v[58:61]
	v_mfma_f32_16x16x32_bf16 v[54:57], v[244:247], v[198:201], v[54:57]
	v_mfma_f32_16x16x32_bf16 v[50:53], v[248:251], v[198:201], v[50:53]
	v_mfma_f32_16x16x32_bf16 v[46:49], v[236:239], v[202:205], v[46:49]
	v_mfma_f32_16x16x32_bf16 v[42:45], v[240:243], v[202:205], v[42:45]
	v_mfma_f32_16x16x32_bf16 v[38:41], v[244:247], v[202:205], v[38:41]
	v_mfma_f32_16x16x32_bf16 v[34:37], v[248:251], v[202:205], v[34:37]
	v_mfma_f32_16x16x32_bf16 v[30:33], v[236:239], v[206:209], v[30:33]
	v_mfma_f32_16x16x32_bf16 v[26:29], v[240:243], v[206:209], v[26:29]
	v_mfma_f32_16x16x32_bf16 v[22:25], v[244:247], v[206:209], v[22:25]
	v_mfma_f32_16x16x32_bf16 v[18:21], v[248:251], v[206:209], v[18:21]
	v_mfma_f32_16x16x32_bf16 v[14:17], v[236:239], v[210:213], v[14:17]
	v_mfma_f32_16x16x32_bf16 v[10:13], v[240:243], v[210:213], v[10:13]
	v_mfma_f32_16x16x32_bf16 v[6:9], v[244:247], v[210:213], v[6:9]
	v_mfma_f32_16x16x32_bf16 v[2:5], v[248:251], v[210:213], v[2:5]
	ds_read_b128 v[140:143], v147 offset:32768
	ds_read_b128 v[150:153], v147 offset:34816
	ds_read_b128 v[154:157], v147 offset:36864
	ds_read_b128 v[158:161], v147 offset:38912
	ds_read_b128 v[162:165], v146 offset:32768
	ds_read_b128 v[166:169], v146 offset:34816
	ds_read_b128 v[170:173], v146 offset:36864
	ds_read_b128 v[174:177], v146 offset:38912
	s_setprio 1
	s_waitcnt lgkmcnt(3)
	v_mfma_f32_16x16x32_bf16 v[126:129], v[140:143], v[162:165], v[126:129]
	v_mfma_f32_16x16x32_bf16 v[122:125], v[150:153], v[162:165], v[122:125]
	v_mfma_f32_16x16x32_bf16 v[118:121], v[154:157], v[162:165], v[118:121]
	v_mfma_f32_16x16x32_bf16 v[114:117], v[158:161], v[162:165], v[114:117]
	s_waitcnt lgkmcnt(2)
	v_mfma_f32_16x16x32_bf16 v[110:113], v[140:143], v[166:169], v[110:113]
	v_mfma_f32_16x16x32_bf16 v[106:109], v[150:153], v[166:169], v[106:109]
	v_mfma_f32_16x16x32_bf16 v[102:105], v[154:157], v[166:169], v[102:105]
	v_mfma_f32_16x16x32_bf16 v[98:101], v[158:161], v[166:169], v[98:101]
	s_waitcnt lgkmcnt(1)
	v_mfma_f32_16x16x32_bf16 v[94:97], v[140:143], v[170:173], v[94:97]
	v_mfma_f32_16x16x32_bf16 v[90:93], v[150:153], v[170:173], v[90:93]
	v_mfma_f32_16x16x32_bf16 v[86:89], v[154:157], v[170:173], v[86:89]
	v_mfma_f32_16x16x32_bf16 v[82:85], v[158:161], v[170:173], v[82:85]
	s_waitcnt lgkmcnt(0)
	v_mfma_f32_16x16x32_bf16 v[78:81], v[140:143], v[174:177], v[78:81]
	v_mfma_f32_16x16x32_bf16 v[74:77], v[150:153], v[174:177], v[74:77]
	v_mfma_f32_16x16x32_bf16 v[70:73], v[154:157], v[174:177], v[70:73]
	v_mfma_f32_16x16x32_bf16 v[66:69], v[158:161], v[174:177], v[66:69]
	s_setprio 0
	ds_read_b128 v[162:165], v146 offset:40960
	ds_read_b128 v[166:169], v146 offset:43008
	ds_read_b128 v[170:173], v146 offset:45056
	ds_read_b128 v[174:177], v146 offset:47104
	s_setprio 1
	s_waitcnt lgkmcnt(3)
	v_mfma_f32_16x16x32_bf16 v[62:65], v[140:143], v[162:165], v[62:65]
	v_mfma_f32_16x16x32_bf16 v[58:61], v[150:153], v[162:165], v[58:61]
	v_mfma_f32_16x16x32_bf16 v[54:57], v[154:157], v[162:165], v[54:57]
	v_mfma_f32_16x16x32_bf16 v[50:53], v[158:161], v[162:165], v[50:53]
	s_waitcnt lgkmcnt(2)
	v_mfma_f32_16x16x32_bf16 v[46:49], v[140:143], v[166:169], v[46:49]
	v_mfma_f32_16x16x32_bf16 v[42:45], v[150:153], v[166:169], v[42:45]
	v_mfma_f32_16x16x32_bf16 v[38:41], v[154:157], v[166:169], v[38:41]
	v_mfma_f32_16x16x32_bf16 v[34:37], v[158:161], v[166:169], v[34:37]
	s_waitcnt lgkmcnt(1)
	v_mfma_f32_16x16x32_bf16 v[30:33], v[140:143], v[170:173], v[30:33]
	v_mfma_f32_16x16x32_bf16 v[26:29], v[150:153], v[170:173], v[26:29]
	v_mfma_f32_16x16x32_bf16 v[22:25], v[154:157], v[170:173], v[22:25]
	v_mfma_f32_16x16x32_bf16 v[18:21], v[158:161], v[170:173], v[18:21]
	s_waitcnt lgkmcnt(0)
	v_mfma_f32_16x16x32_bf16 v[14:17], v[140:143], v[174:177], v[14:17]
	v_mfma_f32_16x16x32_bf16 v[10:13], v[150:153], v[174:177], v[10:13]
	v_mfma_f32_16x16x32_bf16 v[6:9], v[154:157], v[174:177], v[6:9]
	v_mfma_f32_16x16x32_bf16 v[2:5], v[158:161], v[174:177], v[2:5]
	s_setprio 0
	ds_read_b128 v[140:143], v217 offset:32768
	ds_read_b128 v[150:153], v217 offset:34816
	ds_read_b128 v[154:157], v217 offset:36864
	ds_read_b128 v[158:161], v217 offset:38912
	ds_read_b128 v[162:165], v216 offset:32768
	ds_read_b128 v[166:169], v216 offset:34816
	ds_read_b128 v[170:173], v216 offset:36864
	ds_read_b128 v[174:177], v216 offset:38912
	s_setprio 1
	s_waitcnt lgkmcnt(3)
	v_mfma_f32_16x16x32_bf16 v[126:129], v[140:143], v[162:165], v[126:129]
	v_mfma_f32_16x16x32_bf16 v[122:125], v[150:153], v[162:165], v[122:125]
	v_mfma_f32_16x16x32_bf16 v[118:121], v[154:157], v[162:165], v[118:121]
	v_mfma_f32_16x16x32_bf16 v[114:117], v[158:161], v[162:165], v[114:117]
	s_waitcnt lgkmcnt(2)
	v_mfma_f32_16x16x32_bf16 v[110:113], v[140:143], v[166:169], v[110:113]
	v_mfma_f32_16x16x32_bf16 v[106:109], v[150:153], v[166:169], v[106:109]
	v_mfma_f32_16x16x32_bf16 v[102:105], v[154:157], v[166:169], v[102:105]
	v_mfma_f32_16x16x32_bf16 v[98:101], v[158:161], v[166:169], v[98:101]
	s_waitcnt lgkmcnt(1)
	v_mfma_f32_16x16x32_bf16 v[94:97], v[140:143], v[170:173], v[94:97]
	v_mfma_f32_16x16x32_bf16 v[162:165], v[150:153], v[170:173], v[90:93]
	v_mfma_f32_16x16x32_bf16 v[86:89], v[154:157], v[170:173], v[86:89]
	v_mfma_f32_16x16x32_bf16 v[82:85], v[158:161], v[170:173], v[82:85]
	s_waitcnt lgkmcnt(0)
	v_mfma_f32_16x16x32_bf16 v[78:81], v[140:143], v[174:177], v[78:81]
	v_mfma_f32_16x16x32_bf16 v[74:77], v[150:153], v[174:177], v[74:77]
	v_mfma_f32_16x16x32_bf16 v[70:73], v[154:157], v[174:177], v[70:73]
	v_mfma_f32_16x16x32_bf16 v[66:69], v[158:161], v[174:177], v[66:69]
	s_setprio 0
	ds_read_b128 v[90:93], v216 offset:40960
	ds_read_b128 v[166:169], v216 offset:43008
	ds_read_b128 v[170:173], v216 offset:45056
	ds_read_b128 v[174:177], v216 offset:47104
	s_setprio 1
	s_waitcnt lgkmcnt(3)
	v_mfma_f32_16x16x32_bf16 v[62:65], v[140:143], v[90:93], v[62:65]
	v_mfma_f32_16x16x32_bf16 v[58:61], v[150:153], v[90:93], v[58:61]
	v_mfma_f32_16x16x32_bf16 v[54:57], v[154:157], v[90:93], v[54:57]
	v_mfma_f32_16x16x32_bf16 v[50:53], v[158:161], v[90:93], v[50:53]
	s_waitcnt lgkmcnt(2)
	v_mfma_f32_16x16x32_bf16 v[46:49], v[140:143], v[166:169], v[46:49]
	v_mfma_f32_16x16x32_bf16 v[42:45], v[150:153], v[166:169], v[42:45]
	v_mfma_f32_16x16x32_bf16 v[38:41], v[154:157], v[166:169], v[38:41]
	v_mfma_f32_16x16x32_bf16 v[34:37], v[158:161], v[166:169], v[34:37]
	s_waitcnt lgkmcnt(1)
	v_mfma_f32_16x16x32_bf16 v[30:33], v[140:143], v[170:173], v[30:33]
	v_mfma_f32_16x16x32_bf16 v[26:29], v[150:153], v[170:173], v[26:29]
	v_mfma_f32_16x16x32_bf16 v[22:25], v[154:157], v[170:173], v[22:25]
	v_mfma_f32_16x16x32_bf16 v[18:21], v[158:161], v[170:173], v[18:21]
	s_waitcnt lgkmcnt(0)
	v_mfma_f32_16x16x32_bf16 v[14:17], v[140:143], v[174:177], v[14:17]
	v_mfma_f32_16x16x32_bf16 v[10:13], v[150:153], v[174:177], v[10:13]
	v_mfma_f32_16x16x32_bf16 v[6:9], v[154:157], v[174:177], v[6:9]
	v_mfma_f32_16x16x32_bf16 v[2:5], v[158:161], v[174:177], v[2:5]
	s_setprio 0
	v_mul_f32_e32 v93, 0xbfb8aa3b, v126
	v_exp_f32_e32 v93, v93
	v_mul_f32_e32 v140, 0xbfb8aa3b, v127
	v_exp_f32_e32 v141, v140
	v_or_b32_e32 v90, s22, v148
	v_add_f32_e32 v93, 1.0, v93
	v_rcp_f32_e32 v140, v93
	v_add_f32_e32 v93, 1.0, v141
	v_mul_f32_e32 v141, 0xbfb8aa3b, v128
	v_exp_f32_e32 v142, v141
	v_mul_f32_e32 v141, 0xbfb8aa3b, v129
	v_exp_f32_e32 v143, v141
	v_rcp_f32_e32 v141, v93
	v_add_f32_e32 v93, 1.0, v142
	v_rcp_f32_e32 v142, v93
	v_add_f32_e32 v93, 1.0, v143
	v_rcp_f32_e32 v143, v93
	v_pk_mul_f32 v[126:127], v[126:127], v[140:141]
	v_mul_f32_e32 v93, 0xbfb8aa3b, v118
	v_pk_mul_f32 v[122:123], v[122:123], v[126:127]
	v_pk_mul_f32 v[126:127], v[128:129], v[142:143]
	v_cvt_pk_bf16_f32 v122, v122, v123
	v_exp_f32_e32 v93, v93
	v_mul_f32_e32 v123, 0xbfb8aa3b, v119
	v_pk_mul_f32 v[124:125], v[124:125], v[126:127]
	v_exp_f32_e32 v126, v123
	v_cvt_pk_bf16_f32 v123, v124, v125
	v_add_f32_e32 v93, 1.0, v93
	v_mul_f32_e32 v125, 0xbfb8aa3b, v120
	v_rcp_f32_e32 v124, v93
	v_add_f32_e32 v93, 1.0, v126
	v_exp_f32_e32 v126, v125
	v_mul_f32_e32 v125, 0xbfb8aa3b, v121
	v_exp_f32_e32 v127, v125
	v_rcp_f32_e32 v125, v93
	v_add_f32_e32 v93, 1.0, v126
	v_rcp_f32_e32 v126, v93
	v_add_f32_e32 v93, 1.0, v127
	v_rcp_f32_e32 v127, v93
	v_ashrrev_i32_e32 v90, 1, v90
	v_pk_mul_f32 v[118:119], v[118:119], v[124:125]
	v_ashrrev_i32_e32 v91, 31, v90
	v_pk_mul_f32 v[114:115], v[114:115], v[118:119]
	v_pk_mul_f32 v[118:119], v[120:121], v[126:127]
	v_add_u32_e32 v92, s21, v149
	v_lshl_add_u64 v[90:91], v[90:91], 1, v[136:137]
	v_pk_mul_f32 v[116:117], v[116:117], v[118:119]
	v_mad_i64_i32 v[150:151], s[0:1], v92, s20, v[90:91]
	v_cvt_pk_bf16_f32 v114, v114, v115
	v_cvt_pk_bf16_f32 v115, v116, v117
	v_mul_f32_e32 v93, 0xbfb8aa3b, v110
	s_barrier
	global_store_dwordx2 v[150:151], v[114:115], off offset:32
	v_exp_f32_e32 v93, v93
	v_mul_f32_e32 v114, 0xbfb8aa3b, v111
	v_exp_f32_e32 v115, v114
	v_or_b32_e32 v118, 16, v92
	v_add_f32_e32 v93, 1.0, v93
	v_rcp_f32_e32 v114, v93
	v_add_f32_e32 v93, 1.0, v115
	v_mul_f32_e32 v115, 0xbfb8aa3b, v112
	v_exp_f32_e32 v116, v115
	v_mul_f32_e32 v115, 0xbfb8aa3b, v113
	v_exp_f32_e32 v117, v115
	v_rcp_f32_e32 v115, v93
	v_add_f32_e32 v93, 1.0, v116
	v_rcp_f32_e32 v116, v93
	v_add_f32_e32 v93, 1.0, v117
	v_rcp_f32_e32 v117, v93
	v_pk_mul_f32 v[110:111], v[110:111], v[114:115]
	v_mul_f32_e32 v93, 0xbfb8aa3b, v102
	v_pk_mul_f32 v[106:107], v[106:107], v[110:111]
	v_pk_mul_f32 v[110:111], v[112:113], v[116:117]
	v_cvt_pk_bf16_f32 v106, v106, v107
	v_exp_f32_e32 v93, v93
	v_mul_f32_e32 v107, 0xbfb8aa3b, v103
	v_pk_mul_f32 v[108:109], v[108:109], v[110:111]
	v_exp_f32_e32 v110, v107
	v_cvt_pk_bf16_f32 v107, v108, v109
	v_add_f32_e32 v93, 1.0, v93
	v_mul_f32_e32 v109, 0xbfb8aa3b, v104
	v_rcp_f32_e32 v108, v93
	v_add_f32_e32 v93, 1.0, v110
	v_exp_f32_e32 v110, v109
	v_mul_f32_e32 v109, 0xbfb8aa3b, v105
	v_exp_f32_e32 v111, v109
	v_rcp_f32_e32 v109, v93
	v_add_f32_e32 v93, 1.0, v110
	v_rcp_f32_e32 v110, v93
	v_add_f32_e32 v93, 1.0, v111
	v_rcp_f32_e32 v111, v93
	v_pk_mul_f32 v[102:103], v[102:103], v[108:109]
	v_mad_i64_i32 v[118:119], s[0:1], v118, s20, v[90:91]
	v_pk_mul_f32 v[98:99], v[98:99], v[102:103]
	v_pk_mul_f32 v[102:103], v[104:105], v[110:111]
	v_cvt_pk_bf16_f32 v98, v98, v99
	v_pk_mul_f32 v[100:101], v[100:101], v[102:103]
	v_mul_f32_e32 v93, 0xbfb8aa3b, v94
	v_cvt_pk_bf16_f32 v99, v100, v101
	global_store_dwordx2 v[118:119], v[98:99], off offset:32
	v_exp_f32_e32 v93, v93
	v_mul_f32_e32 v98, 0xbfb8aa3b, v95
	v_exp_f32_e32 v99, v98
	v_or_b32_e32 v102, 32, v92
	v_add_f32_e32 v93, 1.0, v93
	v_rcp_f32_e32 v98, v93
	v_add_f32_e32 v93, 1.0, v99
	v_mul_f32_e32 v99, 0xbfb8aa3b, v96
	v_exp_f32_e32 v100, v99
	v_mul_f32_e32 v99, 0xbfb8aa3b, v97
	v_exp_f32_e32 v101, v99
	v_rcp_f32_e32 v99, v93
	v_add_f32_e32 v93, 1.0, v100
	v_rcp_f32_e32 v100, v93
	v_add_f32_e32 v93, 1.0, v101
	v_rcp_f32_e32 v101, v93
	v_pk_mul_f32 v[94:95], v[94:95], v[98:99]
	v_mul_f32_e32 v93, 0xbfb8aa3b, v86
	v_pk_mul_f32 v[94:95], v[162:163], v[94:95]
	v_exp_f32_e32 v93, v93
	v_cvt_pk_bf16_f32 v94, v94, v95
	v_mul_f32_e32 v95, 0xbfb8aa3b, v87
	v_exp_f32_e32 v98, v95
	v_pk_mul_f32 v[96:97], v[96:97], v[100:101]
	v_add_f32_e32 v93, 1.0, v93
	v_pk_mul_f32 v[96:97], v[164:165], v[96:97]
	v_mad_i64_i32 v[102:103], s[0:1], v102, s20, v[90:91]
	v_cvt_pk_bf16_f32 v95, v96, v97
	v_mul_f32_e32 v97, 0xbfb8aa3b, v88
	v_rcp_f32_e32 v96, v93
	v_add_f32_e32 v93, 1.0, v98
	v_exp_f32_e32 v98, v97
	v_mul_f32_e32 v97, 0xbfb8aa3b, v89
	v_exp_f32_e32 v99, v97
	v_rcp_f32_e32 v97, v93
	v_add_f32_e32 v93, 1.0, v98
	v_rcp_f32_e32 v98, v93
	v_add_f32_e32 v93, 1.0, v99
	v_rcp_f32_e32 v99, v93
	v_pk_mul_f32 v[86:87], v[86:87], v[96:97]
	s_add_i32 s3, s3, s7
	v_pk_mul_f32 v[82:83], v[82:83], v[86:87]
	v_pk_mul_f32 v[86:87], v[88:89], v[98:99]
	v_cvt_pk_bf16_f32 v82, v82, v83
	v_pk_mul_f32 v[84:85], v[84:85], v[86:87]
	v_or_b32_e32 v86, 48, v92
	v_cvt_pk_bf16_f32 v83, v84, v85
	global_store_dwordx2 v[102:103], v[82:83], off offset:32
	v_mul_f32_e32 v82, 0xbfb8aa3b, v78
	v_mul_f32_e32 v83, 0xbfb8aa3b, v79
	v_exp_f32_e32 v82, v82
	v_exp_f32_e32 v83, v83
	v_mul_f32_e32 v84, 0xbfb8aa3b, v80
	v_mul_f32_e32 v85, 0xbfb8aa3b, v81
	v_exp_f32_e32 v84, v84
	v_exp_f32_e32 v85, v85
	v_add_f32_e32 v82, 1.0, v82
	v_add_f32_e32 v83, 1.0, v83
	v_rcp_f32_e32 v82, v82
	v_rcp_f32_e32 v83, v83
	v_add_f32_e32 v84, 1.0, v84
	v_add_f32_e32 v85, 1.0, v85
	v_rcp_f32_e32 v84, v84
	v_rcp_f32_e32 v85, v85
	v_pk_mul_f32 v[78:79], v[78:79], v[82:83]
	v_mad_i64_i32 v[86:87], s[0:1], v86, s20, v[90:91]
	v_pk_mul_f32 v[74:75], v[74:75], v[78:79]
	v_pk_mul_f32 v[78:79], v[80:81], v[84:85]
	v_cvt_pk_bf16_f32 v74, v74, v75
	v_mul_f32_e32 v75, 0xbfb8aa3b, v70
	v_pk_mul_f32 v[76:77], v[76:77], v[78:79]
	v_exp_f32_e32 v78, v75
	v_mul_f32_e32 v75, 0xbfb8aa3b, v71
	v_exp_f32_e32 v79, v75
	v_cvt_pk_bf16_f32 v75, v76, v77
	v_add_f32_e32 v76, 1.0, v78
	v_mul_f32_e32 v78, 0xbfb8aa3b, v72
	v_add_f32_e32 v77, 1.0, v79
	v_mul_f32_e32 v79, 0xbfb8aa3b, v73
	v_exp_f32_e32 v78, v78
	v_exp_f32_e32 v79, v79
	v_rcp_f32_e32 v76, v76
	v_rcp_f32_e32 v77, v77
	v_add_f32_e32 v78, 1.0, v78
	v_add_f32_e32 v79, 1.0, v79
	v_rcp_f32_e32 v78, v78
	v_rcp_f32_e32 v79, v79
	v_pk_mul_f32 v[70:71], v[70:71], v[76:77]
	s_cmpk_gt_i32 s3, 0x2bf
	v_pk_mul_f32 v[66:67], v[66:67], v[70:71]
	v_pk_mul_f32 v[70:71], v[72:73], v[78:79]
	v_cvt_pk_bf16_f32 v66, v66, v67
	v_pk_mul_f32 v[68:69], v[68:69], v[70:71]
	v_or_b32_e32 v70, 64, v92
	v_cvt_pk_bf16_f32 v67, v68, v69
	global_store_dwordx2 v[86:87], v[66:67], off offset:32
	v_mul_f32_e32 v66, 0xbfb8aa3b, v62
	v_mul_f32_e32 v67, 0xbfb8aa3b, v63
	v_exp_f32_e32 v66, v66
	v_exp_f32_e32 v67, v67
	v_mul_f32_e32 v68, 0xbfb8aa3b, v64
	v_mul_f32_e32 v69, 0xbfb8aa3b, v65
	v_exp_f32_e32 v68, v68
	v_exp_f32_e32 v69, v69
	v_add_f32_e32 v66, 1.0, v66
	v_add_f32_e32 v67, 1.0, v67
	v_rcp_f32_e32 v66, v66
	v_rcp_f32_e32 v67, v67
	v_add_f32_e32 v68, 1.0, v68
	v_add_f32_e32 v69, 1.0, v69
	v_rcp_f32_e32 v68, v68
	v_rcp_f32_e32 v69, v69
	v_pk_mul_f32 v[62:63], v[62:63], v[66:67]
	v_mad_i64_i32 v[70:71], s[0:1], v70, s20, v[90:91]
	v_pk_mul_f32 v[58:59], v[58:59], v[62:63]
	v_pk_mul_f32 v[62:63], v[64:65], v[68:69]
	v_cvt_pk_bf16_f32 v58, v58, v59
	v_mul_f32_e32 v59, 0xbfb8aa3b, v54
	v_pk_mul_f32 v[60:61], v[60:61], v[62:63]
	v_exp_f32_e32 v62, v59
	v_mul_f32_e32 v59, 0xbfb8aa3b, v55
	v_exp_f32_e32 v63, v59
	v_cvt_pk_bf16_f32 v59, v60, v61
	v_add_f32_e32 v60, 1.0, v62
	v_mul_f32_e32 v62, 0xbfb8aa3b, v56
	v_add_f32_e32 v61, 1.0, v63
	v_mul_f32_e32 v63, 0xbfb8aa3b, v57
	v_exp_f32_e32 v62, v62
	v_exp_f32_e32 v63, v63
	v_rcp_f32_e32 v60, v60
	v_rcp_f32_e32 v61, v61
	v_add_f32_e32 v62, 1.0, v62
	v_add_f32_e32 v63, 1.0, v63
	v_rcp_f32_e32 v62, v62
	v_rcp_f32_e32 v63, v63
	v_pk_mul_f32 v[54:55], v[54:55], v[60:61]
	v_add_u32_e32 v130, s8, v130
	v_pk_mul_f32 v[50:51], v[50:51], v[54:55]
	v_pk_mul_f32 v[54:55], v[56:57], v[62:63]
	v_cvt_pk_bf16_f32 v50, v50, v51
	v_pk_mul_f32 v[52:53], v[52:53], v[54:55]
	v_or_b32_e32 v54, 0x50, v92
	v_cvt_pk_bf16_f32 v51, v52, v53
	global_store_dwordx2 v[70:71], v[50:51], off offset:32
	v_mul_f32_e32 v50, 0xbfb8aa3b, v46
	v_mul_f32_e32 v51, 0xbfb8aa3b, v47
	v_exp_f32_e32 v50, v50
	v_exp_f32_e32 v51, v51
	v_mul_f32_e32 v52, 0xbfb8aa3b, v48
	v_mul_f32_e32 v53, 0xbfb8aa3b, v49
	v_exp_f32_e32 v52, v52
	v_exp_f32_e32 v53, v53
	v_add_f32_e32 v50, 1.0, v50
	v_add_f32_e32 v51, 1.0, v51
	v_rcp_f32_e32 v50, v50
	v_rcp_f32_e32 v51, v51
	v_add_f32_e32 v52, 1.0, v52
	v_add_f32_e32 v53, 1.0, v53
	v_rcp_f32_e32 v52, v52
	v_rcp_f32_e32 v53, v53
	v_pk_mul_f32 v[46:47], v[46:47], v[50:51]
	v_mad_i64_i32 v[54:55], s[0:1], v54, s20, v[90:91]
	v_pk_mul_f32 v[42:43], v[42:43], v[46:47]
	v_pk_mul_f32 v[46:47], v[48:49], v[52:53]
	v_cvt_pk_bf16_f32 v42, v42, v43
	v_mul_f32_e32 v43, 0xbfb8aa3b, v38
	v_pk_mul_f32 v[44:45], v[44:45], v[46:47]
	v_exp_f32_e32 v46, v43
	v_mul_f32_e32 v43, 0xbfb8aa3b, v39
	v_exp_f32_e32 v47, v43
	v_cvt_pk_bf16_f32 v43, v44, v45
	v_add_f32_e32 v44, 1.0, v46
	v_mul_f32_e32 v46, 0xbfb8aa3b, v40
	v_add_f32_e32 v45, 1.0, v47
	v_mul_f32_e32 v47, 0xbfb8aa3b, v41
	v_exp_f32_e32 v46, v46
	v_exp_f32_e32 v47, v47
	v_rcp_f32_e32 v44, v44
	v_rcp_f32_e32 v45, v45
	v_add_f32_e32 v46, 1.0, v46
	v_add_f32_e32 v47, 1.0, v47
	v_rcp_f32_e32 v46, v46
	v_rcp_f32_e32 v47, v47
	v_pk_mul_f32 v[38:39], v[38:39], v[44:45]
	global_store_dwordx2 v[150:151], v[122:123], off
	v_pk_mul_f32 v[34:35], v[34:35], v[38:39]
	v_pk_mul_f32 v[38:39], v[40:41], v[46:47]
	v_cvt_pk_bf16_f32 v34, v34, v35
	v_pk_mul_f32 v[36:37], v[36:37], v[38:39]
	v_or_b32_e32 v38, 0x60, v92
	v_cvt_pk_bf16_f32 v35, v36, v37
	global_store_dwordx2 v[54:55], v[34:35], off offset:32
	v_mul_f32_e32 v34, 0xbfb8aa3b, v30
	v_mul_f32_e32 v35, 0xbfb8aa3b, v31
	v_exp_f32_e32 v34, v34
	v_exp_f32_e32 v35, v35
	v_mul_f32_e32 v36, 0xbfb8aa3b, v32
	v_mul_f32_e32 v37, 0xbfb8aa3b, v33
	v_exp_f32_e32 v36, v36
	v_exp_f32_e32 v37, v37
	v_add_f32_e32 v34, 1.0, v34
	v_add_f32_e32 v35, 1.0, v35
	v_rcp_f32_e32 v34, v34
	v_rcp_f32_e32 v35, v35
	v_add_f32_e32 v36, 1.0, v36
	v_add_f32_e32 v37, 1.0, v37
	v_rcp_f32_e32 v36, v36
	v_rcp_f32_e32 v37, v37
	v_pk_mul_f32 v[30:31], v[30:31], v[34:35]
	v_mad_i64_i32 v[38:39], s[0:1], v38, s20, v[90:91]
	v_pk_mul_f32 v[26:27], v[26:27], v[30:31]
	v_pk_mul_f32 v[30:31], v[32:33], v[36:37]
	v_cvt_pk_bf16_f32 v26, v26, v27
	v_mul_f32_e32 v27, 0xbfb8aa3b, v22
	v_pk_mul_f32 v[28:29], v[28:29], v[30:31]
	v_exp_f32_e32 v30, v27
	v_mul_f32_e32 v27, 0xbfb8aa3b, v23
	v_exp_f32_e32 v31, v27
	v_cvt_pk_bf16_f32 v27, v28, v29
	v_add_f32_e32 v28, 1.0, v30
	v_mul_f32_e32 v30, 0xbfb8aa3b, v24
	v_add_f32_e32 v29, 1.0, v31
	v_mul_f32_e32 v31, 0xbfb8aa3b, v25
	v_exp_f32_e32 v30, v30
	v_exp_f32_e32 v31, v31
	v_rcp_f32_e32 v28, v28
	v_rcp_f32_e32 v29, v29
	v_add_f32_e32 v30, 1.0, v30
	v_add_f32_e32 v31, 1.0, v31
	v_rcp_f32_e32 v30, v30
	v_rcp_f32_e32 v31, v31
	v_pk_mul_f32 v[22:23], v[22:23], v[28:29]
	global_store_dwordx2 v[118:119], v[106:107], off
	v_pk_mul_f32 v[18:19], v[18:19], v[22:23]
	v_pk_mul_f32 v[22:23], v[24:25], v[30:31]
	v_cvt_pk_bf16_f32 v18, v18, v19
	v_pk_mul_f32 v[20:21], v[20:21], v[22:23]
	v_or_b32_e32 v22, 0x70, v92
	v_cvt_pk_bf16_f32 v19, v20, v21
	global_store_dwordx2 v[38:39], v[18:19], off offset:32
	v_mul_f32_e32 v18, 0xbfb8aa3b, v14
	v_mul_f32_e32 v19, 0xbfb8aa3b, v15
	v_exp_f32_e32 v18, v18
	v_exp_f32_e32 v19, v19
	v_mul_f32_e32 v20, 0xbfb8aa3b, v16
	v_mul_f32_e32 v21, 0xbfb8aa3b, v17
	v_exp_f32_e32 v20, v20
	v_exp_f32_e32 v21, v21
	v_add_f32_e32 v18, 1.0, v18
	v_add_f32_e32 v19, 1.0, v19
	v_rcp_f32_e32 v18, v18
	v_rcp_f32_e32 v19, v19
	v_add_f32_e32 v20, 1.0, v20
	v_add_f32_e32 v21, 1.0, v21
	v_rcp_f32_e32 v20, v20
	v_rcp_f32_e32 v21, v21
	v_pk_mul_f32 v[14:15], v[14:15], v[18:19]
	v_mad_i64_i32 v[22:23], s[0:1], v22, s20, v[90:91]
	v_pk_mul_f32 v[10:11], v[10:11], v[14:15]
	v_pk_mul_f32 v[14:15], v[16:17], v[20:21]
	v_cvt_pk_bf16_f32 v10, v10, v11
	v_mul_f32_e32 v11, 0xbfb8aa3b, v6
	v_pk_mul_f32 v[12:13], v[12:13], v[14:15]
	v_exp_f32_e32 v14, v11
	v_mul_f32_e32 v11, 0xbfb8aa3b, v7
	v_exp_f32_e32 v15, v11
	v_cvt_pk_bf16_f32 v11, v12, v13
	v_add_f32_e32 v12, 1.0, v14
	v_mul_f32_e32 v14, 0xbfb8aa3b, v8
	v_add_f32_e32 v13, 1.0, v15
	v_mul_f32_e32 v15, 0xbfb8aa3b, v9
	v_exp_f32_e32 v14, v14
	v_exp_f32_e32 v15, v15
	v_rcp_f32_e32 v12, v12
	v_rcp_f32_e32 v13, v13
	v_add_f32_e32 v14, 1.0, v14
	v_add_f32_e32 v15, 1.0, v15
	v_rcp_f32_e32 v14, v14
	v_rcp_f32_e32 v15, v15
	v_pk_mul_f32 v[6:7], v[6:7], v[12:13]
	global_store_dwordx2 v[102:103], v[94:95], off
	v_pk_mul_f32 v[2:3], v[2:3], v[6:7]
	v_pk_mul_f32 v[6:7], v[8:9], v[14:15]
	v_cvt_pk_bf16_f32 v2, v2, v3
	v_pk_mul_f32 v[4:5], v[4:5], v[6:7]
	global_store_dwordx2 v[86:87], v[74:75], off
	v_cvt_pk_bf16_f32 v3, v4, v5
	global_store_dwordx2 v[70:71], v[58:59], off
	global_store_dwordx2 v[54:55], v[42:43], off
	global_store_dwordx2 v[38:39], v[26:27], off
	global_store_dwordx2 v[22:23], v[10:11], off
	global_store_dwordx2 v[22:23], v[2:3], off offset:32
	s_cbranch_scc0 .LBB0_749

.LBB0_773:
	s_lshl_b32 s37, s29, 8
	v_or_b32_e32 v27, s37, v1
	v_mad_i64_i32 v[2:3], s[8:9], v27, s12, v[130:131]
	v_add_co_u32_e32 v6, vcc, 0x58000, v2
	s_lshl_b32 s36, s28, 8
	s_nop 0
	v_addc_co_u32_e32 v7, vcc, 0, v3, vcc
	global_load_dwordx4 v[28:31], v[2:3], off
	global_load_dwordx4 v[32:35], v[6:7], off
	v_add_co_u32_e32 v6, vcc, 0xb0000, v2
	v_or_b32_e32 v60, s36, v1
	s_nop 0
	v_addc_co_u32_e32 v7, vcc, 0, v3, vcc
	v_add_co_u32_e32 v2, vcc, 0x108000, v2
	v_mad_i64_i32 v[4:5], s[8:9], v60, s12, v[132:133]
	s_nop 0
	v_addc_co_u32_e32 v3, vcc, 0, v3, vcc
	global_load_dwordx4 v[36:39], v[6:7], off
	global_load_dwordx4 v[40:43], v[2:3], off
	v_add_co_u32_e32 v2, vcc, s13, v4
	s_waitcnt vmcnt(63) expcnt(7) lgkmcnt(15)
	s_nop 0
	v_addc_co_u32_e32 v3, vcc, 0, v5, vcc
	s_barrier
	global_load_dwordx4 v[44:47], v[4:5], off
	global_load_dwordx4 v[48:51], v[2:3], off
	v_add_co_u32_e32 v2, vcc, s14, v4
	s_mov_b32 s38, 0
	s_nop 0
	v_addc_co_u32_e32 v3, vcc, 0, v5, vcc
	v_add_co_u32_e32 v4, vcc, s15, v4
	s_mov_b64 s[8:9], 0
	s_nop 0
	v_addc_co_u32_e32 v5, vcc, 0, v5, vcc
	global_load_dwordx4 v[52:55], v[2:3], off
	global_load_dwordx4 v[56:59], v[4:5], off
	v_mov_b32_e32 v2, 0
	v_mov_b32_e32 v3, v2
	v_mov_b32_e32 v4, v2
	v_mov_b32_e32 v5, v2
	v_mov_b32_e32 v6, v2
	v_mov_b32_e32 v7, v2
	v_mov_b32_e32 v8, v2
	v_mov_b32_e32 v9, v2
	v_mov_b32_e32 v10, v2
	v_mov_b32_e32 v11, v2
	v_mov_b32_e32 v12, v2
	v_mov_b32_e32 v13, v2
	v_mov_b32_e32 v14, v2
	v_mov_b32_e32 v15, v2
	v_mov_b32_e32 v16, v2
	v_mov_b32_e32 v17, v2
	v_mov_b32_e32 v18, v2
	v_mov_b32_e32 v19, v2
	v_mov_b32_e32 v20, v2
	v_mov_b32_e32 v21, v2
	v_mov_b32_e32 v22, v2
	v_mov_b32_e32 v23, v2
	v_mov_b32_e32 v24, v2
	v_mov_b32_e32 v25, v2
	v_mov_b32_e32 v26, v2
	v_mad_i64_i32 v[136:137], s[40:41], v27, s12, v[134:135]
	v_mad_i64_i32 v[138:139], s[40:41], v60, s12, v[134:135]
	v_mov_b32_e32 v27, v2
	v_mov_b32_e32 v60, v2
	v_mov_b32_e32 v61, v2
	v_mov_b32_e32 v62, v2
	v_mov_b32_e32 v63, v2
	v_mov_b32_e32 v64, v2
	v_mov_b32_e32 v65, v2
	v_mov_b32_e32 v66, v2
	v_mov_b32_e32 v67, v2
	v_mov_b32_e32 v68, v2
	v_mov_b32_e32 v69, v2
	v_mov_b32_e32 v70, v2
	v_mov_b32_e32 v71, v2
	v_mov_b32_e32 v72, v2
	v_mov_b32_e32 v73, v2
	v_mov_b32_e32 v74, v2
	v_mov_b32_e32 v75, v2
	v_mov_b32_e32 v76, v2
	v_mov_b32_e32 v77, v2
	v_mov_b32_e32 v78, v2
	v_mov_b32_e32 v79, v2
	v_mov_b32_e32 v80, v2
	v_mov_b32_e32 v81, v2
	v_mov_b32_e32 v82, v2
	s_waitcnt vmcnt(7)
	ds_write_b128 v146, v[28:31]
	s_waitcnt vmcnt(6)
	ds_write_b128 v146, v[32:35] offset:8192
	s_waitcnt vmcnt(5)
	ds_write_b128 v146, v[36:39] offset:16384
	s_waitcnt vmcnt(4)
	ds_write_b128 v146, v[40:43] offset:24576
	s_waitcnt vmcnt(3)
	ds_write_b128 v147, v[44:47]
	s_waitcnt vmcnt(2)
	ds_write_b128 v147, v[48:51] offset:8192
	s_waitcnt vmcnt(1)
	ds_write_b128 v147, v[52:55] offset:16384
	s_waitcnt vmcnt(0)
	ds_write_b128 v147, v[56:59] offset:24576
	v_mov_b32_e32 v28, v2
	v_mov_b32_e32 v29, v2
	v_mov_b32_e32 v30, v2
	v_mov_b32_e32 v31, v2
	v_mov_b32_e32 v32, v2
	v_mov_b32_e32 v33, v2
	v_mov_b32_e32 v34, v2
	v_mov_b32_e32 v35, v2
	v_mov_b32_e32 v36, v2
	v_mov_b32_e32 v37, v2
	v_mov_b32_e32 v38, v2
	v_mov_b32_e32 v39, v2
	v_mov_b32_e32 v40, v2
	v_mov_b32_e32 v41, v2
	v_mov_b32_e32 v42, v2
	v_mov_b32_e32 v43, v2
	v_mov_b32_e32 v44, v2
	v_mov_b32_e32 v45, v2
	v_mov_b32_e32 v46, v2
	v_mov_b32_e32 v47, v2
	v_mov_b32_e32 v48, v2
	v_mov_b32_e32 v49, v2
	v_mov_b32_e32 v50, v2
	v_mov_b32_e32 v51, v2
	v_mov_b32_e32 v52, v2
	v_mov_b32_e32 v53, v2
	v_mov_b32_e32 v54, v2
	v_mov_b32_e32 v55, v2
	v_mov_b32_e32 v56, v2
	v_mov_b32_e32 v57, v2
	v_mov_b32_e32 v58, v2
	v_mov_b32_e32 v59, v2
	v_mov_b32_e32 v83, v2
	v_mov_b32_e32 v84, v2
	v_mov_b32_e32 v85, v2
	v_mov_b32_e32 v86, v2
	v_mov_b32_e32 v87, v2
	v_mov_b32_e32 v88, v2
	v_mov_b32_e32 v89, v2
	v_mov_b32_e32 v90, v2
	v_mov_b32_e32 v91, v2
	v_mov_b32_e32 v92, v2
	v_mov_b32_e32 v93, v2
	v_mov_b32_e32 v94, v2
	v_mov_b32_e32 v95, v2
	v_mov_b32_e32 v96, v2
	v_mov_b32_e32 v97, v2
	v_mov_b32_e32 v98, v2
	v_mov_b32_e32 v99, v2
	v_mov_b32_e32 v100, v2
	v_mov_b32_e32 v101, v2
	v_mov_b32_e32 v102, v2
	v_mov_b32_e32 v103, v2
	v_mov_b32_e32 v104, v2
	v_mov_b32_e32 v105, v2
	v_mov_b32_e32 v106, v2
	v_mov_b32_e32 v107, v2
	v_mov_b32_e32 v108, v2
	v_mov_b32_e32 v109, v2
	v_mov_b32_e32 v110, v2
	v_mov_b32_e32 v111, v2
	v_mov_b32_e32 v112, v2
	v_mov_b32_e32 v113, v2
	v_mov_b32_e32 v114, v2
	v_mov_b32_e32 v115, v2
	v_mov_b32_e32 v116, v2
	v_mov_b32_e32 v117, v2
	v_mov_b32_e32 v118, v2
	v_mov_b32_e32 v119, v2
	v_mov_b32_e32 v120, v2
	v_mov_b32_e32 v121, v2
	v_mov_b32_e32 v122, v2
	v_mov_b32_e32 v123, v2
	v_mov_b32_e32 v124, v2
	v_mov_b32_e32 v125, v2
	v_mov_b32_e32 v126, v2
	v_mov_b32_e32 v127, v2
	v_mov_b32_e32 v128, v2
	v_mov_b32_e32 v129, v2
	s_waitcnt lgkmcnt(0)
	s_barrier
	s_movk_i32 s97, 0x70
	v_readfirstlane_b32 s98, v136
	v_readfirstlane_b32 s99, v137
	v_subrev_u32_e32 v248, s98, v136
	v_bfi_b32 v248, s97, v146, v248
	v_add_u32_e32 v140, s16, v248
	v_add_u32_e32 v152, s17, v248
	v_add_u32_e32 v156, s18, v248
	v_add_u32_e32 v160, s19, v248
	s_add_u32 s98, s98, s8
	s_addc_u32 s99, s99, s9
	s_add_u32 s98, s98, 0x80
	s_addc_u32 s99, s99, 0
	v_readfirstlane_b32 s100, v138
	v_readfirstlane_b32 s101, v139
	v_subrev_u32_e32 v250, s100, v138
	v_bfi_b32 v250, s97, v146, v250
	v_add_u32_e32 v164, s20, v250
	v_add_u32_e32 v168, s21, v250
	v_add_u32_e32 v172, s22, v250
	v_add_u32_e32 v176, s23, v250
	s_add_u32 s100, s100, s8
	s_addc_u32 s101, s101, s9
	s_add_u32 s100, s100, 0x80
	s_addc_u32 s101, s101, 0
	v_readfirstlane_b32 s96, v146
	s_and_b32 s96, s96, 0xfc00
	s_cmp_lt_u32 s96, 0x1000
	s_cbranch_scc1 .Lg2_p15_np
	s_setprio 1

.Lg2_p15_tail:
	s_setprio 0
	s_nop 0
	v_mfma_f32_16x16x32_bf16 v[62:65], v[232:235], v[196:199], v[62:65]
	v_mfma_f32_16x16x32_bf16 v[58:61], v[236:239], v[196:199], v[58:61]
	v_mfma_f32_16x16x32_bf16 v[54:57], v[240:243], v[196:199], v[54:57]
	v_mfma_f32_16x16x32_bf16 v[50:53], v[244:247], v[196:199], v[50:53]
	v_mfma_f32_16x16x32_bf16 v[46:49], v[232:235], v[200:203], v[46:49]
	v_mfma_f32_16x16x32_bf16 v[42:45], v[236:239], v[200:203], v[42:45]
	v_mfma_f32_16x16x32_bf16 v[38:41], v[240:243], v[200:203], v[38:41]
	v_mfma_f32_16x16x32_bf16 v[34:37], v[244:247], v[200:203], v[34:37]
	v_mfma_f32_16x16x32_bf16 v[30:33], v[232:235], v[204:207], v[30:33]
	v_mfma_f32_16x16x32_bf16 v[26:29], v[236:239], v[204:207], v[26:29]
	v_mfma_f32_16x16x32_bf16 v[22:25], v[240:243], v[204:207], v[22:25]
	v_mfma_f32_16x16x32_bf16 v[18:21], v[244:247], v[204:207], v[18:21]
	v_mfma_f32_16x16x32_bf16 v[14:17], v[232:235], v[208:211], v[14:17]
	v_mfma_f32_16x16x32_bf16 v[10:13], v[236:239], v[208:211], v[10:13]
	v_mfma_f32_16x16x32_bf16 v[6:9], v[240:243], v[208:211], v[6:9]
	v_mfma_f32_16x16x32_bf16 v[2:5], v[244:247], v[208:211], v[2:5]
	ds_read_b128 v[136:139], v149 offset:32768
	ds_read_b128 v[140:143], v149 offset:34816
	ds_read_b128 v[152:155], v149 offset:36864
	ds_read_b128 v[156:159], v149 offset:38912
	ds_read_b128 v[160:163], v148 offset:32768
	ds_read_b128 v[164:167], v148 offset:34816
	ds_read_b128 v[168:171], v148 offset:36864
	ds_read_b128 v[172:175], v148 offset:38912
	s_setprio 1
	s_waitcnt lgkmcnt(3)
	v_mfma_f32_16x16x32_bf16 v[126:129], v[136:139], v[160:163], v[126:129]
	v_mfma_f32_16x16x32_bf16 v[122:125], v[140:143], v[160:163], v[122:125]
	v_mfma_f32_16x16x32_bf16 v[118:121], v[152:155], v[160:163], v[118:121]
	v_mfma_f32_16x16x32_bf16 v[114:117], v[156:159], v[160:163], v[114:117]
	s_waitcnt lgkmcnt(2)
	v_mfma_f32_16x16x32_bf16 v[110:113], v[136:139], v[164:167], v[110:113]
	v_mfma_f32_16x16x32_bf16 v[106:109], v[140:143], v[164:167], v[106:109]
	v_mfma_f32_16x16x32_bf16 v[102:105], v[152:155], v[164:167], v[102:105]
	v_mfma_f32_16x16x32_bf16 v[98:101], v[156:159], v[164:167], v[98:101]
	s_waitcnt lgkmcnt(1)
	v_mfma_f32_16x16x32_bf16 v[94:97], v[136:139], v[168:171], v[94:97]
	v_mfma_f32_16x16x32_bf16 v[90:93], v[140:143], v[168:171], v[90:93]
	v_mfma_f32_16x16x32_bf16 v[86:89], v[152:155], v[168:171], v[86:89]
	v_mfma_f32_16x16x32_bf16 v[82:85], v[156:159], v[168:171], v[82:85]
	s_waitcnt lgkmcnt(0)
	v_mfma_f32_16x16x32_bf16 v[78:81], v[136:139], v[172:175], v[78:81]
	v_mfma_f32_16x16x32_bf16 v[74:77], v[140:143], v[172:175], v[74:77]
	v_mfma_f32_16x16x32_bf16 v[70:73], v[152:155], v[172:175], v[70:73]
	v_mfma_f32_16x16x32_bf16 v[66:69], v[156:159], v[172:175], v[66:69]
	s_setprio 0
	ds_read_b128 v[160:163], v148 offset:40960
	ds_read_b128 v[164:167], v148 offset:43008
	ds_read_b128 v[168:171], v148 offset:45056
	ds_read_b128 v[172:175], v148 offset:47104
	s_setprio 1
	s_waitcnt lgkmcnt(3)
	v_mfma_f32_16x16x32_bf16 v[62:65], v[136:139], v[160:163], v[62:65]
	v_mfma_f32_16x16x32_bf16 v[58:61], v[140:143], v[160:163], v[58:61]
	v_mfma_f32_16x16x32_bf16 v[54:57], v[152:155], v[160:163], v[54:57]
	v_mfma_f32_16x16x32_bf16 v[50:53], v[156:159], v[160:163], v[50:53]
	s_waitcnt lgkmcnt(2)
	v_mfma_f32_16x16x32_bf16 v[46:49], v[136:139], v[164:167], v[46:49]
	v_mfma_f32_16x16x32_bf16 v[42:45], v[140:143], v[164:167], v[42:45]
	v_mfma_f32_16x16x32_bf16 v[38:41], v[152:155], v[164:167], v[38:41]
	v_mfma_f32_16x16x32_bf16 v[34:37], v[156:159], v[164:167], v[34:37]
	s_waitcnt lgkmcnt(1)
	v_mfma_f32_16x16x32_bf16 v[30:33], v[136:139], v[168:171], v[30:33]
	v_mfma_f32_16x16x32_bf16 v[26:29], v[140:143], v[168:171], v[26:29]
	v_mfma_f32_16x16x32_bf16 v[22:25], v[152:155], v[168:171], v[22:25]
	v_mfma_f32_16x16x32_bf16 v[18:21], v[156:159], v[168:171], v[18:21]
	s_waitcnt lgkmcnt(0)
	v_mfma_f32_16x16x32_bf16 v[14:17], v[136:139], v[172:175], v[14:17]
	v_mfma_f32_16x16x32_bf16 v[10:13], v[140:143], v[172:175], v[10:13]
	v_mfma_f32_16x16x32_bf16 v[6:9], v[152:155], v[172:175], v[6:9]
	v_mfma_f32_16x16x32_bf16 v[2:5], v[156:159], v[172:175], v[2:5]
	s_setprio 0
	ds_read_b128 v[136:139], v217 offset:32768
	ds_read_b128 v[140:143], v217 offset:34816
	ds_read_b128 v[152:155], v217 offset:36864
	ds_read_b128 v[156:159], v217 offset:38912
	ds_read_b128 v[160:163], v216 offset:32768
	ds_read_b128 v[164:167], v216 offset:34816
	ds_read_b128 v[168:171], v216 offset:36864
	ds_read_b128 v[172:175], v216 offset:38912
	s_setprio 1
	s_waitcnt lgkmcnt(3)
	v_mfma_f32_16x16x32_bf16 v[126:129], v[136:139], v[160:163], v[126:129]
	v_mfma_f32_16x16x32_bf16 v[122:125], v[140:143], v[160:163], v[122:125]
	v_mfma_f32_16x16x32_bf16 v[118:121], v[152:155], v[160:163], v[118:121]
	v_mfma_f32_16x16x32_bf16 v[114:117], v[156:159], v[160:163], v[114:117]
	s_waitcnt lgkmcnt(2)
	v_mfma_f32_16x16x32_bf16 v[110:113], v[136:139], v[164:167], v[110:113]
	v_mfma_f32_16x16x32_bf16 v[106:109], v[140:143], v[164:167], v[106:109]
	v_mfma_f32_16x16x32_bf16 v[102:105], v[152:155], v[164:167], v[102:105]
	v_mfma_f32_16x16x32_bf16 v[98:101], v[156:159], v[164:167], v[98:101]
	s_waitcnt lgkmcnt(1)
	v_mfma_f32_16x16x32_bf16 v[94:97], v[136:139], v[168:171], v[94:97]
	v_mfma_f32_16x16x32_bf16 v[90:93], v[140:143], v[168:171], v[90:93]
	v_mfma_f32_16x16x32_bf16 v[86:89], v[152:155], v[168:171], v[86:89]
	v_mfma_f32_16x16x32_bf16 v[82:85], v[156:159], v[168:171], v[82:85]
	s_waitcnt lgkmcnt(0)
	v_mfma_f32_16x16x32_bf16 v[78:81], v[136:139], v[172:175], v[78:81]
	v_mfma_f32_16x16x32_bf16 v[74:77], v[140:143], v[172:175], v[74:77]
	v_mfma_f32_16x16x32_bf16 v[70:73], v[152:155], v[172:175], v[70:73]
	v_mfma_f32_16x16x32_bf16 v[66:69], v[156:159], v[172:175], v[66:69]
	s_setprio 0
	ds_read_b128 v[160:163], v216 offset:40960
	ds_read_b128 v[164:167], v216 offset:43008
	ds_read_b128 v[168:171], v216 offset:45056
	ds_read_b128 v[172:175], v216 offset:47104
	s_setprio 1
	s_waitcnt lgkmcnt(3)
	v_mfma_f32_16x16x32_bf16 v[62:65], v[136:139], v[160:163], v[62:65]
	v_mfma_f32_16x16x32_bf16 v[58:61], v[140:143], v[160:163], v[58:61]
	v_mfma_f32_16x16x32_bf16 v[54:57], v[152:155], v[160:163], v[54:57]
	v_mfma_f32_16x16x32_bf16 v[50:53], v[156:159], v[160:163], v[50:53]
	s_waitcnt lgkmcnt(2)
	v_mfma_f32_16x16x32_bf16 v[46:49], v[136:139], v[164:167], v[46:49]
	v_mfma_f32_16x16x32_bf16 v[42:45], v[140:143], v[164:167], v[42:45]
	v_mfma_f32_16x16x32_bf16 v[38:41], v[152:155], v[164:167], v[38:41]
	v_mfma_f32_16x16x32_bf16 v[34:37], v[156:159], v[164:167], v[34:37]
	s_waitcnt lgkmcnt(1)
	v_mfma_f32_16x16x32_bf16 v[30:33], v[136:139], v[168:171], v[30:33]
	v_mfma_f32_16x16x32_bf16 v[26:29], v[140:143], v[168:171], v[26:29]
	v_mfma_f32_16x16x32_bf16 v[22:25], v[152:155], v[168:171], v[22:25]
	v_mfma_f32_16x16x32_bf16 v[18:21], v[156:159], v[168:171], v[18:21]
	s_waitcnt lgkmcnt(0)
	v_mfma_f32_16x16x32_bf16 v[14:17], v[136:139], v[172:175], v[14:17]
	v_mfma_f32_16x16x32_bf16 v[10:13], v[140:143], v[172:175], v[10:13]
	v_mfma_f32_16x16x32_bf16 v[6:9], v[152:155], v[172:175], v[6:9]
	v_mfma_f32_16x16x32_bf16 v[2:5], v[156:159], v[172:175], v[2:5]
	s_setprio 0
	v_add_u32_e32 v152, s37, v150
	v_mul_hi_i32 v136, v152, s24
	v_lshrrev_b32_e32 v137, 31, v136
	v_ashrrev_i32_e32 v136, 11, v136
	v_add_u32_e32 v137, v136, v137
	v_mad_i32_i24 v142, v137, s25, v152
	v_lshlrev_b32_e32 v139, 13, v137
	v_cmp_lt_i32_e32 vcc, s26, v142
	v_add3_u32 v138, v139, v142, s27
	s_barrier
	s_and_saveexec_b64 s[8:9], vcc
	s_xor_b64 s[8:9], exec, s[8:9]
	v_add3_u32 v136, v139, v142, s27
	s_or_saveexec_b64 s[8:9], s[8:9]
	v_mov_b64_e32 v[140:141], s[84:85]
	v_lshl_add_u32 v139, v137, 8, v142
	s_xor_b64 exec, exec, s[8:9]
	v_lshl_add_u32 v136, v137, 8, v142
	v_mov_b64_e32 v[140:141], s[4:5]
	s_or_b64 exec, exec, s[8:9]
	s_and_saveexec_b64 s[8:9], vcc
	s_xor_b64 s[8:9], exec, s[8:9]
	s_cbranch_execz .LBB0_781
	v_mul_hi_i32_i24_e32 v143, 0x6000, v137
	v_mul_i32_i24_e32 v142, 0x6000, v137
	s_or_saveexec_b64 s[8:9], s[8:9]
	v_mov_b64_e32 v[144:145], s[84:85]
	s_xor_b64 exec, exec, s[8:9]
	s_cbranch_execnz .LBB0_782
	s_branch .LBB0_783
